# GEMM main loops: MFMAs in each half-block reordered to snake order (A fragment fixed for 4 MFMAs, B reversed on the turn) to reduce operand toggling
# baseline (speedup 1.0000x reference)
; #define PG8_STAGE(bufoff, gbase, voff) do { _Pragma("unroll") for (int _i = 0; _i < 2; ++_i) \
;         __builtin_amdgcn_global_load_lds((const unsigned*)((const char*)(gbase) + (voff)[_i]), (LAS unsigned*)(lds + (bufoff) + ldsw + _i * 8192), 16, 0, 0); } while (0)
; #define PG8_LDA(dst, b, h) do { _Pragma("unroll") for (int m = 0; m < 4; ++m) _Pragma("unroll") for (int k = 0; k < 2; ++k) dst[m][k] = *(const LAS bf16x8*)(lds + PG8_SA(b, h) + aoff + m * 2048 + k * 1024); } while (0)
; #define PG8_LDB(dst, b, h) do { _Pragma("unroll") for (int n = 0; n < 2; ++n) _Pragma("unroll") for (int k = 0; k < 2; ++k) dst[n][k] = *(const LAS bf16x8*)(lds + PG8_SB(b, h) + boff + n * 2048 + k * 1024); } while (0)
; #define PG8_MMA(ai, bj, At, Bt) do { __builtin_amdgcn_s_setprio(1); _Pragma("unroll") for (int m = 0; m < 4; ++m) _Pragma("unroll") for (int n = 0; n < 2; ++n) _Pragma("unroll") for (int k = 0; k < 2; ++k) \
;         acc[ai][bj][m][n] = __builtin_amdgcn_mfma_f32_16x16x32_bf16(Bt[n][k], At[m][k], acc[ai][bj][m][n], 0, 0, 0); __builtin_amdgcn_s_setprio(0); } while (0)
; #define PG8_WAIT_V(n) asm volatile("s_waitcnt vmcnt(" #n ")" ::: "memory")
; #define PG8_WAIT_L(n) asm volatile("s_waitcnt lgkmcnt(" #n ")" ::: "memory")
; #define PG8_BAR __builtin_amdgcn_s_barrier()
; #define PG8_SCHED __builtin_amdgcn_sched_barrier(0)
; template <class Epi>
; __device__ __forceinline__ void gemm_phase(LAS unsigned char* lds, const Gemm g, const StaticOrder& S, const Epi& E) {
;     ...
;         for (int t = 0; t < nt; t += 2) {
;             const bool last = (t == nt - 2);
;             const char* a1 = cA + (unsigned)(t + 1) * kstep;
;             const char* a2 = last ? nA : cA + (unsigned)(t + 2) * kstep; const char* b2 = last ? nB : cB + (unsigned)(t + 2) * kstep;
;             const char* a3 = a2 + kstep; const char* b3 = b2 + kstep;
;             PG8_LDB(B0, 0, 0); PG8_LDB(B1, 0, 1); PG8_SCHED; PG8_LDA(At, 0, 0); PG8_STAGE(PG8_SA(1, 1), a1 + hstepA, voffA);
;             PG8_WAIT_V(8); PG8_WAIT_L(0); PG8_BAR; PG8_MMA(0, 0, At, B0); PG8_MMA(0, 1, At, B1); PG8_BAR; PG8_SCHED;
;             PG8_LDA(At, 0, 1); PG8_STAGE(PG8_SB(0, 0), b2, voffB); PG8_STAGE(PG8_SB(0, 1), b2 + hstepB, voffB); PG8_STAGE(PG8_SA(0, 0), a2, voffA);
;             PG8_WAIT_V(8); PG8_WAIT_L(0); PG8_BAR; PG8_MMA(1, 0, At, B0); PG8_MMA(1, 1, At, B1); PG8_BAR; PG8_SCHED;
.LBB0_162:
	ds_read_b128 v[156:159], v149
	ds_read_b128 v[160:163], v149 offset:1024
	ds_read_b128 v[164:167], v149 offset:2048
	ds_read_b128 v[168:171], v149 offset:3072
	ds_read_b128 v[172:175], v150
	ds_read_b128 v[176:179], v150 offset:1024
	ds_read_b128 v[180:183], v150 offset:2048
	ds_read_b128 v[184:187], v150 offset:3072
	s_add_u32 s26, s24, 0xfffc0080
	s_addc_u32 s27, s25, -1
	s_cmp_eq_u32 s61, 12
	s_cselect_b32 s29, s17, s27
	s_cselect_b32 s28, s57, s26
	s_cselect_b32 s27, s13, s60
	s_cselect_b32 s26, s58, s59
	v_lshl_add_u64 v[144:145], s[24:25], 0, v[138:139]
	s_add_i32 m0, s23, 0xc000
	ds_read_b128 v[188:191], v151
	ds_read_b128 v[192:195], v151 offset:1024
	ds_read_b128 v[196:199], v151 offset:2048
	ds_read_b128 v[200:203], v151 offset:3072
	ds_read_b128 v[204:207], v151 offset:4096
	ds_read_b128 v[208:211], v151 offset:5120
	ds_read_b128 v[212:215], v151 offset:6144
	ds_read_b128 v[216:219], v151 offset:7168
	global_load_lds_dwordx4 v[144:145], off
	v_lshl_add_u64 v[144:145], s[24:25], 0, v[136:137]
	s_add_i32 m0, s23, 0xe000
	s_nop 0
	global_load_lds_dwordx4 v[144:145], off
	s_waitcnt vmcnt(8)
	s_waitcnt lgkmcnt(0)
	s_barrier
	s_setprio 1
	s_waitcnt lgkmcnt(0)
	v_mfma_f32_16x16x32_bf16 v[116:119], v[156:159], v[188:191], v[116:119]
	v_mfma_f32_16x16x32_bf16 v[108:111], v[156:159], v[196:199], v[108:111]
	v_mfma_f32_16x16x32_bf16 v[92:95], v[156:159], v[204:207], v[92:95]
	v_mfma_f32_16x16x32_bf16 v[76:79], v[156:159], v[212:215], v[76:79]
	v_mfma_f32_16x16x32_bf16 v[68:71], v[164:167], v[212:215], v[68:71]
	v_mfma_f32_16x16x32_bf16 v[84:87], v[164:167], v[204:207], v[84:87]
	v_mfma_f32_16x16x32_bf16 v[100:103], v[164:167], v[196:199], v[100:103]
	v_mfma_f32_16x16x32_bf16 v[112:115], v[164:167], v[188:191], v[112:115]
	v_mfma_f32_16x16x32_bf16 v[116:119], v[160:163], v[192:195], v[116:119]
	v_mfma_f32_16x16x32_bf16 v[108:111], v[160:163], v[200:203], v[108:111]
	v_mfma_f32_16x16x32_bf16 v[92:95], v[160:163], v[208:211], v[92:95]
	v_mfma_f32_16x16x32_bf16 v[76:79], v[160:163], v[216:219], v[76:79]
	v_mfma_f32_16x16x32_bf16 v[68:71], v[168:171], v[216:219], v[68:71]
	v_mfma_f32_16x16x32_bf16 v[84:87], v[168:171], v[208:211], v[84:87]
	v_mfma_f32_16x16x32_bf16 v[100:103], v[168:171], v[200:203], v[100:103]
	v_mfma_f32_16x16x32_bf16 v[112:115], v[168:171], v[192:195], v[112:115]
	s_setprio 0
	s_setprio 1
	v_mfma_f32_16x16x32_bf16 v[124:127], v[172:175], v[188:191], v[124:127]
	v_mfma_f32_16x16x32_bf16 v[104:107], v[172:175], v[196:199], v[104:107]
	v_mfma_f32_16x16x32_bf16 v[88:91], v[172:175], v[204:207], v[88:91]
	v_mfma_f32_16x16x32_bf16 v[72:75], v[172:175], v[212:215], v[72:75]
	v_mfma_f32_16x16x32_bf16 v[64:67], v[180:183], v[212:215], v[64:67]
	v_mfma_f32_16x16x32_bf16 v[80:83], v[180:183], v[204:207], v[80:83]
	v_mfma_f32_16x16x32_bf16 v[96:99], v[180:183], v[196:199], v[96:99]
	v_mfma_f32_16x16x32_bf16 v[120:123], v[180:183], v[188:191], v[120:123]
	v_mfma_f32_16x16x32_bf16 v[124:127], v[176:179], v[192:195], v[124:127]
	v_mfma_f32_16x16x32_bf16 v[104:107], v[176:179], v[200:203], v[104:107]
	v_mfma_f32_16x16x32_bf16 v[88:91], v[176:179], v[208:211], v[88:91]
	v_mfma_f32_16x16x32_bf16 v[72:75], v[176:179], v[216:219], v[72:75]
	v_mfma_f32_16x16x32_bf16 v[64:67], v[184:187], v[216:219], v[64:67]
	v_mfma_f32_16x16x32_bf16 v[80:83], v[184:187], v[208:211], v[80:83]
	v_mfma_f32_16x16x32_bf16 v[96:99], v[184:187], v[200:203], v[96:99]
	v_mfma_f32_16x16x32_bf16 v[120:123], v[184:187], v[192:195], v[120:123]
	s_setprio 0
	s_barrier
	s_add_i32 s50, s54, s35
	v_lshl_add_u64 v[144:145], s[26:27], 0, v[132:133]
	s_mov_b32 m0, s50
	ds_read_b128 v[188:191], v151 offset:16384
	ds_read_b128 v[192:195], v151 offset:17408
	ds_read_b128 v[196:199], v151 offset:18432
	ds_read_b128 v[200:203], v151 offset:19456
	ds_read_b128 v[204:207], v151 offset:20480
	ds_read_b128 v[208:211], v151 offset:21504
	ds_read_b128 v[212:215], v151 offset:22528
	ds_read_b128 v[216:219], v151 offset:23552
	global_load_lds_dwordx4 v[144:145], off
	s_add_i32 m0, s50, 0x2000
	s_add_u32 s50, s26, 0x40000
	v_lshl_add_u64 v[220:221], s[26:27], 0, v[128:129]
	s_addc_u32 s51, s27, 0
	s_add_i32 s62, s55, s35
	global_load_lds_dwordx4 v[220:221], off
	v_lshl_add_u64 v[222:223], s[50:51], 0, v[132:133]
	s_mov_b32 m0, s62
	v_lshl_add_u64 v[224:225], s[28:29], 0, v[130:131]
	global_load_lds_dwordx4 v[222:223], off
	v_lshl_add_u64 v[222:223], s[50:51], 0, v[128:129]
	s_add_i32 m0, s62, 0x2000
	s_nop 0
	global_load_lds_dwordx4 v[222:223], off
	v_lshl_add_u64 v[222:223], s[28:29], 0, v[134:135]
	s_mov_b32 m0, s23
	s_nop 0
	global_load_lds_dwordx4 v[222:223], off
	s_mov_b32 m0, s44
	s_nop 0
	global_load_lds_dwordx4 v[224:225], off
	s_waitcnt vmcnt(8)
	s_waitcnt lgkmcnt(0)
	s_barrier
; #define PG8_STAGE(bufoff, gbase, voff) do { _Pragma("unroll") for (int _i = 0; _i < 2; ++_i) \
;         __builtin_amdgcn_global_load_lds((const unsigned*)((const char*)(gbase) + (voff)[_i]), (LAS unsigned*)(lds + (bufoff) + ldsw + _i * 8192), 16, 0, 0); } while (0)
; #define PG8_LDA(dst, b, h) do { _Pragma("unroll") for (int m = 0; m < 4; ++m) _Pragma("unroll") for (int k = 0; k < 2; ++k) dst[m][k] = *(const LAS bf16x8*)(lds + PG8_SA(b, h) + aoff + m * 2048 + k * 1024); } while (0)
; #define PG8_LDB(dst, b, h) do { _Pragma("unroll") for (int n = 0; n < 2; ++n) _Pragma("unroll") for (int k = 0; k < 2; ++k) dst[n][k] = *(const LAS bf16x8*)(lds + PG8_SB(b, h) + boff + n * 2048 + k * 1024); } while (0)
; #define PG8_MMA(ai, bj, At, Bt) do { __builtin_amdgcn_s_setprio(1); _Pragma("unroll") for (int m = 0; m < 4; ++m) _Pragma("unroll") for (int n = 0; n < 2; ++n) _Pragma("unroll") for (int k = 0; k < 2; ++k) \
;         acc[ai][bj][m][n] = __builtin_amdgcn_mfma_f32_16x16x32_bf16(Bt[n][k], At[m][k], acc[ai][bj][m][n], 0, 0, 0); __builtin_amdgcn_s_setprio(0); } while (0)
; #define PG8_WAIT_V(n) asm volatile("s_waitcnt vmcnt(" #n ")" ::: "memory")
; #define PG8_WAIT_L(n) asm volatile("s_waitcnt lgkmcnt(" #n ")" ::: "memory")
; #define PG8_BAR __builtin_amdgcn_s_barrier()
; #define PG8_SCHED __builtin_amdgcn_sched_barrier(0)
; template <class Epi>
; __device__ __forceinline__ void gemm_phase(LAS unsigned char* lds, const Gemm g, const StaticOrder& S, const Epi& E) {
;     ...
;             PG8_WAIT_V(8); PG8_WAIT_L(0); PG8_BAR; PG8_MMA(1, 0, At, B0); PG8_MMA(1, 1, At, B1); PG8_BAR; PG8_SCHED;
;             PG8_LDB(B0, 1, 0); PG8_LDB(B1, 1, 1); PG8_SCHED; PG8_LDA(At, 1, 0); PG8_STAGE(PG8_SA(0, 1), a2 + hstepA, voffA);
;             PG8_WAIT_V(8); PG8_WAIT_L(0); PG8_BAR; PG8_MMA(0, 0, At, B0); PG8_MMA(0, 1, At, B1); PG8_BAR; PG8_SCHED;
;             PG8_LDA(At, 1, 1); PG8_STAGE(PG8_SB(1, 0), b3, voffB); PG8_STAGE(PG8_SB(1, 1), b3 + hstepB, voffB); PG8_STAGE(PG8_SA(1, 0), a3, voffA);
	s_setprio 1
	s_waitcnt lgkmcnt(0)
	v_mfma_f32_16x16x32_bf16 v[60:63], v[156:159], v[188:191], v[60:63]
	v_mfma_f32_16x16x32_bf16 v[44:47], v[156:159], v[196:199], v[44:47]
	v_mfma_f32_16x16x32_bf16 v[28:31], v[156:159], v[204:207], v[28:31]
	v_mfma_f32_16x16x32_bf16 v[12:15], v[156:159], v[212:215], v[12:15]
	v_mfma_f32_16x16x32_bf16 v[4:7], v[164:167], v[212:215], v[4:7]
	v_mfma_f32_16x16x32_bf16 v[20:23], v[164:167], v[204:207], v[20:23]
	v_mfma_f32_16x16x32_bf16 v[36:39], v[164:167], v[196:199], v[36:39]
	v_mfma_f32_16x16x32_bf16 v[52:55], v[164:167], v[188:191], v[52:55]
	v_mfma_f32_16x16x32_bf16 v[60:63], v[160:163], v[192:195], v[60:63]
	v_mfma_f32_16x16x32_bf16 v[44:47], v[160:163], v[200:203], v[44:47]
	v_mfma_f32_16x16x32_bf16 v[28:31], v[160:163], v[208:211], v[28:31]
	v_mfma_f32_16x16x32_bf16 v[12:15], v[160:163], v[216:219], v[12:15]
	v_mfma_f32_16x16x32_bf16 v[4:7], v[168:171], v[216:219], v[4:7]
	v_mfma_f32_16x16x32_bf16 v[20:23], v[168:171], v[208:211], v[20:23]
	v_mfma_f32_16x16x32_bf16 v[36:39], v[168:171], v[200:203], v[36:39]
	v_mfma_f32_16x16x32_bf16 v[52:55], v[168:171], v[192:195], v[52:55]
	s_setprio 0
	s_setprio 1
	v_mfma_f32_16x16x32_bf16 v[56:59], v[172:175], v[188:191], v[56:59]
	v_mfma_f32_16x16x32_bf16 v[40:43], v[172:175], v[196:199], v[40:43]
	v_mfma_f32_16x16x32_bf16 v[24:27], v[172:175], v[204:207], v[24:27]
	v_mfma_f32_16x16x32_bf16 v[8:11], v[172:175], v[212:215], v[8:11]
	v_mfma_f32_16x16x32_bf16 v[0:3], v[180:183], v[212:215], v[0:3]
	v_mfma_f32_16x16x32_bf16 v[16:19], v[180:183], v[204:207], v[16:19]
	v_mfma_f32_16x16x32_bf16 v[32:35], v[180:183], v[196:199], v[32:35]
	v_mfma_f32_16x16x32_bf16 v[48:51], v[180:183], v[188:191], v[48:51]
	v_mfma_f32_16x16x32_bf16 v[56:59], v[176:179], v[192:195], v[56:59]
	v_mfma_f32_16x16x32_bf16 v[40:43], v[176:179], v[200:203], v[40:43]
	v_mfma_f32_16x16x32_bf16 v[24:27], v[176:179], v[208:211], v[24:27]
	v_mfma_f32_16x16x32_bf16 v[8:11], v[176:179], v[216:219], v[8:11]
	v_mfma_f32_16x16x32_bf16 v[0:3], v[184:187], v[216:219], v[0:3]
	v_mfma_f32_16x16x32_bf16 v[16:19], v[184:187], v[208:211], v[16:19]
	v_mfma_f32_16x16x32_bf16 v[32:35], v[184:187], v[200:203], v[32:35]
	v_mfma_f32_16x16x32_bf16 v[48:51], v[184:187], v[192:195], v[48:51]
	s_setprio 0
	s_barrier
	s_add_i32 s50, 0, 0x18000
	s_add_i32 s51, 0, 0x1c000
	v_add_u32_e32 v168, s50, v147
	v_add_u32_e32 v184, s51, v147
	ds_read_b128 v[156:159], v168
	ds_read_b128 v[160:163], v168 offset:1024
	ds_read_b128 v[164:167], v168 offset:2048
	ds_read_b128 v[168:171], v168 offset:3072
	ds_read_b128 v[172:175], v184
	ds_read_b128 v[176:179], v184 offset:1024
	ds_read_b128 v[180:183], v184 offset:2048
	ds_read_b128 v[184:187], v184 offset:3072
	s_add_u32 s28, s28, 0x40000
	s_addc_u32 s29, s29, 0
	s_mov_b32 m0, s45
	v_lshl_add_u64 v[226:227], s[28:29], 0, v[134:135]
	ds_read_b128 v[188:191], v151 offset:32768
	ds_read_b128 v[192:195], v151 offset:33792
	ds_read_b128 v[196:199], v151 offset:34816
	ds_read_b128 v[200:203], v151 offset:35840
	ds_read_b128 v[204:207], v151 offset:36864
	ds_read_b128 v[208:211], v151 offset:37888
	ds_read_b128 v[212:215], v151 offset:38912
	ds_read_b128 v[216:219], v151 offset:39936
	global_load_lds_dwordx4 v[226:227], off
	v_lshl_add_u64 v[226:227], s[28:29], 0, v[130:131]
	s_mov_b32 m0, s46
	s_nop 0
	global_load_lds_dwordx4 v[226:227], off
	s_waitcnt vmcnt(8)
	s_waitcnt lgkmcnt(0)
	s_barrier
	s_setprio 1
	s_waitcnt lgkmcnt(0)
	v_mfma_f32_16x16x32_bf16 v[116:119], v[156:159], v[188:191], v[116:119]
	v_mfma_f32_16x16x32_bf16 v[108:111], v[156:159], v[196:199], v[108:111]
	v_mfma_f32_16x16x32_bf16 v[92:95], v[156:159], v[204:207], v[92:95]
	v_mfma_f32_16x16x32_bf16 v[76:79], v[156:159], v[212:215], v[76:79]
	v_mfma_f32_16x16x32_bf16 v[68:71], v[164:167], v[212:215], v[68:71]
	v_mfma_f32_16x16x32_bf16 v[84:87], v[164:167], v[204:207], v[84:87]
	v_mfma_f32_16x16x32_bf16 v[100:103], v[164:167], v[196:199], v[100:103]
	v_mfma_f32_16x16x32_bf16 v[112:115], v[164:167], v[188:191], v[112:115]
	v_mfma_f32_16x16x32_bf16 v[116:119], v[160:163], v[192:195], v[116:119]
	v_mfma_f32_16x16x32_bf16 v[108:111], v[160:163], v[200:203], v[108:111]
	v_mfma_f32_16x16x32_bf16 v[92:95], v[160:163], v[208:211], v[92:95]
	v_mfma_f32_16x16x32_bf16 v[76:79], v[160:163], v[216:219], v[76:79]
	v_mfma_f32_16x16x32_bf16 v[68:71], v[168:171], v[216:219], v[68:71]
	v_mfma_f32_16x16x32_bf16 v[84:87], v[168:171], v[208:211], v[84:87]
	v_mfma_f32_16x16x32_bf16 v[100:103], v[168:171], v[200:203], v[100:103]
	v_mfma_f32_16x16x32_bf16 v[112:115], v[168:171], v[192:195], v[112:115]
	s_setprio 0
	s_setprio 1
	v_mfma_f32_16x16x32_bf16 v[124:127], v[172:175], v[188:191], v[124:127]
	v_mfma_f32_16x16x32_bf16 v[104:107], v[172:175], v[196:199], v[104:107]
	v_mfma_f32_16x16x32_bf16 v[88:91], v[172:175], v[204:207], v[88:91]
	v_mfma_f32_16x16x32_bf16 v[72:75], v[172:175], v[212:215], v[72:75]
	v_mfma_f32_16x16x32_bf16 v[64:67], v[180:183], v[212:215], v[64:67]
	v_mfma_f32_16x16x32_bf16 v[80:83], v[180:183], v[204:207], v[80:83]
	v_mfma_f32_16x16x32_bf16 v[96:99], v[180:183], v[196:199], v[96:99]
	v_mfma_f32_16x16x32_bf16 v[120:123], v[180:183], v[188:191], v[120:123]
	v_mfma_f32_16x16x32_bf16 v[124:127], v[176:179], v[192:195], v[124:127]
	v_mfma_f32_16x16x32_bf16 v[104:107], v[176:179], v[200:203], v[104:107]
	v_mfma_f32_16x16x32_bf16 v[88:91], v[176:179], v[208:211], v[88:91]
	v_mfma_f32_16x16x32_bf16 v[72:75], v[176:179], v[216:219], v[72:75]
	v_mfma_f32_16x16x32_bf16 v[64:67], v[184:187], v[216:219], v[64:67]
	v_mfma_f32_16x16x32_bf16 v[80:83], v[184:187], v[208:211], v[80:83]
	v_mfma_f32_16x16x32_bf16 v[96:99], v[184:187], v[200:203], v[96:99]
	v_mfma_f32_16x16x32_bf16 v[120:123], v[184:187], v[192:195], v[120:123]
	s_setprio 0
	s_barrier
; #define PG8_STAGE(bufoff, gbase, voff) do { _Pragma("unroll") for (int _i = 0; _i < 2; ++_i) \
;         __builtin_amdgcn_global_load_lds((const unsigned*)((const char*)(gbase) + (voff)[_i]), (LAS unsigned*)(lds + (bufoff) + ldsw + _i * 8192), 16, 0, 0); } while (0)
; #define PG8_LDA(dst, b, h) do { _Pragma("unroll") for (int m = 0; m < 4; ++m) _Pragma("unroll") for (int k = 0; k < 2; ++k) dst[m][k] = *(const LAS bf16x8*)(lds + PG8_SA(b, h) + aoff + m * 2048 + k * 1024); } while (0)
; #define PG8_MMA(ai, bj, At, Bt) do { __builtin_amdgcn_s_setprio(1); _Pragma("unroll") for (int m = 0; m < 4; ++m) _Pragma("unroll") for (int n = 0; n < 2; ++n) _Pragma("unroll") for (int k = 0; k < 2; ++k) \
;         acc[ai][bj][m][n] = __builtin_amdgcn_mfma_f32_16x16x32_bf16(Bt[n][k], At[m][k], acc[ai][bj][m][n], 0, 0, 0); __builtin_amdgcn_s_setprio(0); } while (0)
; #define PG8_WAIT_V(n) asm volatile("s_waitcnt vmcnt(" #n ")" ::: "memory")
; #define PG8_WAIT_L(n) asm volatile("s_waitcnt lgkmcnt(" #n ")" ::: "memory")
; #define PG8_BAR __builtin_amdgcn_s_barrier()
; #define PG8_SCHED __builtin_amdgcn_sched_barrier(0)
; template <class Epi>
; __device__ __forceinline__ void gemm_phase(LAS unsigned char* lds, const Gemm g, const StaticOrder& S, const Epi& E) {
;     ...
;             PG8_LDA(At, 1, 1); PG8_STAGE(PG8_SB(1, 0), b3, voffB); PG8_STAGE(PG8_SB(1, 1), b3 + hstepB, voffB); PG8_STAGE(PG8_SA(1, 0), a3, voffA);
;             PG8_WAIT_V(8); PG8_WAIT_L(0); PG8_BAR; PG8_MMA(1, 0, At, B0); PG8_MMA(1, 1, At, B1); PG8_BAR; PG8_SCHED;
;         }
;         if (wr == 0) PG8_BAR;
	s_add_i32 s28, s50, s35
	v_lshl_add_u64 v[144:145], v[144:145], 0, s[8:9]
	s_mov_b32 m0, s28
	ds_read_b128 v[188:191], v151 offset:49152
	ds_read_b128 v[192:195], v151 offset:50176
	ds_read_b128 v[196:199], v151 offset:51200
	ds_read_b128 v[200:203], v151 offset:52224
	ds_read_b128 v[204:207], v151 offset:53248
	ds_read_b128 v[208:211], v151 offset:54272
	ds_read_b128 v[212:215], v151 offset:55296
	ds_read_b128 v[216:219], v151 offset:56320
	global_load_lds_dwordx4 v[144:145], off
	s_add_i32 m0, s28, 0x2000
	s_add_u32 s26, s26, 0x40080
	v_lshl_add_u64 v[144:145], v[220:221], 0, s[8:9]
	s_addc_u32 s27, s27, 0
	s_add_i32 s28, s51, s35
	global_load_lds_dwordx4 v[144:145], off
	v_lshl_add_u64 v[144:145], s[26:27], 0, v[132:133]
	s_mov_b32 m0, s28
	s_nop 0
	global_load_lds_dwordx4 v[144:145], off
	v_lshl_add_u64 v[144:145], s[26:27], 0, v[128:129]
	s_add_i32 m0, s28, 0x2000
	s_nop 0
	global_load_lds_dwordx4 v[144:145], off
	v_lshl_add_u64 v[144:145], v[222:223], 0, s[8:9]
	s_mov_b32 m0, s48
	s_nop 0
	global_load_lds_dwordx4 v[144:145], off
	v_lshl_add_u64 v[144:145], v[224:225], 0, s[8:9]
	s_mov_b32 m0, s49
	s_nop 0
	global_load_lds_dwordx4 v[144:145], off
	s_waitcnt vmcnt(8)
	s_waitcnt lgkmcnt(0)
	s_barrier
	s_setprio 1
	s_waitcnt lgkmcnt(0)
	v_mfma_f32_16x16x32_bf16 v[60:63], v[156:159], v[188:191], v[60:63]
	v_mfma_f32_16x16x32_bf16 v[44:47], v[156:159], v[196:199], v[44:47]
	v_mfma_f32_16x16x32_bf16 v[28:31], v[156:159], v[204:207], v[28:31]
	v_mfma_f32_16x16x32_bf16 v[12:15], v[156:159], v[212:215], v[12:15]
	v_mfma_f32_16x16x32_bf16 v[4:7], v[164:167], v[212:215], v[4:7]
	v_mfma_f32_16x16x32_bf16 v[20:23], v[164:167], v[204:207], v[20:23]
	v_mfma_f32_16x16x32_bf16 v[36:39], v[164:167], v[196:199], v[36:39]
	v_mfma_f32_16x16x32_bf16 v[52:55], v[164:167], v[188:191], v[52:55]
	v_mfma_f32_16x16x32_bf16 v[60:63], v[160:163], v[192:195], v[60:63]
	v_mfma_f32_16x16x32_bf16 v[44:47], v[160:163], v[200:203], v[44:47]
	v_mfma_f32_16x16x32_bf16 v[28:31], v[160:163], v[208:211], v[28:31]
	v_mfma_f32_16x16x32_bf16 v[12:15], v[160:163], v[216:219], v[12:15]
	v_mfma_f32_16x16x32_bf16 v[4:7], v[168:171], v[216:219], v[4:7]
	v_mfma_f32_16x16x32_bf16 v[20:23], v[168:171], v[208:211], v[20:23]
	v_mfma_f32_16x16x32_bf16 v[36:39], v[168:171], v[200:203], v[36:39]
	v_mfma_f32_16x16x32_bf16 v[52:55], v[168:171], v[192:195], v[52:55]
	s_setprio 0
	s_setprio 1
	v_mfma_f32_16x16x32_bf16 v[56:59], v[172:175], v[188:191], v[56:59]
	v_mfma_f32_16x16x32_bf16 v[40:43], v[172:175], v[196:199], v[40:43]
	v_mfma_f32_16x16x32_bf16 v[24:27], v[172:175], v[204:207], v[24:27]
	v_mfma_f32_16x16x32_bf16 v[8:11], v[172:175], v[212:215], v[8:11]
	v_mfma_f32_16x16x32_bf16 v[0:3], v[180:183], v[212:215], v[0:3]
	v_mfma_f32_16x16x32_bf16 v[16:19], v[180:183], v[204:207], v[16:19]
	v_mfma_f32_16x16x32_bf16 v[32:35], v[180:183], v[196:199], v[32:35]
	v_mfma_f32_16x16x32_bf16 v[48:51], v[180:183], v[188:191], v[48:51]
	v_mfma_f32_16x16x32_bf16 v[56:59], v[176:179], v[192:195], v[56:59]
	v_mfma_f32_16x16x32_bf16 v[40:43], v[176:179], v[200:203], v[40:43]
	v_mfma_f32_16x16x32_bf16 v[24:27], v[176:179], v[208:211], v[24:27]
	v_mfma_f32_16x16x32_bf16 v[8:11], v[176:179], v[216:219], v[8:11]
	v_mfma_f32_16x16x32_bf16 v[0:3], v[184:187], v[216:219], v[0:3]
	v_mfma_f32_16x16x32_bf16 v[16:19], v[184:187], v[208:211], v[16:19]
	v_mfma_f32_16x16x32_bf16 v[32:35], v[184:187], v[200:203], v[32:35]
	v_mfma_f32_16x16x32_bf16 v[48:51], v[184:187], v[192:195], v[48:51]
	s_setprio 0
	s_barrier
	s_add_i32 s61, s61, 2
	s_add_u32 s59, s59, 0x100
	s_addc_u32 s60, s60, 0
	s_add_u32 s24, s24, 0x100
	s_addc_u32 s25, s25, 0
	s_cmp_gt_u32 s61, 13
	s_cbranch_scc0 .LBB0_162
	s_and_b64 vcc, exec, s[10:11]
	s_cbranch_vccz .LBB0_165
	s_barrier

; #define PG8_STAGE(bufoff, gbase, voff) do { _Pragma("unroll") for (int _i = 0; _i < 2; ++_i) \
;         __builtin_amdgcn_global_load_lds((const unsigned*)((const char*)(gbase) + (voff)[_i]), (LAS unsigned*)(lds + (bufoff) + ldsw + _i * 8192), 16, 0, 0); } while (0)
; #define PG8_LDA(dst, b, h) do { _Pragma("unroll") for (int m = 0; m < 4; ++m) _Pragma("unroll") for (int k = 0; k < 2; ++k) dst[m][k] = *(const LAS bf16x8*)(lds + PG8_SA(b, h) + aoff + m * 2048 + k * 1024); } while (0)
; #define PG8_LDB(dst, b, h) do { _Pragma("unroll") for (int n = 0; n < 2; ++n) _Pragma("unroll") for (int k = 0; k < 2; ++k) dst[n][k] = *(const LAS bf16x8*)(lds + PG8_SB(b, h) + boff + n * 2048 + k * 1024); } while (0)
; #define PG8_MMA(ai, bj, At, Bt) do { __builtin_amdgcn_s_setprio(1); _Pragma("unroll") for (int m = 0; m < 4; ++m) _Pragma("unroll") for (int n = 0; n < 2; ++n) _Pragma("unroll") for (int k = 0; k < 2; ++k) \
;         acc[ai][bj][m][n] = __builtin_amdgcn_mfma_f32_16x16x32_bf16(Bt[n][k], At[m][k], acc[ai][bj][m][n], 0, 0, 0); __builtin_amdgcn_s_setprio(0); } while (0)
; #define PG8_WAIT_V(n) asm volatile("s_waitcnt vmcnt(" #n ")" ::: "memory")
; #define PG8_WAIT_L(n) asm volatile("s_waitcnt lgkmcnt(" #n ")" ::: "memory")
; #define PG8_BAR __builtin_amdgcn_s_barrier()
; #define PG8_SCHED __builtin_amdgcn_sched_barrier(0)
; template <class Epi>
; __device__ __forceinline__ void gemm_phase(LAS unsigned char* lds, const Gemm g, const StaticOrder& S, const Epi& E) {
;     ...
;             PG8_LDB(B0, 0, 0); PG8_LDB(B1, 0, 1); PG8_SCHED; PG8_LDA(At, 0, 0); PG8_STAGE(PG8_SA(1, 1), a1 + hstepA, voffA);
;             PG8_WAIT_V(8); PG8_WAIT_L(0); PG8_BAR; PG8_MMA(0, 0, At, B0); PG8_MMA(0, 1, At, B1); PG8_BAR; PG8_SCHED;
;             PG8_LDA(At, 0, 1); PG8_STAGE(PG8_SB(0, 0), b2, voffB); PG8_STAGE(PG8_SB(0, 1), b2 + hstepB, voffB); PG8_STAGE(PG8_SA(0, 0), a2, voffA);
;             PG8_WAIT_V(8); PG8_WAIT_L(0); PG8_BAR; PG8_MMA(1, 0, At, B0); PG8_MMA(1, 1, At, B1); PG8_BAR; PG8_SCHED;
.LBB0_228:
	ds_read_b128 v[128:131], v192
	ds_read_b128 v[132:135], v192 offset:1024
	ds_read_b128 v[136:139], v192 offset:2048
	ds_read_b128 v[140:143], v192 offset:3072
	ds_read_b128 v[144:147], v193
	ds_read_b128 v[148:151], v193 offset:1024
	ds_read_b128 v[172:175], v193 offset:2048
	ds_read_b128 v[176:179], v193 offset:3072
	s_add_u32 s26, s24, 0x100
	s_addc_u32 s27, s25, 0
	s_cmp_eq_u32 s64, 40
	s_cselect_b32 s31, s7, s27
	s_cselect_b32 s30, s6, s26
	s_cselect_b32 s29, s23, s63
	s_cselect_b32 s28, s22, s62
	v_lshl_add_u64 v[188:189], s[24:25], 0, v[166:167]
	s_add_i32 m0, s44, 0xc000
	ds_read_b128 v[180:183], v194
	ds_read_b128 v[184:187], v194 offset:1024
	ds_read_b128 v[196:199], v194 offset:2048
	ds_read_b128 v[200:203], v194 offset:3072
	ds_read_b128 v[204:207], v194 offset:4096
	ds_read_b128 v[208:211], v194 offset:5120
	ds_read_b128 v[212:215], v194 offset:6144
	ds_read_b128 v[216:219], v194 offset:7168
	global_load_lds_dwordx4 v[188:189], off
	v_lshl_add_u64 v[188:189], s[24:25], 0, v[164:165]
	s_add_i32 m0, s44, 0xe000
	s_nop 0
	global_load_lds_dwordx4 v[188:189], off
	s_waitcnt vmcnt(8)
	s_waitcnt lgkmcnt(0)
	s_barrier
	s_setprio 1
	s_waitcnt lgkmcnt(0)
	v_mfma_f32_16x16x32_bf16 v[124:127], v[128:131], v[180:183], v[124:127]
	v_mfma_f32_16x16x32_bf16 v[108:111], v[128:131], v[196:199], v[108:111]
	v_mfma_f32_16x16x32_bf16 v[92:95], v[128:131], v[204:207], v[92:95]
	v_mfma_f32_16x16x32_bf16 v[76:79], v[128:131], v[212:215], v[76:79]
	v_mfma_f32_16x16x32_bf16 v[72:75], v[136:139], v[212:215], v[72:75]
	v_mfma_f32_16x16x32_bf16 v[88:91], v[136:139], v[204:207], v[88:91]
	v_mfma_f32_16x16x32_bf16 v[104:107], v[136:139], v[196:199], v[104:107]
	v_mfma_f32_16x16x32_bf16 v[120:123], v[136:139], v[180:183], v[120:123]
	v_mfma_f32_16x16x32_bf16 v[124:127], v[132:135], v[184:187], v[124:127]
	v_mfma_f32_16x16x32_bf16 v[108:111], v[132:135], v[200:203], v[108:111]
	v_mfma_f32_16x16x32_bf16 v[92:95], v[132:135], v[208:211], v[92:95]
	v_mfma_f32_16x16x32_bf16 v[76:79], v[132:135], v[216:219], v[76:79]
	v_mfma_f32_16x16x32_bf16 v[72:75], v[140:143], v[216:219], v[72:75]
	v_mfma_f32_16x16x32_bf16 v[88:91], v[140:143], v[208:211], v[88:91]
	v_mfma_f32_16x16x32_bf16 v[104:107], v[140:143], v[200:203], v[104:107]
	v_mfma_f32_16x16x32_bf16 v[120:123], v[140:143], v[184:187], v[120:123]
	s_setprio 0
	s_setprio 1
	v_mfma_f32_16x16x32_bf16 v[116:119], v[144:147], v[180:183], v[116:119]
	v_mfma_f32_16x16x32_bf16 v[100:103], v[144:147], v[196:199], v[100:103]
	v_mfma_f32_16x16x32_bf16 v[84:87], v[144:147], v[204:207], v[84:87]
	v_mfma_f32_16x16x32_bf16 v[68:71], v[144:147], v[212:215], v[68:71]
	v_mfma_f32_16x16x32_bf16 v[64:67], v[172:175], v[212:215], v[64:67]
	v_mfma_f32_16x16x32_bf16 v[80:83], v[172:175], v[204:207], v[80:83]
	v_mfma_f32_16x16x32_bf16 v[96:99], v[172:175], v[196:199], v[96:99]
	v_mfma_f32_16x16x32_bf16 v[112:115], v[172:175], v[180:183], v[112:115]
	v_mfma_f32_16x16x32_bf16 v[116:119], v[148:151], v[184:187], v[116:119]
	v_mfma_f32_16x16x32_bf16 v[100:103], v[148:151], v[200:203], v[100:103]
	v_mfma_f32_16x16x32_bf16 v[84:87], v[148:151], v[208:211], v[84:87]
	v_mfma_f32_16x16x32_bf16 v[68:71], v[148:151], v[216:219], v[68:71]
	v_mfma_f32_16x16x32_bf16 v[64:67], v[176:179], v[216:219], v[64:67]
	v_mfma_f32_16x16x32_bf16 v[80:83], v[176:179], v[208:211], v[80:83]
	v_mfma_f32_16x16x32_bf16 v[96:99], v[176:179], v[200:203], v[96:99]
	v_mfma_f32_16x16x32_bf16 v[112:115], v[176:179], v[184:187], v[112:115]
	s_setprio 0
	s_barrier
	s_add_i32 s24, s57, s37
	v_lshl_add_u64 v[188:189], s[28:29], 0, v[158:159]
	s_mov_b32 m0, s24
	ds_read_b128 v[180:183], v194 offset:16384
	ds_read_b128 v[184:187], v194 offset:17408
	ds_read_b128 v[196:199], v194 offset:18432
	ds_read_b128 v[200:203], v194 offset:19456
	ds_read_b128 v[204:207], v194 offset:20480
	ds_read_b128 v[208:211], v194 offset:21504
	ds_read_b128 v[212:215], v194 offset:22528
	ds_read_b128 v[216:219], v194 offset:23552
	global_load_lds_dwordx4 v[188:189], off
	s_add_i32 m0, s24, 0x2000
	s_add_u32 s24, s28, 0xb0000
	v_lshl_add_u64 v[220:221], s[28:29], 0, v[162:163]
	s_addc_u32 s25, s29, 0
	s_add_i32 s50, s58, s37
	global_load_lds_dwordx4 v[220:221], off
	v_lshl_add_u64 v[222:223], s[24:25], 0, v[158:159]
	s_mov_b32 m0, s50
	v_lshl_add_u64 v[224:225], s[30:31], 0, v[160:161]
	global_load_lds_dwordx4 v[222:223], off
	v_lshl_add_u64 v[222:223], s[24:25], 0, v[162:163]
	s_add_i32 m0, s50, 0x2000
	s_nop 0
	global_load_lds_dwordx4 v[222:223], off
	v_lshl_add_u64 v[222:223], s[30:31], 0, v[156:157]
	s_mov_b32 m0, s44
	s_nop 0
	global_load_lds_dwordx4 v[222:223], off
	s_mov_b32 m0, s45
	s_nop 0
	global_load_lds_dwordx4 v[224:225], off
	s_waitcnt vmcnt(8)
	s_waitcnt lgkmcnt(0)
	s_barrier
; #define PG8_STAGE(bufoff, gbase, voff) do { _Pragma("unroll") for (int _i = 0; _i < 2; ++_i) \
;         __builtin_amdgcn_global_load_lds((const unsigned*)((const char*)(gbase) + (voff)[_i]), (LAS unsigned*)(lds + (bufoff) + ldsw + _i * 8192), 16, 0, 0); } while (0)
; #define PG8_LDA(dst, b, h) do { _Pragma("unroll") for (int m = 0; m < 4; ++m) _Pragma("unroll") for (int k = 0; k < 2; ++k) dst[m][k] = *(const LAS bf16x8*)(lds + PG8_SA(b, h) + aoff + m * 2048 + k * 1024); } while (0)
; #define PG8_LDB(dst, b, h) do { _Pragma("unroll") for (int n = 0; n < 2; ++n) _Pragma("unroll") for (int k = 0; k < 2; ++k) dst[n][k] = *(const LAS bf16x8*)(lds + PG8_SB(b, h) + boff + n * 2048 + k * 1024); } while (0)
; #define PG8_MMA(ai, bj, At, Bt) do { __builtin_amdgcn_s_setprio(1); _Pragma("unroll") for (int m = 0; m < 4; ++m) _Pragma("unroll") for (int n = 0; n < 2; ++n) _Pragma("unroll") for (int k = 0; k < 2; ++k) \
;         acc[ai][bj][m][n] = __builtin_amdgcn_mfma_f32_16x16x32_bf16(Bt[n][k], At[m][k], acc[ai][bj][m][n], 0, 0, 0); __builtin_amdgcn_s_setprio(0); } while (0)
; #define PG8_WAIT_V(n) asm volatile("s_waitcnt vmcnt(" #n ")" ::: "memory")
; #define PG8_WAIT_L(n) asm volatile("s_waitcnt lgkmcnt(" #n ")" ::: "memory")
; #define PG8_BAR __builtin_amdgcn_s_barrier()
; #define PG8_SCHED __builtin_amdgcn_sched_barrier(0)
; template <class Epi>
; __device__ __forceinline__ void gemm_phase(LAS unsigned char* lds, const Gemm g, const StaticOrder& S, const Epi& E) {
;     ...
;             PG8_WAIT_V(8); PG8_WAIT_L(0); PG8_BAR; PG8_MMA(1, 0, At, B0); PG8_MMA(1, 1, At, B1); PG8_BAR; PG8_SCHED;
;             PG8_LDB(B0, 1, 0); PG8_LDB(B1, 1, 1); PG8_SCHED; PG8_LDA(At, 1, 0); PG8_STAGE(PG8_SA(0, 1), a2 + hstepA, voffA);
;             PG8_WAIT_V(8); PG8_WAIT_L(0); PG8_BAR; PG8_MMA(0, 0, At, B0); PG8_MMA(0, 1, At, B1); PG8_BAR; PG8_SCHED;
	s_setprio 1
	s_waitcnt lgkmcnt(0)
	v_mfma_f32_16x16x32_bf16 v[60:63], v[128:131], v[180:183], v[60:63]
	v_mfma_f32_16x16x32_bf16 v[44:47], v[128:131], v[196:199], v[44:47]
	v_mfma_f32_16x16x32_bf16 v[28:31], v[128:131], v[204:207], v[28:31]
	v_mfma_f32_16x16x32_bf16 v[12:15], v[128:131], v[212:215], v[12:15]
	v_mfma_f32_16x16x32_bf16 v[8:11], v[136:139], v[212:215], v[8:11]
	v_mfma_f32_16x16x32_bf16 v[24:27], v[136:139], v[204:207], v[24:27]
	v_mfma_f32_16x16x32_bf16 v[40:43], v[136:139], v[196:199], v[40:43]
	v_mfma_f32_16x16x32_bf16 v[56:59], v[136:139], v[180:183], v[56:59]
	v_mfma_f32_16x16x32_bf16 v[60:63], v[132:135], v[184:187], v[60:63]
	v_mfma_f32_16x16x32_bf16 v[44:47], v[132:135], v[200:203], v[44:47]
	v_mfma_f32_16x16x32_bf16 v[28:31], v[132:135], v[208:211], v[28:31]
	v_mfma_f32_16x16x32_bf16 v[12:15], v[132:135], v[216:219], v[12:15]
	v_mfma_f32_16x16x32_bf16 v[8:11], v[140:143], v[216:219], v[8:11]
	v_mfma_f32_16x16x32_bf16 v[24:27], v[140:143], v[208:211], v[24:27]
	v_mfma_f32_16x16x32_bf16 v[40:43], v[140:143], v[200:203], v[40:43]
	v_mfma_f32_16x16x32_bf16 v[56:59], v[140:143], v[184:187], v[56:59]
	s_setprio 0
	s_setprio 1
	v_mfma_f32_16x16x32_bf16 v[52:55], v[144:147], v[180:183], v[52:55]
	v_mfma_f32_16x16x32_bf16 v[36:39], v[144:147], v[196:199], v[36:39]
	v_mfma_f32_16x16x32_bf16 v[20:23], v[144:147], v[204:207], v[20:23]
	v_mfma_f32_16x16x32_bf16 v[4:7], v[144:147], v[212:215], v[4:7]
	v_mfma_f32_16x16x32_bf16 v[0:3], v[172:175], v[212:215], v[0:3]
	v_mfma_f32_16x16x32_bf16 v[16:19], v[172:175], v[204:207], v[16:19]
	v_mfma_f32_16x16x32_bf16 v[32:35], v[172:175], v[196:199], v[32:35]
	v_mfma_f32_16x16x32_bf16 v[48:51], v[172:175], v[180:183], v[48:51]
	v_mfma_f32_16x16x32_bf16 v[52:55], v[148:151], v[184:187], v[52:55]
	v_mfma_f32_16x16x32_bf16 v[36:39], v[148:151], v[200:203], v[36:39]
	v_mfma_f32_16x16x32_bf16 v[20:23], v[148:151], v[208:211], v[20:23]
	v_mfma_f32_16x16x32_bf16 v[4:7], v[148:151], v[216:219], v[4:7]
	v_mfma_f32_16x16x32_bf16 v[0:3], v[176:179], v[216:219], v[0:3]
	v_mfma_f32_16x16x32_bf16 v[16:19], v[176:179], v[208:211], v[16:19]
	v_mfma_f32_16x16x32_bf16 v[32:35], v[176:179], v[200:203], v[32:35]
	v_mfma_f32_16x16x32_bf16 v[48:51], v[176:179], v[184:187], v[48:51]
	s_setprio 0
	s_barrier
	s_add_i32 s50, 0, 0x18000
	s_add_i32 s51, 0, 0x1c000
	v_add_u32_e32 v140, s50, v190
	v_add_u32_e32 v176, s51, v190
	ds_read_b128 v[128:131], v140
	ds_read_b128 v[132:135], v140 offset:1024
	ds_read_b128 v[136:139], v140 offset:2048
	ds_read_b128 v[140:143], v140 offset:3072
	ds_read_b128 v[144:147], v176
	ds_read_b128 v[148:151], v176 offset:1024
	ds_read_b128 v[172:175], v176 offset:2048
	ds_read_b128 v[176:179], v176 offset:3072
	s_add_u32 s24, s30, 0xb0000
	s_addc_u32 s25, s31, 0
	s_mov_b32 m0, s46
	v_lshl_add_u64 v[226:227], s[24:25], 0, v[156:157]
	ds_read_b128 v[180:183], v194 offset:32768
	ds_read_b128 v[184:187], v194 offset:33792
	ds_read_b128 v[196:199], v194 offset:34816
	ds_read_b128 v[200:203], v194 offset:35840
	ds_read_b128 v[204:207], v194 offset:36864
	ds_read_b128 v[208:211], v194 offset:37888
	ds_read_b128 v[212:215], v194 offset:38912
	ds_read_b128 v[216:219], v194 offset:39936
	global_load_lds_dwordx4 v[226:227], off
	v_lshl_add_u64 v[226:227], s[24:25], 0, v[160:161]
	s_mov_b32 m0, s47
	s_nop 0
	global_load_lds_dwordx4 v[226:227], off
	s_waitcnt vmcnt(8)
	s_waitcnt lgkmcnt(0)
	s_barrier
	s_setprio 1
	s_waitcnt lgkmcnt(0)
	v_mfma_f32_16x16x32_bf16 v[124:127], v[128:131], v[180:183], v[124:127]
	v_mfma_f32_16x16x32_bf16 v[108:111], v[128:131], v[196:199], v[108:111]
	v_mfma_f32_16x16x32_bf16 v[92:95], v[128:131], v[204:207], v[92:95]
	v_mfma_f32_16x16x32_bf16 v[76:79], v[128:131], v[212:215], v[76:79]
	v_mfma_f32_16x16x32_bf16 v[72:75], v[136:139], v[212:215], v[72:75]
	v_mfma_f32_16x16x32_bf16 v[88:91], v[136:139], v[204:207], v[88:91]
	v_mfma_f32_16x16x32_bf16 v[104:107], v[136:139], v[196:199], v[104:107]
	v_mfma_f32_16x16x32_bf16 v[120:123], v[136:139], v[180:183], v[120:123]
	v_mfma_f32_16x16x32_bf16 v[124:127], v[132:135], v[184:187], v[124:127]
	v_mfma_f32_16x16x32_bf16 v[108:111], v[132:135], v[200:203], v[108:111]
	v_mfma_f32_16x16x32_bf16 v[92:95], v[132:135], v[208:211], v[92:95]
	v_mfma_f32_16x16x32_bf16 v[76:79], v[132:135], v[216:219], v[76:79]
	v_mfma_f32_16x16x32_bf16 v[72:75], v[140:143], v[216:219], v[72:75]
	v_mfma_f32_16x16x32_bf16 v[88:91], v[140:143], v[208:211], v[88:91]
	v_mfma_f32_16x16x32_bf16 v[104:107], v[140:143], v[200:203], v[104:107]
	v_mfma_f32_16x16x32_bf16 v[120:123], v[140:143], v[184:187], v[120:123]
	s_setprio 0
	s_setprio 1
	v_mfma_f32_16x16x32_bf16 v[116:119], v[144:147], v[180:183], v[116:119]
	v_mfma_f32_16x16x32_bf16 v[100:103], v[144:147], v[196:199], v[100:103]
	v_mfma_f32_16x16x32_bf16 v[84:87], v[144:147], v[204:207], v[84:87]
	v_mfma_f32_16x16x32_bf16 v[68:71], v[144:147], v[212:215], v[68:71]
	v_mfma_f32_16x16x32_bf16 v[64:67], v[172:175], v[212:215], v[64:67]
	v_mfma_f32_16x16x32_bf16 v[80:83], v[172:175], v[204:207], v[80:83]
	v_mfma_f32_16x16x32_bf16 v[96:99], v[172:175], v[196:199], v[96:99]
	v_mfma_f32_16x16x32_bf16 v[112:115], v[172:175], v[180:183], v[112:115]
	v_mfma_f32_16x16x32_bf16 v[116:119], v[148:151], v[184:187], v[116:119]
	v_mfma_f32_16x16x32_bf16 v[100:103], v[148:151], v[200:203], v[100:103]
	v_mfma_f32_16x16x32_bf16 v[84:87], v[148:151], v[208:211], v[84:87]
	v_mfma_f32_16x16x32_bf16 v[68:71], v[148:151], v[216:219], v[68:71]
	v_mfma_f32_16x16x32_bf16 v[64:67], v[176:179], v[216:219], v[64:67]
	v_mfma_f32_16x16x32_bf16 v[80:83], v[176:179], v[208:211], v[80:83]
	v_mfma_f32_16x16x32_bf16 v[96:99], v[176:179], v[200:203], v[96:99]
	v_mfma_f32_16x16x32_bf16 v[112:115], v[176:179], v[184:187], v[112:115]
	s_setprio 0
	s_barrier
; #define PG8_STAGE(bufoff, gbase, voff) do { _Pragma("unroll") for (int _i = 0; _i < 2; ++_i) \
;         __builtin_amdgcn_global_load_lds((const unsigned*)((const char*)(gbase) + (voff)[_i]), (LAS unsigned*)(lds + (bufoff) + ldsw + _i * 8192), 16, 0, 0); } while (0)
; #define PG8_LDA(dst, b, h) do { _Pragma("unroll") for (int m = 0; m < 4; ++m) _Pragma("unroll") for (int k = 0; k < 2; ++k) dst[m][k] = *(const LAS bf16x8*)(lds + PG8_SA(b, h) + aoff + m * 2048 + k * 1024); } while (0)
; #define PG8_MMA(ai, bj, At, Bt) do { __builtin_amdgcn_s_setprio(1); _Pragma("unroll") for (int m = 0; m < 4; ++m) _Pragma("unroll") for (int n = 0; n < 2; ++n) _Pragma("unroll") for (int k = 0; k < 2; ++k) \
;         acc[ai][bj][m][n] = __builtin_amdgcn_mfma_f32_16x16x32_bf16(Bt[n][k], At[m][k], acc[ai][bj][m][n], 0, 0, 0); __builtin_amdgcn_s_setprio(0); } while (0)
; #define PG8_WAIT_V(n) asm volatile("s_waitcnt vmcnt(" #n ")" ::: "memory")
; #define PG8_WAIT_L(n) asm volatile("s_waitcnt lgkmcnt(" #n ")" ::: "memory")
; #define PG8_BAR __builtin_amdgcn_s_barrier()
; #define PG8_SCHED __builtin_amdgcn_sched_barrier(0)
; template <class Epi>
; __device__ __forceinline__ void gemm_phase(LAS unsigned char* lds, const Gemm g, const StaticOrder& S, const Epi& E) {
;     ...
;             PG8_LDA(At, 1, 1); PG8_STAGE(PG8_SB(1, 0), b3, voffB); PG8_STAGE(PG8_SB(1, 1), b3 + hstepB, voffB); PG8_STAGE(PG8_SA(1, 0), a3, voffA);
;             PG8_WAIT_V(8); PG8_WAIT_L(0); PG8_BAR; PG8_MMA(1, 0, At, B0); PG8_MMA(1, 1, At, B1); PG8_BAR; PG8_SCHED;
;         }
;         if (wr == 0) PG8_BAR;
	s_add_i32 s24, s50, s37
	v_lshl_add_u64 v[188:189], v[188:189], 0, s[18:19]
	s_mov_b32 m0, s24
	ds_read_b128 v[180:183], v194 offset:49152
	ds_read_b128 v[184:187], v194 offset:50176
	ds_read_b128 v[196:199], v194 offset:51200
	ds_read_b128 v[200:203], v194 offset:52224
	ds_read_b128 v[204:207], v194 offset:53248
	ds_read_b128 v[208:211], v194 offset:54272
	ds_read_b128 v[212:215], v194 offset:55296
	ds_read_b128 v[216:219], v194 offset:56320
	global_load_lds_dwordx4 v[188:189], off
	s_add_i32 m0, s24, 0x2000
	s_add_u32 s24, s28, 0xb0080
	v_lshl_add_u64 v[188:189], v[220:221], 0, s[18:19]
	s_addc_u32 s25, s29, 0
	s_add_i32 s28, s51, s37
	global_load_lds_dwordx4 v[188:189], off
	v_lshl_add_u64 v[188:189], s[24:25], 0, v[158:159]
	s_mov_b32 m0, s28
	s_nop 0
	global_load_lds_dwordx4 v[188:189], off
	v_lshl_add_u64 v[188:189], s[24:25], 0, v[162:163]
	s_add_i32 m0, s28, 0x2000
	s_nop 0
	global_load_lds_dwordx4 v[188:189], off
	v_lshl_add_u64 v[188:189], v[222:223], 0, s[18:19]
	s_mov_b32 m0, s49
	s_nop 0
	global_load_lds_dwordx4 v[188:189], off
	v_lshl_add_u64 v[188:189], v[224:225], 0, s[18:19]
	s_mov_b32 m0, s52
	s_nop 0
	global_load_lds_dwordx4 v[188:189], off
	s_waitcnt vmcnt(8)
	s_waitcnt lgkmcnt(0)
	s_barrier
	s_setprio 1
	s_waitcnt lgkmcnt(0)
	v_mfma_f32_16x16x32_bf16 v[60:63], v[128:131], v[180:183], v[60:63]
	v_mfma_f32_16x16x32_bf16 v[44:47], v[128:131], v[196:199], v[44:47]
	v_mfma_f32_16x16x32_bf16 v[28:31], v[128:131], v[204:207], v[28:31]
	v_mfma_f32_16x16x32_bf16 v[12:15], v[128:131], v[212:215], v[12:15]
	v_mfma_f32_16x16x32_bf16 v[8:11], v[136:139], v[212:215], v[8:11]
	v_mfma_f32_16x16x32_bf16 v[24:27], v[136:139], v[204:207], v[24:27]
	v_mfma_f32_16x16x32_bf16 v[40:43], v[136:139], v[196:199], v[40:43]
	v_mfma_f32_16x16x32_bf16 v[56:59], v[136:139], v[180:183], v[56:59]
	v_mfma_f32_16x16x32_bf16 v[60:63], v[132:135], v[184:187], v[60:63]
	v_mfma_f32_16x16x32_bf16 v[44:47], v[132:135], v[200:203], v[44:47]
	v_mfma_f32_16x16x32_bf16 v[28:31], v[132:135], v[208:211], v[28:31]
	v_mfma_f32_16x16x32_bf16 v[12:15], v[132:135], v[216:219], v[12:15]
	v_mfma_f32_16x16x32_bf16 v[8:11], v[140:143], v[216:219], v[8:11]
	v_mfma_f32_16x16x32_bf16 v[24:27], v[140:143], v[208:211], v[24:27]
	v_mfma_f32_16x16x32_bf16 v[40:43], v[140:143], v[200:203], v[40:43]
	v_mfma_f32_16x16x32_bf16 v[56:59], v[140:143], v[184:187], v[56:59]
	s_setprio 0
	s_setprio 1
	v_mfma_f32_16x16x32_bf16 v[52:55], v[144:147], v[180:183], v[52:55]
	v_mfma_f32_16x16x32_bf16 v[36:39], v[144:147], v[196:199], v[36:39]
	v_mfma_f32_16x16x32_bf16 v[20:23], v[144:147], v[204:207], v[20:23]
	v_mfma_f32_16x16x32_bf16 v[4:7], v[144:147], v[212:215], v[4:7]
	v_mfma_f32_16x16x32_bf16 v[0:3], v[172:175], v[212:215], v[0:3]
	v_mfma_f32_16x16x32_bf16 v[16:19], v[172:175], v[204:207], v[16:19]
	v_mfma_f32_16x16x32_bf16 v[32:35], v[172:175], v[196:199], v[32:35]
	v_mfma_f32_16x16x32_bf16 v[48:51], v[172:175], v[180:183], v[48:51]
	v_mfma_f32_16x16x32_bf16 v[52:55], v[148:151], v[184:187], v[52:55]
	v_mfma_f32_16x16x32_bf16 v[36:39], v[148:151], v[200:203], v[36:39]
	v_mfma_f32_16x16x32_bf16 v[20:23], v[148:151], v[208:211], v[20:23]
	v_mfma_f32_16x16x32_bf16 v[4:7], v[148:151], v[216:219], v[4:7]
	v_mfma_f32_16x16x32_bf16 v[0:3], v[176:179], v[216:219], v[0:3]
	v_mfma_f32_16x16x32_bf16 v[16:19], v[176:179], v[208:211], v[16:19]
	v_mfma_f32_16x16x32_bf16 v[32:35], v[176:179], v[200:203], v[32:35]
	v_mfma_f32_16x16x32_bf16 v[48:51], v[176:179], v[184:187], v[48:51]
	s_setprio 0
	s_barrier
	s_add_i32 s64, s64, 2
	s_add_u32 s62, s62, 0x100
	s_addc_u32 s63, s63, 0
	s_cmp_gt_u32 s64, 41
	s_mov_b64 s[24:25], s[26:27]
	s_cbranch_scc0 .LBB0_228
	s_and_b64 vcc, exec, s[20:21]
	s_cbranch_vccz .LBB0_231
	s_barrier

; #define PG8_STAGE(bufoff, gbase, voff) do { _Pragma("unroll") for (int _i = 0; _i < 2; ++_i) \
;         __builtin_amdgcn_global_load_lds((const unsigned*)((const char*)(gbase) + (voff)[_i]), (LAS unsigned*)(lds + (bufoff) + ldsw + _i * 8192), 16, 0, 0); } while (0)
; #define PG8_LDA(dst, b, h) do { _Pragma("unroll") for (int m = 0; m < 4; ++m) _Pragma("unroll") for (int k = 0; k < 2; ++k) dst[m][k] = *(const LAS bf16x8*)(lds + PG8_SA(b, h) + aoff + m * 2048 + k * 1024); } while (0)
; #define PG8_LDB(dst, b, h) do { _Pragma("unroll") for (int n = 0; n < 2; ++n) _Pragma("unroll") for (int k = 0; k < 2; ++k) dst[n][k] = *(const LAS bf16x8*)(lds + PG8_SB(b, h) + boff + n * 2048 + k * 1024); } while (0)
; #define PG8_MMA(ai, bj, At, Bt) do { __builtin_amdgcn_s_setprio(1); _Pragma("unroll") for (int m = 0; m < 4; ++m) _Pragma("unroll") for (int n = 0; n < 2; ++n) _Pragma("unroll") for (int k = 0; k < 2; ++k) \
;         acc[ai][bj][m][n] = __builtin_amdgcn_mfma_f32_16x16x32_bf16(Bt[n][k], At[m][k], acc[ai][bj][m][n], 0, 0, 0); __builtin_amdgcn_s_setprio(0); } while (0)
; #define PG8_WAIT_V(n) asm volatile("s_waitcnt vmcnt(" #n ")" ::: "memory")
; #define PG8_WAIT_L(n) asm volatile("s_waitcnt lgkmcnt(" #n ")" ::: "memory")
; #define PG8_BAR __builtin_amdgcn_s_barrier()
; #define PG8_SCHED __builtin_amdgcn_sched_barrier(0)
; template <class Epi>
; __device__ __forceinline__ void gemm_phase(LAS unsigned char* lds, const Gemm g, const StaticOrder& S, const Epi& E) {
;     ...
;             const bool last = (t == nt - 2);
;             const char* a1 = cA + (unsigned)(t + 1) * kstep;
;             const char* a2 = last ? nA : cA + (unsigned)(t + 2) * kstep; const char* b2 = last ? nB : cB + (unsigned)(t + 2) * kstep;
;             const char* a3 = a2 + kstep; const char* b3 = b2 + kstep;
;             PG8_LDB(B0, 0, 0); PG8_LDB(B1, 0, 1); PG8_SCHED; PG8_LDA(At, 0, 0); PG8_STAGE(PG8_SA(1, 1), a1 + hstepA, voffA);
;             PG8_WAIT_V(8); PG8_WAIT_L(0); PG8_BAR; PG8_MMA(0, 0, At, B0); PG8_MMA(0, 1, At, B1); PG8_BAR; PG8_SCHED;
;             PG8_LDA(At, 0, 1); PG8_STAGE(PG8_SB(0, 0), b2, voffB); PG8_STAGE(PG8_SB(0, 1), b2 + hstepB, voffB); PG8_STAGE(PG8_SA(0, 0), a2, voffA);
;             PG8_WAIT_V(8); PG8_WAIT_L(0); PG8_BAR; PG8_MMA(1, 0, At, B0); PG8_MMA(1, 1, At, B1); PG8_BAR; PG8_SCHED;
.LBB0_306:
	ds_read_b128 v[156:159], v188
	ds_read_b128 v[160:163], v188 offset:1024
	ds_read_b128 v[164:167], v188 offset:2048
	ds_read_b128 v[168:171], v188 offset:3072
	ds_read_b128 v[172:175], v189
	ds_read_b128 v[176:179], v189 offset:1024
	ds_read_b128 v[180:183], v189 offset:2048
	ds_read_b128 v[184:187], v189 offset:3072
	s_add_u32 s46, s44, 0xfffc0080
	s_addc_u32 s47, s45, -1
	s_cmp_eq_u32 s78, 12
	s_cselect_b32 s49, s7, s47
	s_cselect_b32 s48, s9, s46
	s_cselect_b32 s47, s15, s77
	s_cselect_b32 s46, s29, s31
	v_lshl_add_u64 v[150:151], s[44:45], 0, v[144:145]
	s_add_i32 m0, s56, 0xc000
	ds_read_b128 v[194:197], v190
	ds_read_b128 v[198:201], v190 offset:1024
	ds_read_b128 v[202:205], v190 offset:2048
	ds_read_b128 v[206:209], v190 offset:3072
	ds_read_b128 v[210:213], v190 offset:4096
	ds_read_b128 v[214:217], v190 offset:5120
	ds_read_b128 v[218:221], v190 offset:6144
	ds_read_b128 v[222:225], v190 offset:7168
	global_load_lds_dwordx4 v[150:151], off
	v_lshl_add_u64 v[150:151], s[44:45], 0, v[142:143]
	s_add_i32 m0, s56, 0xe000
	s_nop 0
	global_load_lds_dwordx4 v[150:151], off
	s_waitcnt vmcnt(8)
	s_waitcnt lgkmcnt(0)
	s_barrier
	s_setprio 1
	s_waitcnt lgkmcnt(0)
	v_mfma_f32_16x16x32_bf16 v[124:127], v[156:159], v[194:197], v[124:127]
	v_mfma_f32_16x16x32_bf16 v[108:111], v[156:159], v[202:205], v[108:111]
	v_mfma_f32_16x16x32_bf16 v[92:95], v[156:159], v[210:213], v[92:95]
	v_mfma_f32_16x16x32_bf16 v[76:79], v[156:159], v[218:221], v[76:79]
	v_mfma_f32_16x16x32_bf16 v[72:75], v[164:167], v[218:221], v[72:75]
	v_mfma_f32_16x16x32_bf16 v[88:91], v[164:167], v[210:213], v[88:91]
	v_mfma_f32_16x16x32_bf16 v[104:107], v[164:167], v[202:205], v[104:107]
	v_mfma_f32_16x16x32_bf16 v[120:123], v[164:167], v[194:197], v[120:123]
	v_mfma_f32_16x16x32_bf16 v[124:127], v[160:163], v[198:201], v[124:127]
	v_mfma_f32_16x16x32_bf16 v[108:111], v[160:163], v[206:209], v[108:111]
	v_mfma_f32_16x16x32_bf16 v[92:95], v[160:163], v[214:217], v[92:95]
	v_mfma_f32_16x16x32_bf16 v[76:79], v[160:163], v[222:225], v[76:79]
	v_mfma_f32_16x16x32_bf16 v[72:75], v[168:171], v[222:225], v[72:75]
	v_mfma_f32_16x16x32_bf16 v[88:91], v[168:171], v[214:217], v[88:91]
	v_mfma_f32_16x16x32_bf16 v[104:107], v[168:171], v[206:209], v[104:107]
	v_mfma_f32_16x16x32_bf16 v[120:123], v[168:171], v[198:201], v[120:123]
	s_setprio 0
	s_setprio 1
	v_mfma_f32_16x16x32_bf16 v[116:119], v[172:175], v[194:197], v[116:119]
	v_mfma_f32_16x16x32_bf16 v[100:103], v[172:175], v[202:205], v[100:103]
	v_mfma_f32_16x16x32_bf16 v[84:87], v[172:175], v[210:213], v[84:87]
	v_mfma_f32_16x16x32_bf16 v[68:71], v[172:175], v[218:221], v[68:71]
	v_mfma_f32_16x16x32_bf16 v[64:67], v[180:183], v[218:221], v[64:67]
	v_mfma_f32_16x16x32_bf16 v[80:83], v[180:183], v[210:213], v[80:83]
	v_mfma_f32_16x16x32_bf16 v[96:99], v[180:183], v[202:205], v[96:99]
	v_mfma_f32_16x16x32_bf16 v[112:115], v[180:183], v[194:197], v[112:115]
	v_mfma_f32_16x16x32_bf16 v[116:119], v[176:179], v[198:201], v[116:119]
	v_mfma_f32_16x16x32_bf16 v[100:103], v[176:179], v[206:209], v[100:103]
	v_mfma_f32_16x16x32_bf16 v[84:87], v[176:179], v[214:217], v[84:87]
	v_mfma_f32_16x16x32_bf16 v[68:71], v[176:179], v[222:225], v[68:71]
	v_mfma_f32_16x16x32_bf16 v[64:67], v[184:187], v[222:225], v[64:67]
	v_mfma_f32_16x16x32_bf16 v[80:83], v[184:187], v[214:217], v[80:83]
	v_mfma_f32_16x16x32_bf16 v[96:99], v[184:187], v[206:209], v[96:99]
	v_mfma_f32_16x16x32_bf16 v[112:115], v[184:187], v[198:201], v[112:115]
	s_setprio 0
	s_barrier
	s_add_i32 s50, s69, s55
	v_lshl_add_u64 v[150:151], s[46:47], 0, v[130:131]
	s_mov_b32 m0, s50
	ds_read_b128 v[194:197], v190 offset:16384
	ds_read_b128 v[198:201], v190 offset:17408
	ds_read_b128 v[202:205], v190 offset:18432
	ds_read_b128 v[206:209], v190 offset:19456
	ds_read_b128 v[210:213], v190 offset:20480
	ds_read_b128 v[214:217], v190 offset:21504
	ds_read_b128 v[218:221], v190 offset:22528
	ds_read_b128 v[222:225], v190 offset:23552
	global_load_lds_dwordx4 v[150:151], off
	s_add_i32 m0, s50, 0x2000
	s_add_u32 s50, s46, 0x40000
	v_lshl_add_u64 v[226:227], s[46:47], 0, v[134:135]
	s_addc_u32 s51, s47, 0
	s_add_i32 s79, s71, s55
	global_load_lds_dwordx4 v[226:227], off
	v_lshl_add_u64 v[228:229], s[50:51], 0, v[130:131]
	s_mov_b32 m0, s79
	v_lshl_add_u64 v[230:231], s[48:49], 0, v[132:133]
	global_load_lds_dwordx4 v[228:229], off
	v_lshl_add_u64 v[228:229], s[50:51], 0, v[134:135]
	s_add_i32 m0, s79, 0x2000
	s_nop 0
	global_load_lds_dwordx4 v[228:229], off
	v_lshl_add_u64 v[228:229], s[48:49], 0, v[128:129]
	s_mov_b32 m0, s56
	s_nop 0
	global_load_lds_dwordx4 v[228:229], off
	s_mov_b32 m0, s57
	s_nop 0
	global_load_lds_dwordx4 v[230:231], off
	s_waitcnt vmcnt(8)
	s_waitcnt lgkmcnt(0)
	s_barrier
; #define PG8_STAGE(bufoff, gbase, voff) do { _Pragma("unroll") for (int _i = 0; _i < 2; ++_i) \
;         __builtin_amdgcn_global_load_lds((const unsigned*)((const char*)(gbase) + (voff)[_i]), (LAS unsigned*)(lds + (bufoff) + ldsw + _i * 8192), 16, 0, 0); } while (0)
; #define PG8_LDA(dst, b, h) do { _Pragma("unroll") for (int m = 0; m < 4; ++m) _Pragma("unroll") for (int k = 0; k < 2; ++k) dst[m][k] = *(const LAS bf16x8*)(lds + PG8_SA(b, h) + aoff + m * 2048 + k * 1024); } while (0)
; #define PG8_LDB(dst, b, h) do { _Pragma("unroll") for (int n = 0; n < 2; ++n) _Pragma("unroll") for (int k = 0; k < 2; ++k) dst[n][k] = *(const LAS bf16x8*)(lds + PG8_SB(b, h) + boff + n * 2048 + k * 1024); } while (0)
; #define PG8_MMA(ai, bj, At, Bt) do { __builtin_amdgcn_s_setprio(1); _Pragma("unroll") for (int m = 0; m < 4; ++m) _Pragma("unroll") for (int n = 0; n < 2; ++n) _Pragma("unroll") for (int k = 0; k < 2; ++k) \
;         acc[ai][bj][m][n] = __builtin_amdgcn_mfma_f32_16x16x32_bf16(Bt[n][k], At[m][k], acc[ai][bj][m][n], 0, 0, 0); __builtin_amdgcn_s_setprio(0); } while (0)
; #define PG8_WAIT_V(n) asm volatile("s_waitcnt vmcnt(" #n ")" ::: "memory")
; #define PG8_WAIT_L(n) asm volatile("s_waitcnt lgkmcnt(" #n ")" ::: "memory")
; #define PG8_BAR __builtin_amdgcn_s_barrier()
; #define PG8_SCHED __builtin_amdgcn_sched_barrier(0)
; template <class Epi>
; __device__ __forceinline__ void gemm_phase(LAS unsigned char* lds, const Gemm g, const StaticOrder& S, const Epi& E) {
;     ...
;             PG8_WAIT_V(8); PG8_WAIT_L(0); PG8_BAR; PG8_MMA(1, 0, At, B0); PG8_MMA(1, 1, At, B1); PG8_BAR; PG8_SCHED;
;             PG8_LDB(B0, 1, 0); PG8_LDB(B1, 1, 1); PG8_SCHED; PG8_LDA(At, 1, 0); PG8_STAGE(PG8_SA(0, 1), a2 + hstepA, voffA);
;             PG8_WAIT_V(8); PG8_WAIT_L(0); PG8_BAR; PG8_MMA(0, 0, At, B0); PG8_MMA(0, 1, At, B1); PG8_BAR; PG8_SCHED;
	s_setprio 1
	s_waitcnt lgkmcnt(0)
	v_mfma_f32_16x16x32_bf16 v[60:63], v[156:159], v[194:197], v[60:63]
	v_mfma_f32_16x16x32_bf16 v[44:47], v[156:159], v[202:205], v[44:47]
	v_mfma_f32_16x16x32_bf16 v[28:31], v[156:159], v[210:213], v[28:31]
	v_mfma_f32_16x16x32_bf16 v[12:15], v[156:159], v[218:221], v[12:15]
	v_mfma_f32_16x16x32_bf16 v[8:11], v[164:167], v[218:221], v[8:11]
	v_mfma_f32_16x16x32_bf16 v[24:27], v[164:167], v[210:213], v[24:27]
	v_mfma_f32_16x16x32_bf16 v[40:43], v[164:167], v[202:205], v[40:43]
	v_mfma_f32_16x16x32_bf16 v[56:59], v[164:167], v[194:197], v[56:59]
	v_mfma_f32_16x16x32_bf16 v[60:63], v[160:163], v[198:201], v[60:63]
	v_mfma_f32_16x16x32_bf16 v[44:47], v[160:163], v[206:209], v[44:47]
	v_mfma_f32_16x16x32_bf16 v[28:31], v[160:163], v[214:217], v[28:31]
	v_mfma_f32_16x16x32_bf16 v[12:15], v[160:163], v[222:225], v[12:15]
	v_mfma_f32_16x16x32_bf16 v[8:11], v[168:171], v[222:225], v[8:11]
	v_mfma_f32_16x16x32_bf16 v[24:27], v[168:171], v[214:217], v[24:27]
	v_mfma_f32_16x16x32_bf16 v[40:43], v[168:171], v[206:209], v[40:43]
	v_mfma_f32_16x16x32_bf16 v[56:59], v[168:171], v[198:201], v[56:59]
	s_setprio 0
	s_setprio 1
	v_mfma_f32_16x16x32_bf16 v[52:55], v[172:175], v[194:197], v[52:55]
	v_mfma_f32_16x16x32_bf16 v[36:39], v[172:175], v[202:205], v[36:39]
	v_mfma_f32_16x16x32_bf16 v[20:23], v[172:175], v[210:213], v[20:23]
	v_mfma_f32_16x16x32_bf16 v[4:7], v[172:175], v[218:221], v[4:7]
	v_mfma_f32_16x16x32_bf16 v[0:3], v[180:183], v[218:221], v[0:3]
	v_mfma_f32_16x16x32_bf16 v[16:19], v[180:183], v[210:213], v[16:19]
	v_mfma_f32_16x16x32_bf16 v[32:35], v[180:183], v[202:205], v[32:35]
	v_mfma_f32_16x16x32_bf16 v[48:51], v[180:183], v[194:197], v[48:51]
	v_mfma_f32_16x16x32_bf16 v[52:55], v[176:179], v[198:201], v[52:55]
	v_mfma_f32_16x16x32_bf16 v[36:39], v[176:179], v[206:209], v[36:39]
	v_mfma_f32_16x16x32_bf16 v[20:23], v[176:179], v[214:217], v[20:23]
	v_mfma_f32_16x16x32_bf16 v[4:7], v[176:179], v[222:225], v[4:7]
	v_mfma_f32_16x16x32_bf16 v[0:3], v[184:187], v[222:225], v[0:3]
	v_mfma_f32_16x16x32_bf16 v[16:19], v[184:187], v[214:217], v[16:19]
	v_mfma_f32_16x16x32_bf16 v[32:35], v[184:187], v[206:209], v[32:35]
	v_mfma_f32_16x16x32_bf16 v[48:51], v[184:187], v[198:201], v[48:51]
	s_setprio 0
	s_barrier
	s_add_i32 s50, 0, 0x18000
	v_add_u32_e32 v136, s50, v153
	s_add_i32 s51, 0, 0x1c000
	ds_read_b128 v[156:159], v136
	ds_read_b128 v[160:163], v136 offset:1024
	ds_read_b128 v[164:167], v136 offset:2048
	ds_read_b128 v[168:171], v136 offset:3072
	v_add_u32_e32 v136, s51, v153
	ds_read_b128 v[172:175], v136
	ds_read_b128 v[176:179], v136 offset:1024
	ds_read_b128 v[180:183], v136 offset:2048
	ds_read_b128 v[184:187], v136 offset:3072
	s_add_u32 s48, s48, 0x40000
	s_addc_u32 s49, s49, 0
	s_mov_b32 m0, s58
	v_lshl_add_u64 v[232:233], s[48:49], 0, v[128:129]
	ds_read_b128 v[194:197], v190 offset:32768
	ds_read_b128 v[198:201], v190 offset:33792
	ds_read_b128 v[202:205], v190 offset:34816
	ds_read_b128 v[206:209], v190 offset:35840
	ds_read_b128 v[210:213], v190 offset:36864
	ds_read_b128 v[214:217], v190 offset:37888
	ds_read_b128 v[218:221], v190 offset:38912
	ds_read_b128 v[222:225], v190 offset:39936
	global_load_lds_dwordx4 v[232:233], off
	v_lshl_add_u64 v[232:233], s[48:49], 0, v[132:133]
	s_mov_b32 m0, s59
	s_nop 0
	global_load_lds_dwordx4 v[232:233], off
	s_waitcnt vmcnt(8)
	s_waitcnt lgkmcnt(0)
	s_barrier
	s_setprio 1
	s_waitcnt lgkmcnt(0)
	v_mfma_f32_16x16x32_bf16 v[124:127], v[156:159], v[194:197], v[124:127]
	v_mfma_f32_16x16x32_bf16 v[108:111], v[156:159], v[202:205], v[108:111]
	v_mfma_f32_16x16x32_bf16 v[92:95], v[156:159], v[210:213], v[92:95]
	v_mfma_f32_16x16x32_bf16 v[76:79], v[156:159], v[218:221], v[76:79]
	v_mfma_f32_16x16x32_bf16 v[72:75], v[164:167], v[218:221], v[72:75]
	v_mfma_f32_16x16x32_bf16 v[88:91], v[164:167], v[210:213], v[88:91]
	v_mfma_f32_16x16x32_bf16 v[104:107], v[164:167], v[202:205], v[104:107]
	v_mfma_f32_16x16x32_bf16 v[120:123], v[164:167], v[194:197], v[120:123]
	v_mfma_f32_16x16x32_bf16 v[124:127], v[160:163], v[198:201], v[124:127]
	v_mfma_f32_16x16x32_bf16 v[108:111], v[160:163], v[206:209], v[108:111]
	v_mfma_f32_16x16x32_bf16 v[92:95], v[160:163], v[214:217], v[92:95]
	v_mfma_f32_16x16x32_bf16 v[76:79], v[160:163], v[222:225], v[76:79]
	v_mfma_f32_16x16x32_bf16 v[72:75], v[168:171], v[222:225], v[72:75]
	v_mfma_f32_16x16x32_bf16 v[88:91], v[168:171], v[214:217], v[88:91]
	v_mfma_f32_16x16x32_bf16 v[104:107], v[168:171], v[206:209], v[104:107]
	v_mfma_f32_16x16x32_bf16 v[120:123], v[168:171], v[198:201], v[120:123]
	s_setprio 0
	s_setprio 1
	v_mfma_f32_16x16x32_bf16 v[116:119], v[172:175], v[194:197], v[116:119]
	v_mfma_f32_16x16x32_bf16 v[100:103], v[172:175], v[202:205], v[100:103]
	v_mfma_f32_16x16x32_bf16 v[84:87], v[172:175], v[210:213], v[84:87]
	v_mfma_f32_16x16x32_bf16 v[68:71], v[172:175], v[218:221], v[68:71]
	v_mfma_f32_16x16x32_bf16 v[64:67], v[180:183], v[218:221], v[64:67]
	v_mfma_f32_16x16x32_bf16 v[80:83], v[180:183], v[210:213], v[80:83]
	v_mfma_f32_16x16x32_bf16 v[96:99], v[180:183], v[202:205], v[96:99]
	v_mfma_f32_16x16x32_bf16 v[112:115], v[180:183], v[194:197], v[112:115]
	v_mfma_f32_16x16x32_bf16 v[116:119], v[176:179], v[198:201], v[116:119]
	v_mfma_f32_16x16x32_bf16 v[100:103], v[176:179], v[206:209], v[100:103]
	v_mfma_f32_16x16x32_bf16 v[84:87], v[176:179], v[214:217], v[84:87]
	v_mfma_f32_16x16x32_bf16 v[68:71], v[176:179], v[222:225], v[68:71]
	v_mfma_f32_16x16x32_bf16 v[64:67], v[184:187], v[222:225], v[64:67]
	v_mfma_f32_16x16x32_bf16 v[80:83], v[184:187], v[214:217], v[80:83]
	v_mfma_f32_16x16x32_bf16 v[96:99], v[184:187], v[206:209], v[96:99]
	v_mfma_f32_16x16x32_bf16 v[112:115], v[184:187], v[198:201], v[112:115]
	s_setprio 0
	s_barrier
; #define PG8_STAGE(bufoff, gbase, voff) do { _Pragma("unroll") for (int _i = 0; _i < 2; ++_i) \
;         __builtin_amdgcn_global_load_lds((const unsigned*)((const char*)(gbase) + (voff)[_i]), (LAS unsigned*)(lds + (bufoff) + ldsw + _i * 8192), 16, 0, 0); } while (0)
; #define PG8_LDA(dst, b, h) do { _Pragma("unroll") for (int m = 0; m < 4; ++m) _Pragma("unroll") for (int k = 0; k < 2; ++k) dst[m][k] = *(const LAS bf16x8*)(lds + PG8_SA(b, h) + aoff + m * 2048 + k * 1024); } while (0)
; #define PG8_MMA(ai, bj, At, Bt) do { __builtin_amdgcn_s_setprio(1); _Pragma("unroll") for (int m = 0; m < 4; ++m) _Pragma("unroll") for (int n = 0; n < 2; ++n) _Pragma("unroll") for (int k = 0; k < 2; ++k) \
;         acc[ai][bj][m][n] = __builtin_amdgcn_mfma_f32_16x16x32_bf16(Bt[n][k], At[m][k], acc[ai][bj][m][n], 0, 0, 0); __builtin_amdgcn_s_setprio(0); } while (0)
; #define PG8_WAIT_V(n) asm volatile("s_waitcnt vmcnt(" #n ")" ::: "memory")
; #define PG8_WAIT_L(n) asm volatile("s_waitcnt lgkmcnt(" #n ")" ::: "memory")
; #define PG8_BAR __builtin_amdgcn_s_barrier()
; #define PG8_SCHED __builtin_amdgcn_sched_barrier(0)
; template <class Epi>
; __device__ __forceinline__ void gemm_phase(LAS unsigned char* lds, const Gemm g, const StaticOrder& S, const Epi& E) {
;     ...
;             PG8_LDA(At, 1, 1); PG8_STAGE(PG8_SB(1, 0), b3, voffB); PG8_STAGE(PG8_SB(1, 1), b3 + hstepB, voffB); PG8_STAGE(PG8_SA(1, 0), a3, voffA);
;             PG8_WAIT_V(8); PG8_WAIT_L(0); PG8_BAR; PG8_MMA(1, 0, At, B0); PG8_MMA(1, 1, At, B1); PG8_BAR; PG8_SCHED;
;         }
;         if (wr == 0) PG8_BAR;
	s_add_i32 s48, s50, s55
	v_lshl_add_u64 v[150:151], v[150:151], 0, s[24:25]
	s_mov_b32 m0, s48
	ds_read_b128 v[194:197], v190 offset:49152
	ds_read_b128 v[198:201], v190 offset:50176
	ds_read_b128 v[202:205], v190 offset:51200
	ds_read_b128 v[206:209], v190 offset:52224
	ds_read_b128 v[210:213], v190 offset:53248
	ds_read_b128 v[214:217], v190 offset:54272
	ds_read_b128 v[218:221], v190 offset:55296
	ds_read_b128 v[222:225], v190 offset:56320
	global_load_lds_dwordx4 v[150:151], off
	s_add_i32 m0, s48, 0x2000
	s_add_u32 s46, s46, 0x40080
	v_lshl_add_u64 v[150:151], v[226:227], 0, s[24:25]
	s_addc_u32 s47, s47, 0
	s_add_i32 s48, s51, s55
	global_load_lds_dwordx4 v[150:151], off
	v_lshl_add_u64 v[150:151], s[46:47], 0, v[130:131]
	s_mov_b32 m0, s48
	s_nop 0
	global_load_lds_dwordx4 v[150:151], off
	v_lshl_add_u64 v[150:151], s[46:47], 0, v[134:135]
	s_add_i32 m0, s48, 0x2000
	s_nop 0
	global_load_lds_dwordx4 v[150:151], off
	v_lshl_add_u64 v[150:151], v[228:229], 0, s[24:25]
	s_mov_b32 m0, s62
	s_nop 0
	global_load_lds_dwordx4 v[150:151], off
	v_lshl_add_u64 v[150:151], v[230:231], 0, s[24:25]
	s_mov_b32 m0, s63
	s_nop 0
	global_load_lds_dwordx4 v[150:151], off
	s_waitcnt vmcnt(8)
	s_waitcnt lgkmcnt(0)
	s_barrier
	s_setprio 1
	s_waitcnt lgkmcnt(0)
	v_mfma_f32_16x16x32_bf16 v[60:63], v[156:159], v[194:197], v[60:63]
	v_mfma_f32_16x16x32_bf16 v[44:47], v[156:159], v[202:205], v[44:47]
	v_mfma_f32_16x16x32_bf16 v[28:31], v[156:159], v[210:213], v[28:31]
	v_mfma_f32_16x16x32_bf16 v[12:15], v[156:159], v[218:221], v[12:15]
	v_mfma_f32_16x16x32_bf16 v[8:11], v[164:167], v[218:221], v[8:11]
	v_mfma_f32_16x16x32_bf16 v[24:27], v[164:167], v[210:213], v[24:27]
	v_mfma_f32_16x16x32_bf16 v[40:43], v[164:167], v[202:205], v[40:43]
	v_mfma_f32_16x16x32_bf16 v[56:59], v[164:167], v[194:197], v[56:59]
	v_mfma_f32_16x16x32_bf16 v[60:63], v[160:163], v[198:201], v[60:63]
	v_mfma_f32_16x16x32_bf16 v[44:47], v[160:163], v[206:209], v[44:47]
	v_mfma_f32_16x16x32_bf16 v[28:31], v[160:163], v[214:217], v[28:31]
	v_mfma_f32_16x16x32_bf16 v[12:15], v[160:163], v[222:225], v[12:15]
	v_mfma_f32_16x16x32_bf16 v[8:11], v[168:171], v[222:225], v[8:11]
	v_mfma_f32_16x16x32_bf16 v[24:27], v[168:171], v[214:217], v[24:27]
	v_mfma_f32_16x16x32_bf16 v[40:43], v[168:171], v[206:209], v[40:43]
	v_mfma_f32_16x16x32_bf16 v[56:59], v[168:171], v[198:201], v[56:59]
	s_setprio 0
	s_setprio 1
	v_mfma_f32_16x16x32_bf16 v[52:55], v[172:175], v[194:197], v[52:55]
	v_mfma_f32_16x16x32_bf16 v[36:39], v[172:175], v[202:205], v[36:39]
	v_mfma_f32_16x16x32_bf16 v[20:23], v[172:175], v[210:213], v[20:23]
	v_mfma_f32_16x16x32_bf16 v[4:7], v[172:175], v[218:221], v[4:7]
	v_mfma_f32_16x16x32_bf16 v[0:3], v[180:183], v[218:221], v[0:3]
	v_mfma_f32_16x16x32_bf16 v[16:19], v[180:183], v[210:213], v[16:19]
	v_mfma_f32_16x16x32_bf16 v[32:35], v[180:183], v[202:205], v[32:35]
	v_mfma_f32_16x16x32_bf16 v[48:51], v[180:183], v[194:197], v[48:51]
	v_mfma_f32_16x16x32_bf16 v[52:55], v[176:179], v[198:201], v[52:55]
	v_mfma_f32_16x16x32_bf16 v[36:39], v[176:179], v[206:209], v[36:39]
	v_mfma_f32_16x16x32_bf16 v[20:23], v[176:179], v[214:217], v[20:23]
	v_mfma_f32_16x16x32_bf16 v[4:7], v[176:179], v[222:225], v[4:7]
	v_mfma_f32_16x16x32_bf16 v[0:3], v[184:187], v[222:225], v[0:3]
	v_mfma_f32_16x16x32_bf16 v[16:19], v[184:187], v[214:217], v[16:19]
	v_mfma_f32_16x16x32_bf16 v[32:35], v[184:187], v[206:209], v[32:35]
	v_mfma_f32_16x16x32_bf16 v[48:51], v[184:187], v[198:201], v[48:51]
	s_setprio 0
	s_barrier
	s_add_i32 s78, s78, 2
	s_add_u32 s31, s31, 0x100
	s_addc_u32 s77, s77, 0
	s_add_u32 s44, s44, 0x100
	s_addc_u32 s45, s45, 0
	s_cmp_gt_u32 s78, 13
	s_cbranch_scc0 .LBB0_306
	s_and_b64 vcc, exec, s[26:27]
	s_cbranch_vccz .LBB0_309
	s_barrier

; #define PG8_STAGE(bufoff, gbase, voff) do { _Pragma("unroll") for (int _i = 0; _i < 2; ++_i) \
;         __builtin_amdgcn_global_load_lds((const unsigned*)((const char*)(gbase) + (voff)[_i]), (LAS unsigned*)(lds + (bufoff) + ldsw + _i * 8192), 16, 0, 0); } while (0)
; #define PG8_LDA(dst, b, h) do { _Pragma("unroll") for (int m = 0; m < 4; ++m) _Pragma("unroll") for (int k = 0; k < 2; ++k) dst[m][k] = *(const LAS bf16x8*)(lds + PG8_SA(b, h) + aoff + m * 2048 + k * 1024); } while (0)
; #define PG8_LDB(dst, b, h) do { _Pragma("unroll") for (int n = 0; n < 2; ++n) _Pragma("unroll") for (int k = 0; k < 2; ++k) dst[n][k] = *(const LAS bf16x8*)(lds + PG8_SB(b, h) + boff + n * 2048 + k * 1024); } while (0)
; #define PG8_MMA(ai, bj, At, Bt) do { __builtin_amdgcn_s_setprio(1); _Pragma("unroll") for (int m = 0; m < 4; ++m) _Pragma("unroll") for (int n = 0; n < 2; ++n) _Pragma("unroll") for (int k = 0; k < 2; ++k) \
;         acc[ai][bj][m][n] = __builtin_amdgcn_mfma_f32_16x16x32_bf16(Bt[n][k], At[m][k], acc[ai][bj][m][n], 0, 0, 0); __builtin_amdgcn_s_setprio(0); } while (0)
; #define PG8_WAIT_V(n) asm volatile("s_waitcnt vmcnt(" #n ")" ::: "memory")
; #define PG8_WAIT_L(n) asm volatile("s_waitcnt lgkmcnt(" #n ")" ::: "memory")
; #define PG8_BAR __builtin_amdgcn_s_barrier()
; #define PG8_SCHED __builtin_amdgcn_sched_barrier(0)
; template <class Epi>
; __device__ __forceinline__ void gemm_phase(LAS unsigned char* lds, const Gemm g, const StaticOrder& S, const Epi& E) {
;     ...
;             const bool last = (t == nt - 2);
;             const char* a1 = cA + (unsigned)(t + 1) * kstep;
;             const char* a2 = last ? nA : cA + (unsigned)(t + 2) * kstep; const char* b2 = last ? nB : cB + (unsigned)(t + 2) * kstep;
;             const char* a3 = a2 + kstep; const char* b3 = b2 + kstep;
;             PG8_LDB(B0, 0, 0); PG8_LDB(B1, 0, 1); PG8_SCHED; PG8_LDA(At, 0, 0); PG8_STAGE(PG8_SA(1, 1), a1 + hstepA, voffA);
;             PG8_WAIT_V(8); PG8_WAIT_L(0); PG8_BAR; PG8_MMA(0, 0, At, B0); PG8_MMA(0, 1, At, B1); PG8_BAR; PG8_SCHED;
;             PG8_LDA(At, 0, 1); PG8_STAGE(PG8_SB(0, 0), b2, voffB); PG8_STAGE(PG8_SB(0, 1), b2 + hstepB, voffB); PG8_STAGE(PG8_SA(0, 0), a2, voffA);
;             PG8_WAIT_V(8); PG8_WAIT_L(0); PG8_BAR; PG8_MMA(1, 0, At, B0); PG8_MMA(1, 1, At, B1); PG8_BAR; PG8_SCHED;
.LBB0_627:
	ds_read_b128 v[128:131], v192
	ds_read_b128 v[132:135], v192 offset:1024
	ds_read_b128 v[136:139], v192 offset:2048
	ds_read_b128 v[140:143], v192 offset:3072
	ds_read_b128 v[144:147], v193
	ds_read_b128 v[148:151], v193 offset:1024
	ds_read_b128 v[172:175], v193 offset:2048
	ds_read_b128 v[176:179], v193 offset:3072
	s_add_u32 s8, s30, 0x100
	s_addc_u32 s9, s31, 0
	s_cmp_eq_u32 s77, 12
	s_cselect_b32 s37, s27, s9
	s_cselect_b32 s36, s26, s8
	s_cselect_b32 s35, s25, s76
	s_cselect_b32 s34, s69, s71
	v_lshl_add_u64 v[188:189], s[30:31], 0, v[166:167]
	s_add_i32 m0, s53, 0xc000
	ds_read_b128 v[180:183], v194
	ds_read_b128 v[184:187], v194 offset:1024
	ds_read_b128 v[196:199], v194 offset:2048
	ds_read_b128 v[200:203], v194 offset:3072
	ds_read_b128 v[204:207], v194 offset:4096
	ds_read_b128 v[208:211], v194 offset:5120
	ds_read_b128 v[212:215], v194 offset:6144
	ds_read_b128 v[216:219], v194 offset:7168
	global_load_lds_dwordx4 v[188:189], off
	v_lshl_add_u64 v[188:189], s[30:31], 0, v[164:165]
	s_add_i32 m0, s53, 0xe000
	s_nop 0
	global_load_lds_dwordx4 v[188:189], off
	s_waitcnt vmcnt(8)
	s_waitcnt lgkmcnt(0)
	s_barrier
	s_setprio 1
	s_waitcnt lgkmcnt(0)
	v_mfma_f32_16x16x32_bf16 v[124:127], v[128:131], v[180:183], v[124:127]
	v_mfma_f32_16x16x32_bf16 v[108:111], v[128:131], v[196:199], v[108:111]
	v_mfma_f32_16x16x32_bf16 v[92:95], v[128:131], v[204:207], v[92:95]
	v_mfma_f32_16x16x32_bf16 v[76:79], v[128:131], v[212:215], v[76:79]
	v_mfma_f32_16x16x32_bf16 v[72:75], v[136:139], v[212:215], v[72:75]
	v_mfma_f32_16x16x32_bf16 v[88:91], v[136:139], v[204:207], v[88:91]
	v_mfma_f32_16x16x32_bf16 v[104:107], v[136:139], v[196:199], v[104:107]
	v_mfma_f32_16x16x32_bf16 v[120:123], v[136:139], v[180:183], v[120:123]
	v_mfma_f32_16x16x32_bf16 v[124:127], v[132:135], v[184:187], v[124:127]
	v_mfma_f32_16x16x32_bf16 v[108:111], v[132:135], v[200:203], v[108:111]
	v_mfma_f32_16x16x32_bf16 v[92:95], v[132:135], v[208:211], v[92:95]
	v_mfma_f32_16x16x32_bf16 v[76:79], v[132:135], v[216:219], v[76:79]
	v_mfma_f32_16x16x32_bf16 v[72:75], v[140:143], v[216:219], v[72:75]
	v_mfma_f32_16x16x32_bf16 v[88:91], v[140:143], v[208:211], v[88:91]
	v_mfma_f32_16x16x32_bf16 v[104:107], v[140:143], v[200:203], v[104:107]
	v_mfma_f32_16x16x32_bf16 v[120:123], v[140:143], v[184:187], v[120:123]
	s_setprio 0
	s_setprio 1
	v_mfma_f32_16x16x32_bf16 v[116:119], v[144:147], v[180:183], v[116:119]
	v_mfma_f32_16x16x32_bf16 v[100:103], v[144:147], v[196:199], v[100:103]
	v_mfma_f32_16x16x32_bf16 v[84:87], v[144:147], v[204:207], v[84:87]
	v_mfma_f32_16x16x32_bf16 v[68:71], v[144:147], v[212:215], v[68:71]
	v_mfma_f32_16x16x32_bf16 v[64:67], v[172:175], v[212:215], v[64:67]
	v_mfma_f32_16x16x32_bf16 v[80:83], v[172:175], v[204:207], v[80:83]
	v_mfma_f32_16x16x32_bf16 v[96:99], v[172:175], v[196:199], v[96:99]
	v_mfma_f32_16x16x32_bf16 v[112:115], v[172:175], v[180:183], v[112:115]
	v_mfma_f32_16x16x32_bf16 v[116:119], v[148:151], v[184:187], v[116:119]
	v_mfma_f32_16x16x32_bf16 v[100:103], v[148:151], v[200:203], v[100:103]
	v_mfma_f32_16x16x32_bf16 v[84:87], v[148:151], v[208:211], v[84:87]
	v_mfma_f32_16x16x32_bf16 v[68:71], v[148:151], v[216:219], v[68:71]
	v_mfma_f32_16x16x32_bf16 v[64:67], v[176:179], v[216:219], v[64:67]
	v_mfma_f32_16x16x32_bf16 v[80:83], v[176:179], v[208:211], v[80:83]
	v_mfma_f32_16x16x32_bf16 v[96:99], v[176:179], v[200:203], v[96:99]
	v_mfma_f32_16x16x32_bf16 v[112:115], v[176:179], v[184:187], v[112:115]
	s_setprio 0
	s_barrier
	s_add_i32 s30, s64, s52
	v_lshl_add_u64 v[188:189], s[34:35], 0, v[158:159]
	s_mov_b32 m0, s30
	ds_read_b128 v[180:183], v194 offset:16384
	ds_read_b128 v[184:187], v194 offset:17408
	ds_read_b128 v[196:199], v194 offset:18432
	ds_read_b128 v[200:203], v194 offset:19456
	ds_read_b128 v[204:207], v194 offset:20480
	ds_read_b128 v[208:211], v194 offset:21504
	ds_read_b128 v[212:215], v194 offset:22528
	ds_read_b128 v[216:219], v194 offset:23552
	global_load_lds_dwordx4 v[188:189], off
	s_add_i32 m0, s30, 0x2000
	s_add_u32 s30, s34, 0x40000
	v_lshl_add_u64 v[220:221], s[34:35], 0, v[162:163]
	s_addc_u32 s31, s35, 0
	s_add_i32 s50, s65, s52
	global_load_lds_dwordx4 v[220:221], off
	v_lshl_add_u64 v[222:223], s[30:31], 0, v[158:159]
	s_mov_b32 m0, s50
	v_lshl_add_u64 v[224:225], s[36:37], 0, v[160:161]
	global_load_lds_dwordx4 v[222:223], off
	v_lshl_add_u64 v[222:223], s[30:31], 0, v[162:163]
	s_add_i32 m0, s50, 0x2000
	s_nop 0
	global_load_lds_dwordx4 v[222:223], off
	v_lshl_add_u64 v[222:223], s[36:37], 0, v[156:157]
	s_mov_b32 m0, s53
	s_nop 0
	global_load_lds_dwordx4 v[222:223], off
	s_mov_b32 m0, s54
	s_nop 0
	global_load_lds_dwordx4 v[224:225], off
	s_waitcnt vmcnt(8)
	s_waitcnt lgkmcnt(0)
	s_barrier
; #define PG8_STAGE(bufoff, gbase, voff) do { _Pragma("unroll") for (int _i = 0; _i < 2; ++_i) \
;         __builtin_amdgcn_global_load_lds((const unsigned*)((const char*)(gbase) + (voff)[_i]), (LAS unsigned*)(lds + (bufoff) + ldsw + _i * 8192), 16, 0, 0); } while (0)
; #define PG8_LDA(dst, b, h) do { _Pragma("unroll") for (int m = 0; m < 4; ++m) _Pragma("unroll") for (int k = 0; k < 2; ++k) dst[m][k] = *(const LAS bf16x8*)(lds + PG8_SA(b, h) + aoff + m * 2048 + k * 1024); } while (0)
; #define PG8_LDB(dst, b, h) do { _Pragma("unroll") for (int n = 0; n < 2; ++n) _Pragma("unroll") for (int k = 0; k < 2; ++k) dst[n][k] = *(const LAS bf16x8*)(lds + PG8_SB(b, h) + boff + n * 2048 + k * 1024); } while (0)
; #define PG8_MMA(ai, bj, At, Bt) do { __builtin_amdgcn_s_setprio(1); _Pragma("unroll") for (int m = 0; m < 4; ++m) _Pragma("unroll") for (int n = 0; n < 2; ++n) _Pragma("unroll") for (int k = 0; k < 2; ++k) \
;         acc[ai][bj][m][n] = __builtin_amdgcn_mfma_f32_16x16x32_bf16(Bt[n][k], At[m][k], acc[ai][bj][m][n], 0, 0, 0); __builtin_amdgcn_s_setprio(0); } while (0)
; #define PG8_WAIT_V(n) asm volatile("s_waitcnt vmcnt(" #n ")" ::: "memory")
; #define PG8_WAIT_L(n) asm volatile("s_waitcnt lgkmcnt(" #n ")" ::: "memory")
; #define PG8_BAR __builtin_amdgcn_s_barrier()
; #define PG8_SCHED __builtin_amdgcn_sched_barrier(0)
; template <class Epi>
; __device__ __forceinline__ void gemm_phase(LAS unsigned char* lds, const Gemm g, const StaticOrder& S, const Epi& E) {
;     ...
;             PG8_WAIT_V(8); PG8_WAIT_L(0); PG8_BAR; PG8_MMA(1, 0, At, B0); PG8_MMA(1, 1, At, B1); PG8_BAR; PG8_SCHED;
;             PG8_LDB(B0, 1, 0); PG8_LDB(B1, 1, 1); PG8_SCHED; PG8_LDA(At, 1, 0); PG8_STAGE(PG8_SA(0, 1), a2 + hstepA, voffA);
;             PG8_WAIT_V(8); PG8_WAIT_L(0); PG8_BAR; PG8_MMA(0, 0, At, B0); PG8_MMA(0, 1, At, B1); PG8_BAR; PG8_SCHED;
	s_setprio 1
	s_waitcnt lgkmcnt(0)
	v_mfma_f32_16x16x32_bf16 v[60:63], v[128:131], v[180:183], v[60:63]
	v_mfma_f32_16x16x32_bf16 v[44:47], v[128:131], v[196:199], v[44:47]
	v_mfma_f32_16x16x32_bf16 v[28:31], v[128:131], v[204:207], v[28:31]
	v_mfma_f32_16x16x32_bf16 v[12:15], v[128:131], v[212:215], v[12:15]
	v_mfma_f32_16x16x32_bf16 v[8:11], v[136:139], v[212:215], v[8:11]
	v_mfma_f32_16x16x32_bf16 v[24:27], v[136:139], v[204:207], v[24:27]
	v_mfma_f32_16x16x32_bf16 v[40:43], v[136:139], v[196:199], v[40:43]
	v_mfma_f32_16x16x32_bf16 v[56:59], v[136:139], v[180:183], v[56:59]
	v_mfma_f32_16x16x32_bf16 v[60:63], v[132:135], v[184:187], v[60:63]
	v_mfma_f32_16x16x32_bf16 v[44:47], v[132:135], v[200:203], v[44:47]
	v_mfma_f32_16x16x32_bf16 v[28:31], v[132:135], v[208:211], v[28:31]
	v_mfma_f32_16x16x32_bf16 v[12:15], v[132:135], v[216:219], v[12:15]
	v_mfma_f32_16x16x32_bf16 v[8:11], v[140:143], v[216:219], v[8:11]
	v_mfma_f32_16x16x32_bf16 v[24:27], v[140:143], v[208:211], v[24:27]
	v_mfma_f32_16x16x32_bf16 v[40:43], v[140:143], v[200:203], v[40:43]
	v_mfma_f32_16x16x32_bf16 v[56:59], v[140:143], v[184:187], v[56:59]
	s_setprio 0
	s_setprio 1
	v_mfma_f32_16x16x32_bf16 v[52:55], v[144:147], v[180:183], v[52:55]
	v_mfma_f32_16x16x32_bf16 v[36:39], v[144:147], v[196:199], v[36:39]
	v_mfma_f32_16x16x32_bf16 v[20:23], v[144:147], v[204:207], v[20:23]
	v_mfma_f32_16x16x32_bf16 v[4:7], v[144:147], v[212:215], v[4:7]
	v_mfma_f32_16x16x32_bf16 v[0:3], v[172:175], v[212:215], v[0:3]
	v_mfma_f32_16x16x32_bf16 v[16:19], v[172:175], v[204:207], v[16:19]
	v_mfma_f32_16x16x32_bf16 v[32:35], v[172:175], v[196:199], v[32:35]
	v_mfma_f32_16x16x32_bf16 v[48:51], v[172:175], v[180:183], v[48:51]
	v_mfma_f32_16x16x32_bf16 v[52:55], v[148:151], v[184:187], v[52:55]
	v_mfma_f32_16x16x32_bf16 v[36:39], v[148:151], v[200:203], v[36:39]
	v_mfma_f32_16x16x32_bf16 v[20:23], v[148:151], v[208:211], v[20:23]
	v_mfma_f32_16x16x32_bf16 v[4:7], v[148:151], v[216:219], v[4:7]
	v_mfma_f32_16x16x32_bf16 v[0:3], v[176:179], v[216:219], v[0:3]
	v_mfma_f32_16x16x32_bf16 v[16:19], v[176:179], v[208:211], v[16:19]
	v_mfma_f32_16x16x32_bf16 v[32:35], v[176:179], v[200:203], v[32:35]
	v_mfma_f32_16x16x32_bf16 v[48:51], v[176:179], v[184:187], v[48:51]
	s_setprio 0
	s_barrier
	s_add_i32 s50, 0, 0x18000
	s_add_i32 s51, 0, 0x1c000
	v_add_u32_e32 v140, s50, v190
	v_add_u32_e32 v176, s51, v190
	ds_read_b128 v[128:131], v140
	ds_read_b128 v[132:135], v140 offset:1024
	ds_read_b128 v[136:139], v140 offset:2048
	ds_read_b128 v[140:143], v140 offset:3072
	ds_read_b128 v[144:147], v176
	ds_read_b128 v[148:151], v176 offset:1024
	ds_read_b128 v[172:175], v176 offset:2048
	ds_read_b128 v[176:179], v176 offset:3072
	s_add_u32 s30, s36, 0xc0000
	s_addc_u32 s31, s37, 0
	s_mov_b32 m0, s55
	v_lshl_add_u64 v[226:227], s[30:31], 0, v[156:157]
	ds_read_b128 v[180:183], v194 offset:32768
	ds_read_b128 v[184:187], v194 offset:33792
	ds_read_b128 v[196:199], v194 offset:34816
	ds_read_b128 v[200:203], v194 offset:35840
	ds_read_b128 v[204:207], v194 offset:36864
	ds_read_b128 v[208:211], v194 offset:37888
	ds_read_b128 v[212:215], v194 offset:38912
	ds_read_b128 v[216:219], v194 offset:39936
	global_load_lds_dwordx4 v[226:227], off
	v_lshl_add_u64 v[226:227], s[30:31], 0, v[160:161]
	s_mov_b32 m0, s56
	s_nop 0
	global_load_lds_dwordx4 v[226:227], off
	s_waitcnt vmcnt(8)
	s_waitcnt lgkmcnt(0)
	s_barrier
	s_setprio 1
	s_waitcnt lgkmcnt(0)
	v_mfma_f32_16x16x32_bf16 v[124:127], v[128:131], v[180:183], v[124:127]
	v_mfma_f32_16x16x32_bf16 v[108:111], v[128:131], v[196:199], v[108:111]
	v_mfma_f32_16x16x32_bf16 v[92:95], v[128:131], v[204:207], v[92:95]
	v_mfma_f32_16x16x32_bf16 v[76:79], v[128:131], v[212:215], v[76:79]
	v_mfma_f32_16x16x32_bf16 v[72:75], v[136:139], v[212:215], v[72:75]
	v_mfma_f32_16x16x32_bf16 v[88:91], v[136:139], v[204:207], v[88:91]
	v_mfma_f32_16x16x32_bf16 v[104:107], v[136:139], v[196:199], v[104:107]
	v_mfma_f32_16x16x32_bf16 v[120:123], v[136:139], v[180:183], v[120:123]
	v_mfma_f32_16x16x32_bf16 v[124:127], v[132:135], v[184:187], v[124:127]
	v_mfma_f32_16x16x32_bf16 v[108:111], v[132:135], v[200:203], v[108:111]
	v_mfma_f32_16x16x32_bf16 v[92:95], v[132:135], v[208:211], v[92:95]
	v_mfma_f32_16x16x32_bf16 v[76:79], v[132:135], v[216:219], v[76:79]
	v_mfma_f32_16x16x32_bf16 v[72:75], v[140:143], v[216:219], v[72:75]
	v_mfma_f32_16x16x32_bf16 v[88:91], v[140:143], v[208:211], v[88:91]
	v_mfma_f32_16x16x32_bf16 v[104:107], v[140:143], v[200:203], v[104:107]
	v_mfma_f32_16x16x32_bf16 v[120:123], v[140:143], v[184:187], v[120:123]
	s_setprio 0
	s_setprio 1
	v_mfma_f32_16x16x32_bf16 v[116:119], v[144:147], v[180:183], v[116:119]
	v_mfma_f32_16x16x32_bf16 v[100:103], v[144:147], v[196:199], v[100:103]
	v_mfma_f32_16x16x32_bf16 v[84:87], v[144:147], v[204:207], v[84:87]
	v_mfma_f32_16x16x32_bf16 v[68:71], v[144:147], v[212:215], v[68:71]
	v_mfma_f32_16x16x32_bf16 v[64:67], v[172:175], v[212:215], v[64:67]
	v_mfma_f32_16x16x32_bf16 v[80:83], v[172:175], v[204:207], v[80:83]
	v_mfma_f32_16x16x32_bf16 v[96:99], v[172:175], v[196:199], v[96:99]
	v_mfma_f32_16x16x32_bf16 v[112:115], v[172:175], v[180:183], v[112:115]
	v_mfma_f32_16x16x32_bf16 v[116:119], v[148:151], v[184:187], v[116:119]
	v_mfma_f32_16x16x32_bf16 v[100:103], v[148:151], v[200:203], v[100:103]
	v_mfma_f32_16x16x32_bf16 v[84:87], v[148:151], v[208:211], v[84:87]
	v_mfma_f32_16x16x32_bf16 v[68:71], v[148:151], v[216:219], v[68:71]
	v_mfma_f32_16x16x32_bf16 v[64:67], v[176:179], v[216:219], v[64:67]
	v_mfma_f32_16x16x32_bf16 v[80:83], v[176:179], v[208:211], v[80:83]
	v_mfma_f32_16x16x32_bf16 v[96:99], v[176:179], v[200:203], v[96:99]
	v_mfma_f32_16x16x32_bf16 v[112:115], v[176:179], v[184:187], v[112:115]
	s_setprio 0
	s_barrier
; #define PG8_STAGE(bufoff, gbase, voff) do { _Pragma("unroll") for (int _i = 0; _i < 2; ++_i) \
;         __builtin_amdgcn_global_load_lds((const unsigned*)((const char*)(gbase) + (voff)[_i]), (LAS unsigned*)(lds + (bufoff) + ldsw + _i * 8192), 16, 0, 0); } while (0)
; #define PG8_LDA(dst, b, h) do { _Pragma("unroll") for (int m = 0; m < 4; ++m) _Pragma("unroll") for (int k = 0; k < 2; ++k) dst[m][k] = *(const LAS bf16x8*)(lds + PG8_SA(b, h) + aoff + m * 2048 + k * 1024); } while (0)
; #define PG8_MMA(ai, bj, At, Bt) do { __builtin_amdgcn_s_setprio(1); _Pragma("unroll") for (int m = 0; m < 4; ++m) _Pragma("unroll") for (int n = 0; n < 2; ++n) _Pragma("unroll") for (int k = 0; k < 2; ++k) \
;         acc[ai][bj][m][n] = __builtin_amdgcn_mfma_f32_16x16x32_bf16(Bt[n][k], At[m][k], acc[ai][bj][m][n], 0, 0, 0); __builtin_amdgcn_s_setprio(0); } while (0)
; #define PG8_WAIT_V(n) asm volatile("s_waitcnt vmcnt(" #n ")" ::: "memory")
; #define PG8_WAIT_L(n) asm volatile("s_waitcnt lgkmcnt(" #n ")" ::: "memory")
; #define PG8_BAR __builtin_amdgcn_s_barrier()
; #define PG8_SCHED __builtin_amdgcn_sched_barrier(0)
; template <class Epi>
; __device__ __forceinline__ void gemm_phase(LAS unsigned char* lds, const Gemm g, const StaticOrder& S, const Epi& E) {
;     ...
;             PG8_LDA(At, 1, 1); PG8_STAGE(PG8_SB(1, 0), b3, voffB); PG8_STAGE(PG8_SB(1, 1), b3 + hstepB, voffB); PG8_STAGE(PG8_SA(1, 0), a3, voffA);
;             PG8_WAIT_V(8); PG8_WAIT_L(0); PG8_BAR; PG8_MMA(1, 0, At, B0); PG8_MMA(1, 1, At, B1); PG8_BAR; PG8_SCHED;
;         }
;         if (wr == 0) PG8_BAR;
	s_add_i32 s30, s50, s52
	v_lshl_add_u64 v[188:189], v[188:189], 0, s[20:21]
	s_mov_b32 m0, s30
	ds_read_b128 v[180:183], v194 offset:49152
	ds_read_b128 v[184:187], v194 offset:50176
	ds_read_b128 v[196:199], v194 offset:51200
	ds_read_b128 v[200:203], v194 offset:52224
	ds_read_b128 v[204:207], v194 offset:53248
	ds_read_b128 v[208:211], v194 offset:54272
	ds_read_b128 v[212:215], v194 offset:55296
	ds_read_b128 v[216:219], v194 offset:56320
	global_load_lds_dwordx4 v[188:189], off
	s_add_i32 m0, s30, 0x2000
	s_add_u32 s30, s34, 0x40080
	v_lshl_add_u64 v[188:189], v[220:221], 0, s[20:21]
	s_addc_u32 s31, s35, 0
	s_add_i32 s34, s51, s52
	global_load_lds_dwordx4 v[188:189], off
	v_lshl_add_u64 v[188:189], s[30:31], 0, v[158:159]
	s_mov_b32 m0, s34
	s_nop 0
	global_load_lds_dwordx4 v[188:189], off
	v_lshl_add_u64 v[188:189], s[30:31], 0, v[162:163]
	s_add_i32 m0, s34, 0x2000
	s_nop 0
	global_load_lds_dwordx4 v[188:189], off
	v_lshl_add_u64 v[188:189], v[222:223], 0, s[20:21]
	s_mov_b32 m0, s58
	s_nop 0
	global_load_lds_dwordx4 v[188:189], off
	v_lshl_add_u64 v[188:189], v[224:225], 0, s[20:21]
	s_mov_b32 m0, s59
	s_nop 0
	global_load_lds_dwordx4 v[188:189], off
	s_waitcnt vmcnt(8)
	s_waitcnt lgkmcnt(0)
	s_barrier
	s_setprio 1
	s_waitcnt lgkmcnt(0)
	v_mfma_f32_16x16x32_bf16 v[60:63], v[128:131], v[180:183], v[60:63]
	v_mfma_f32_16x16x32_bf16 v[44:47], v[128:131], v[196:199], v[44:47]
	v_mfma_f32_16x16x32_bf16 v[28:31], v[128:131], v[204:207], v[28:31]
	v_mfma_f32_16x16x32_bf16 v[12:15], v[128:131], v[212:215], v[12:15]
	v_mfma_f32_16x16x32_bf16 v[8:11], v[136:139], v[212:215], v[8:11]
	v_mfma_f32_16x16x32_bf16 v[24:27], v[136:139], v[204:207], v[24:27]
	v_mfma_f32_16x16x32_bf16 v[40:43], v[136:139], v[196:199], v[40:43]
	v_mfma_f32_16x16x32_bf16 v[56:59], v[136:139], v[180:183], v[56:59]
	v_mfma_f32_16x16x32_bf16 v[60:63], v[132:135], v[184:187], v[60:63]
	v_mfma_f32_16x16x32_bf16 v[44:47], v[132:135], v[200:203], v[44:47]
	v_mfma_f32_16x16x32_bf16 v[28:31], v[132:135], v[208:211], v[28:31]
	v_mfma_f32_16x16x32_bf16 v[12:15], v[132:135], v[216:219], v[12:15]
	v_mfma_f32_16x16x32_bf16 v[8:11], v[140:143], v[216:219], v[8:11]
	v_mfma_f32_16x16x32_bf16 v[24:27], v[140:143], v[208:211], v[24:27]
	v_mfma_f32_16x16x32_bf16 v[40:43], v[140:143], v[200:203], v[40:43]
	v_mfma_f32_16x16x32_bf16 v[56:59], v[140:143], v[184:187], v[56:59]
	s_setprio 0
	s_setprio 1
	v_mfma_f32_16x16x32_bf16 v[52:55], v[144:147], v[180:183], v[52:55]
	v_mfma_f32_16x16x32_bf16 v[36:39], v[144:147], v[196:199], v[36:39]
	v_mfma_f32_16x16x32_bf16 v[20:23], v[144:147], v[204:207], v[20:23]
	v_mfma_f32_16x16x32_bf16 v[4:7], v[144:147], v[212:215], v[4:7]
	v_mfma_f32_16x16x32_bf16 v[0:3], v[172:175], v[212:215], v[0:3]
	v_mfma_f32_16x16x32_bf16 v[16:19], v[172:175], v[204:207], v[16:19]
	v_mfma_f32_16x16x32_bf16 v[32:35], v[172:175], v[196:199], v[32:35]
	v_mfma_f32_16x16x32_bf16 v[48:51], v[172:175], v[180:183], v[48:51]
	v_mfma_f32_16x16x32_bf16 v[52:55], v[148:151], v[184:187], v[52:55]
	v_mfma_f32_16x16x32_bf16 v[36:39], v[148:151], v[200:203], v[36:39]
	v_mfma_f32_16x16x32_bf16 v[20:23], v[148:151], v[208:211], v[20:23]
	v_mfma_f32_16x16x32_bf16 v[4:7], v[148:151], v[216:219], v[4:7]
	v_mfma_f32_16x16x32_bf16 v[0:3], v[176:179], v[216:219], v[0:3]
	v_mfma_f32_16x16x32_bf16 v[16:19], v[176:179], v[208:211], v[16:19]
	v_mfma_f32_16x16x32_bf16 v[32:35], v[176:179], v[200:203], v[32:35]
	v_mfma_f32_16x16x32_bf16 v[48:51], v[176:179], v[184:187], v[48:51]
	s_setprio 0
	s_barrier
	s_add_i32 s77, s77, 2
	s_add_u32 s71, s71, 0x100
	s_addc_u32 s76, s76, 0
	s_cmp_gt_u32 s77, 13
	s_mov_b64 s[30:31], s[8:9]
	s_cbranch_scc0 .LBB0_627
	s_and_b64 vcc, exec, s[22:23]
	s_cbranch_vccz .LBB0_630
	s_barrier

; #define PG8_STAGE(bufoff, gbase, voff) do { _Pragma("unroll") for (int _i = 0; _i < 2; ++_i) \
;         __builtin_amdgcn_global_load_lds((const unsigned*)((const char*)(gbase) + (voff)[_i]), (LAS unsigned*)(lds + (bufoff) + ldsw + _i * 8192), 16, 0, 0); } while (0)
; #define PG8_LDA(dst, b, h) do { _Pragma("unroll") for (int m = 0; m < 4; ++m) _Pragma("unroll") for (int k = 0; k < 2; ++k) dst[m][k] = *(const LAS bf16x8*)(lds + PG8_SA(b, h) + aoff + m * 2048 + k * 1024); } while (0)
; #define PG8_LDB(dst, b, h) do { _Pragma("unroll") for (int n = 0; n < 2; ++n) _Pragma("unroll") for (int k = 0; k < 2; ++k) dst[n][k] = *(const LAS bf16x8*)(lds + PG8_SB(b, h) + boff + n * 2048 + k * 1024); } while (0)
; #define PG8_MMA(ai, bj, At, Bt) do { __builtin_amdgcn_s_setprio(1); _Pragma("unroll") for (int m = 0; m < 4; ++m) _Pragma("unroll") for (int n = 0; n < 2; ++n) _Pragma("unroll") for (int k = 0; k < 2; ++k) \
;         acc[ai][bj][m][n] = __builtin_amdgcn_mfma_f32_16x16x32_bf16(Bt[n][k], At[m][k], acc[ai][bj][m][n], 0, 0, 0); __builtin_amdgcn_s_setprio(0); } while (0)
; #define PG8_WAIT_V(n) asm volatile("s_waitcnt vmcnt(" #n ")" ::: "memory")
; #define PG8_WAIT_L(n) asm volatile("s_waitcnt lgkmcnt(" #n ")" ::: "memory")
; #define PG8_BAR __builtin_amdgcn_s_barrier()
; #define PG8_SCHED __builtin_amdgcn_sched_barrier(0)
; template <class Epi>
; __device__ __forceinline__ void gemm_phase(LAS unsigned char* lds, const Gemm g, const StaticOrder& S, const Epi& E) {
;     ...
;             const bool last = (t == nt - 2);
;             const char* a1 = cA + (unsigned)(t + 1) * kstep;
;             const char* a2 = last ? nA : cA + (unsigned)(t + 2) * kstep; const char* b2 = last ? nB : cB + (unsigned)(t + 2) * kstep;
;             const char* a3 = a2 + kstep; const char* b3 = b2 + kstep;
;             PG8_LDB(B0, 0, 0); PG8_LDB(B1, 0, 1); PG8_SCHED; PG8_LDA(At, 0, 0); PG8_STAGE(PG8_SA(1, 1), a1 + hstepA, voffA);
;             PG8_WAIT_V(8); PG8_WAIT_L(0); PG8_BAR; PG8_MMA(0, 0, At, B0); PG8_MMA(0, 1, At, B1); PG8_BAR; PG8_SCHED;
;             PG8_LDA(At, 0, 1); PG8_STAGE(PG8_SB(0, 0), b2, voffB); PG8_STAGE(PG8_SB(0, 1), b2 + hstepB, voffB); PG8_STAGE(PG8_SA(0, 0), a2, voffA);
;             PG8_WAIT_V(8); PG8_WAIT_L(0); PG8_BAR; PG8_MMA(1, 0, At, B0); PG8_MMA(1, 1, At, B1); PG8_BAR; PG8_SCHED;
.LBB0_703:
	ds_read_b128 v[146:149], v168
	ds_read_b128 v[156:159], v168 offset:1024
	ds_read_b128 v[160:163], v168 offset:2048
	ds_read_b128 v[174:177], v168 offset:3072
	ds_read_b128 v[178:181], v169
	ds_read_b128 v[182:185], v169 offset:1024
	ds_read_b128 v[186:189], v169 offset:2048
	ds_read_b128 v[190:193], v169 offset:3072
	s_add_u32 s30, s28, 0xfffc0080
	s_addc_u32 s31, s29, -1
	s_cmp_eq_u32 s66, 12
	s_cselect_b32 s35, s21, s31
	s_cselect_b32 s34, s62, s30
	s_cselect_b32 s31, s19, s65
	s_cselect_b32 s30, s63, s64
	v_lshl_add_u64 v[150:151], s[28:29], 0, v[140:141]
	s_add_i32 m0, s27, 0xc000
	ds_read_b128 v[194:197], v170
	ds_read_b128 v[198:201], v170 offset:1024
	ds_read_b128 v[202:205], v170 offset:2048
	ds_read_b128 v[206:209], v170 offset:3072
	ds_read_b128 v[210:213], v170 offset:4096
	ds_read_b128 v[214:217], v170 offset:5120
	ds_read_b128 v[218:221], v170 offset:6144
	ds_read_b128 v[222:225], v170 offset:7168
	global_load_lds_dwordx4 v[150:151], off
	v_lshl_add_u64 v[150:151], s[28:29], 0, v[138:139]
	s_add_i32 m0, s27, 0xe000
	s_nop 0
	global_load_lds_dwordx4 v[150:151], off
	s_waitcnt vmcnt(8)
	s_waitcnt lgkmcnt(0)
	s_barrier
	s_setprio 1
	s_waitcnt lgkmcnt(0)
	v_mfma_f32_16x16x32_bf16 v[124:127], v[146:149], v[194:197], v[124:127]
	v_mfma_f32_16x16x32_bf16 v[108:111], v[146:149], v[202:205], v[108:111]
	v_mfma_f32_16x16x32_bf16 v[92:95], v[146:149], v[210:213], v[92:95]
	v_mfma_f32_16x16x32_bf16 v[76:79], v[146:149], v[218:221], v[76:79]
	v_mfma_f32_16x16x32_bf16 v[68:71], v[160:163], v[218:221], v[68:71]
	v_mfma_f32_16x16x32_bf16 v[84:87], v[160:163], v[210:213], v[84:87]
	v_mfma_f32_16x16x32_bf16 v[100:103], v[160:163], v[202:205], v[100:103]
	v_mfma_f32_16x16x32_bf16 v[116:119], v[160:163], v[194:197], v[116:119]
	v_mfma_f32_16x16x32_bf16 v[124:127], v[156:159], v[198:201], v[124:127]
	v_mfma_f32_16x16x32_bf16 v[108:111], v[156:159], v[206:209], v[108:111]
	v_mfma_f32_16x16x32_bf16 v[92:95], v[156:159], v[214:217], v[92:95]
	v_mfma_f32_16x16x32_bf16 v[76:79], v[156:159], v[222:225], v[76:79]
	v_mfma_f32_16x16x32_bf16 v[68:71], v[174:177], v[222:225], v[68:71]
	v_mfma_f32_16x16x32_bf16 v[84:87], v[174:177], v[214:217], v[84:87]
	v_mfma_f32_16x16x32_bf16 v[100:103], v[174:177], v[206:209], v[100:103]
	v_mfma_f32_16x16x32_bf16 v[116:119], v[174:177], v[198:201], v[116:119]
	s_setprio 0
	s_setprio 1
	v_mfma_f32_16x16x32_bf16 v[120:123], v[178:181], v[194:197], v[120:123]
	v_mfma_f32_16x16x32_bf16 v[104:107], v[178:181], v[202:205], v[104:107]
	v_mfma_f32_16x16x32_bf16 v[88:91], v[178:181], v[210:213], v[88:91]
	v_mfma_f32_16x16x32_bf16 v[72:75], v[178:181], v[218:221], v[72:75]
	v_mfma_f32_16x16x32_bf16 v[64:67], v[186:189], v[218:221], v[64:67]
	v_mfma_f32_16x16x32_bf16 v[80:83], v[186:189], v[210:213], v[80:83]
	v_mfma_f32_16x16x32_bf16 v[96:99], v[186:189], v[202:205], v[96:99]
	v_mfma_f32_16x16x32_bf16 v[112:115], v[186:189], v[194:197], v[112:115]
	v_mfma_f32_16x16x32_bf16 v[120:123], v[182:185], v[198:201], v[120:123]
	v_mfma_f32_16x16x32_bf16 v[104:107], v[182:185], v[206:209], v[104:107]
	v_mfma_f32_16x16x32_bf16 v[88:91], v[182:185], v[214:217], v[88:91]
	v_mfma_f32_16x16x32_bf16 v[72:75], v[182:185], v[222:225], v[72:75]
	v_mfma_f32_16x16x32_bf16 v[64:67], v[190:193], v[222:225], v[64:67]
	v_mfma_f32_16x16x32_bf16 v[80:83], v[190:193], v[214:217], v[80:83]
	v_mfma_f32_16x16x32_bf16 v[96:99], v[190:193], v[206:209], v[96:99]
	v_mfma_f32_16x16x32_bf16 v[112:115], v[190:193], v[198:201], v[112:115]
	s_setprio 0
	s_barrier
	s_add_i32 s50, s59, s46
	v_lshl_add_u64 v[150:151], s[30:31], 0, v[132:133]
	s_mov_b32 m0, s50
	ds_read_b128 v[194:197], v170 offset:16384
	ds_read_b128 v[198:201], v170 offset:17408
	ds_read_b128 v[202:205], v170 offset:18432
	ds_read_b128 v[206:209], v170 offset:19456
	ds_read_b128 v[210:213], v170 offset:20480
	ds_read_b128 v[214:217], v170 offset:21504
	ds_read_b128 v[218:221], v170 offset:22528
	ds_read_b128 v[222:225], v170 offset:23552
	global_load_lds_dwordx4 v[150:151], off
	s_add_i32 m0, s50, 0x2000
	s_add_u32 s50, s30, 0x40000
	v_lshl_add_u64 v[164:165], s[30:31], 0, v[128:129]
	s_addc_u32 s51, s31, 0
	s_add_i32 s67, s60, s46
	global_load_lds_dwordx4 v[164:165], off
	v_lshl_add_u64 v[226:227], s[50:51], 0, v[132:133]
	s_mov_b32 m0, s67
	v_lshl_add_u64 v[228:229], s[34:35], 0, v[130:131]
	global_load_lds_dwordx4 v[226:227], off
	v_lshl_add_u64 v[226:227], s[50:51], 0, v[128:129]
	s_add_i32 m0, s67, 0x2000
	s_nop 0
	global_load_lds_dwordx4 v[226:227], off
	v_lshl_add_u64 v[226:227], s[34:35], 0, v[134:135]
	s_mov_b32 m0, s27
	s_nop 0
	global_load_lds_dwordx4 v[226:227], off
	s_mov_b32 m0, s49
	s_nop 0
	global_load_lds_dwordx4 v[228:229], off
	s_waitcnt vmcnt(8)
	s_waitcnt lgkmcnt(0)
	s_barrier
; #define PG8_STAGE(bufoff, gbase, voff) do { _Pragma("unroll") for (int _i = 0; _i < 2; ++_i) \
;         __builtin_amdgcn_global_load_lds((const unsigned*)((const char*)(gbase) + (voff)[_i]), (LAS unsigned*)(lds + (bufoff) + ldsw + _i * 8192), 16, 0, 0); } while (0)
; #define PG8_LDA(dst, b, h) do { _Pragma("unroll") for (int m = 0; m < 4; ++m) _Pragma("unroll") for (int k = 0; k < 2; ++k) dst[m][k] = *(const LAS bf16x8*)(lds + PG8_SA(b, h) + aoff + m * 2048 + k * 1024); } while (0)
; #define PG8_LDB(dst, b, h) do { _Pragma("unroll") for (int n = 0; n < 2; ++n) _Pragma("unroll") for (int k = 0; k < 2; ++k) dst[n][k] = *(const LAS bf16x8*)(lds + PG8_SB(b, h) + boff + n * 2048 + k * 1024); } while (0)
; #define PG8_MMA(ai, bj, At, Bt) do { __builtin_amdgcn_s_setprio(1); _Pragma("unroll") for (int m = 0; m < 4; ++m) _Pragma("unroll") for (int n = 0; n < 2; ++n) _Pragma("unroll") for (int k = 0; k < 2; ++k) \
;         acc[ai][bj][m][n] = __builtin_amdgcn_mfma_f32_16x16x32_bf16(Bt[n][k], At[m][k], acc[ai][bj][m][n], 0, 0, 0); __builtin_amdgcn_s_setprio(0); } while (0)
; #define PG8_WAIT_V(n) asm volatile("s_waitcnt vmcnt(" #n ")" ::: "memory")
; #define PG8_WAIT_L(n) asm volatile("s_waitcnt lgkmcnt(" #n ")" ::: "memory")
; #define PG8_BAR __builtin_amdgcn_s_barrier()
; #define PG8_SCHED __builtin_amdgcn_sched_barrier(0)
; template <class Epi>
; __device__ __forceinline__ void gemm_phase(LAS unsigned char* lds, const Gemm g, const StaticOrder& S, const Epi& E) {
;     ...
;             PG8_WAIT_V(8); PG8_WAIT_L(0); PG8_BAR; PG8_MMA(1, 0, At, B0); PG8_MMA(1, 1, At, B1); PG8_BAR; PG8_SCHED;
;             PG8_LDB(B0, 1, 0); PG8_LDB(B1, 1, 1); PG8_SCHED; PG8_LDA(At, 1, 0); PG8_STAGE(PG8_SA(0, 1), a2 + hstepA, voffA);
;             PG8_WAIT_V(8); PG8_WAIT_L(0); PG8_BAR; PG8_MMA(0, 0, At, B0); PG8_MMA(0, 1, At, B1); PG8_BAR; PG8_SCHED;
	s_setprio 1
	s_waitcnt lgkmcnt(0)
	v_mfma_f32_16x16x32_bf16 v[60:63], v[146:149], v[194:197], v[60:63]
	v_mfma_f32_16x16x32_bf16 v[44:47], v[146:149], v[202:205], v[44:47]
	v_mfma_f32_16x16x32_bf16 v[28:31], v[146:149], v[210:213], v[28:31]
	v_mfma_f32_16x16x32_bf16 v[12:15], v[146:149], v[218:221], v[12:15]
	v_mfma_f32_16x16x32_bf16 v[4:7], v[160:163], v[218:221], v[4:7]
	v_mfma_f32_16x16x32_bf16 v[20:23], v[160:163], v[210:213], v[20:23]
	v_mfma_f32_16x16x32_bf16 v[36:39], v[160:163], v[202:205], v[36:39]
	v_mfma_f32_16x16x32_bf16 v[52:55], v[160:163], v[194:197], v[52:55]
	v_mfma_f32_16x16x32_bf16 v[60:63], v[156:159], v[198:201], v[60:63]
	v_mfma_f32_16x16x32_bf16 v[44:47], v[156:159], v[206:209], v[44:47]
	v_mfma_f32_16x16x32_bf16 v[28:31], v[156:159], v[214:217], v[28:31]
	v_mfma_f32_16x16x32_bf16 v[12:15], v[156:159], v[222:225], v[12:15]
	v_mfma_f32_16x16x32_bf16 v[4:7], v[174:177], v[222:225], v[4:7]
	v_mfma_f32_16x16x32_bf16 v[20:23], v[174:177], v[214:217], v[20:23]
	v_mfma_f32_16x16x32_bf16 v[36:39], v[174:177], v[206:209], v[36:39]
	v_mfma_f32_16x16x32_bf16 v[52:55], v[174:177], v[198:201], v[52:55]
	s_setprio 0
	s_setprio 1
	v_mfma_f32_16x16x32_bf16 v[56:59], v[178:181], v[194:197], v[56:59]
	v_mfma_f32_16x16x32_bf16 v[40:43], v[178:181], v[202:205], v[40:43]
	v_mfma_f32_16x16x32_bf16 v[24:27], v[178:181], v[210:213], v[24:27]
	v_mfma_f32_16x16x32_bf16 v[8:11], v[178:181], v[218:221], v[8:11]
	v_mfma_f32_16x16x32_bf16 v[0:3], v[186:189], v[218:221], v[0:3]
	v_mfma_f32_16x16x32_bf16 v[16:19], v[186:189], v[210:213], v[16:19]
	v_mfma_f32_16x16x32_bf16 v[32:35], v[186:189], v[202:205], v[32:35]
	v_mfma_f32_16x16x32_bf16 v[48:51], v[186:189], v[194:197], v[48:51]
	v_mfma_f32_16x16x32_bf16 v[56:59], v[182:185], v[198:201], v[56:59]
	v_mfma_f32_16x16x32_bf16 v[40:43], v[182:185], v[206:209], v[40:43]
	v_mfma_f32_16x16x32_bf16 v[24:27], v[182:185], v[214:217], v[24:27]
	v_mfma_f32_16x16x32_bf16 v[8:11], v[182:185], v[222:225], v[8:11]
	v_mfma_f32_16x16x32_bf16 v[0:3], v[190:193], v[222:225], v[0:3]
	v_mfma_f32_16x16x32_bf16 v[16:19], v[190:193], v[214:217], v[16:19]
	v_mfma_f32_16x16x32_bf16 v[32:35], v[190:193], v[206:209], v[32:35]
	v_mfma_f32_16x16x32_bf16 v[48:51], v[190:193], v[198:201], v[48:51]
	s_setprio 0
	s_barrier
	s_add_i32 s50, 0, 0x18000
	v_add_u32_e32 v173, s50, v166
	s_add_i32 s51, 0, 0x1c000
	ds_read_b128 v[146:149], v173
	ds_read_b128 v[156:159], v173 offset:1024
	ds_read_b128 v[160:163], v173 offset:2048
	ds_read_b128 v[174:177], v173 offset:3072
	v_add_u32_e32 v173, s51, v166
	ds_read_b128 v[178:181], v173
	ds_read_b128 v[182:185], v173 offset:1024
	ds_read_b128 v[186:189], v173 offset:2048
	ds_read_b128 v[190:193], v173 offset:3072
	s_add_u32 s34, s34, 0x40000
	s_addc_u32 s35, s35, 0
	s_mov_b32 m0, s52
	v_lshl_add_u64 v[230:231], s[34:35], 0, v[134:135]
	ds_read_b128 v[194:197], v170 offset:32768
	ds_read_b128 v[198:201], v170 offset:33792
	ds_read_b128 v[202:205], v170 offset:34816
	ds_read_b128 v[206:209], v170 offset:35840
	ds_read_b128 v[210:213], v170 offset:36864
	ds_read_b128 v[214:217], v170 offset:37888
	ds_read_b128 v[218:221], v170 offset:38912
	ds_read_b128 v[222:225], v170 offset:39936
	global_load_lds_dwordx4 v[230:231], off
	v_lshl_add_u64 v[230:231], s[34:35], 0, v[130:131]
	s_mov_b32 m0, s53
	s_nop 0
	global_load_lds_dwordx4 v[230:231], off
	s_waitcnt vmcnt(8)
	s_waitcnt lgkmcnt(0)
	s_barrier
	s_setprio 1
	s_waitcnt lgkmcnt(0)
	v_mfma_f32_16x16x32_bf16 v[124:127], v[146:149], v[194:197], v[124:127]
	v_mfma_f32_16x16x32_bf16 v[108:111], v[146:149], v[202:205], v[108:111]
	v_mfma_f32_16x16x32_bf16 v[92:95], v[146:149], v[210:213], v[92:95]
	v_mfma_f32_16x16x32_bf16 v[76:79], v[146:149], v[218:221], v[76:79]
	v_mfma_f32_16x16x32_bf16 v[68:71], v[160:163], v[218:221], v[68:71]
	v_mfma_f32_16x16x32_bf16 v[84:87], v[160:163], v[210:213], v[84:87]
	v_mfma_f32_16x16x32_bf16 v[100:103], v[160:163], v[202:205], v[100:103]
	v_mfma_f32_16x16x32_bf16 v[116:119], v[160:163], v[194:197], v[116:119]
	v_mfma_f32_16x16x32_bf16 v[124:127], v[156:159], v[198:201], v[124:127]
	v_mfma_f32_16x16x32_bf16 v[108:111], v[156:159], v[206:209], v[108:111]
	v_mfma_f32_16x16x32_bf16 v[92:95], v[156:159], v[214:217], v[92:95]
	v_mfma_f32_16x16x32_bf16 v[76:79], v[156:159], v[222:225], v[76:79]
	v_mfma_f32_16x16x32_bf16 v[68:71], v[174:177], v[222:225], v[68:71]
	v_mfma_f32_16x16x32_bf16 v[84:87], v[174:177], v[214:217], v[84:87]
	v_mfma_f32_16x16x32_bf16 v[100:103], v[174:177], v[206:209], v[100:103]
	v_mfma_f32_16x16x32_bf16 v[116:119], v[174:177], v[198:201], v[116:119]
	s_setprio 0
	s_setprio 1
	v_mfma_f32_16x16x32_bf16 v[120:123], v[178:181], v[194:197], v[120:123]
	v_mfma_f32_16x16x32_bf16 v[104:107], v[178:181], v[202:205], v[104:107]
	v_mfma_f32_16x16x32_bf16 v[88:91], v[178:181], v[210:213], v[88:91]
	v_mfma_f32_16x16x32_bf16 v[72:75], v[178:181], v[218:221], v[72:75]
	v_mfma_f32_16x16x32_bf16 v[64:67], v[186:189], v[218:221], v[64:67]
	v_mfma_f32_16x16x32_bf16 v[80:83], v[186:189], v[210:213], v[80:83]
	v_mfma_f32_16x16x32_bf16 v[96:99], v[186:189], v[202:205], v[96:99]
	v_mfma_f32_16x16x32_bf16 v[112:115], v[186:189], v[194:197], v[112:115]
	v_mfma_f32_16x16x32_bf16 v[120:123], v[182:185], v[198:201], v[120:123]
	v_mfma_f32_16x16x32_bf16 v[104:107], v[182:185], v[206:209], v[104:107]
	v_mfma_f32_16x16x32_bf16 v[88:91], v[182:185], v[214:217], v[88:91]
	v_mfma_f32_16x16x32_bf16 v[72:75], v[182:185], v[222:225], v[72:75]
	v_mfma_f32_16x16x32_bf16 v[64:67], v[190:193], v[222:225], v[64:67]
	v_mfma_f32_16x16x32_bf16 v[80:83], v[190:193], v[214:217], v[80:83]
	v_mfma_f32_16x16x32_bf16 v[96:99], v[190:193], v[206:209], v[96:99]
	v_mfma_f32_16x16x32_bf16 v[112:115], v[190:193], v[198:201], v[112:115]
	s_setprio 0
	s_barrier
; #define PG8_STAGE(bufoff, gbase, voff) do { _Pragma("unroll") for (int _i = 0; _i < 2; ++_i) \
;         __builtin_amdgcn_global_load_lds((const unsigned*)((const char*)(gbase) + (voff)[_i]), (LAS unsigned*)(lds + (bufoff) + ldsw + _i * 8192), 16, 0, 0); } while (0)
; #define PG8_LDA(dst, b, h) do { _Pragma("unroll") for (int m = 0; m < 4; ++m) _Pragma("unroll") for (int k = 0; k < 2; ++k) dst[m][k] = *(const LAS bf16x8*)(lds + PG8_SA(b, h) + aoff + m * 2048 + k * 1024); } while (0)
; #define PG8_MMA(ai, bj, At, Bt) do { __builtin_amdgcn_s_setprio(1); _Pragma("unroll") for (int m = 0; m < 4; ++m) _Pragma("unroll") for (int n = 0; n < 2; ++n) _Pragma("unroll") for (int k = 0; k < 2; ++k) \
;         acc[ai][bj][m][n] = __builtin_amdgcn_mfma_f32_16x16x32_bf16(Bt[n][k], At[m][k], acc[ai][bj][m][n], 0, 0, 0); __builtin_amdgcn_s_setprio(0); } while (0)
; #define PG8_WAIT_V(n) asm volatile("s_waitcnt vmcnt(" #n ")" ::: "memory")
; #define PG8_WAIT_L(n) asm volatile("s_waitcnt lgkmcnt(" #n ")" ::: "memory")
; #define PG8_BAR __builtin_amdgcn_s_barrier()
; #define PG8_SCHED __builtin_amdgcn_sched_barrier(0)
; template <class Epi>
; __device__ __forceinline__ void gemm_phase(LAS unsigned char* lds, const Gemm g, const StaticOrder& S, const Epi& E) {
;     ...
;             PG8_LDA(At, 1, 1); PG8_STAGE(PG8_SB(1, 0), b3, voffB); PG8_STAGE(PG8_SB(1, 1), b3 + hstepB, voffB); PG8_STAGE(PG8_SA(1, 0), a3, voffA);
;             PG8_WAIT_V(8); PG8_WAIT_L(0); PG8_BAR; PG8_MMA(1, 0, At, B0); PG8_MMA(1, 1, At, B1); PG8_BAR; PG8_SCHED;
;         }
;         if (wr == 0) PG8_BAR;
	s_add_i32 s34, s50, s46
	v_lshl_add_u64 v[150:151], v[150:151], 0, s[12:13]
	s_mov_b32 m0, s34
	ds_read_b128 v[194:197], v170 offset:49152
	ds_read_b128 v[198:201], v170 offset:50176
	ds_read_b128 v[202:205], v170 offset:51200
	ds_read_b128 v[206:209], v170 offset:52224
	ds_read_b128 v[210:213], v170 offset:53248
	ds_read_b128 v[214:217], v170 offset:54272
	ds_read_b128 v[218:221], v170 offset:55296
	ds_read_b128 v[222:225], v170 offset:56320
	global_load_lds_dwordx4 v[150:151], off
	s_add_i32 m0, s34, 0x2000
	s_add_u32 s30, s30, 0x40080
	v_lshl_add_u64 v[150:151], v[164:165], 0, s[12:13]
	s_addc_u32 s31, s31, 0
	s_add_i32 s34, s51, s46
	global_load_lds_dwordx4 v[150:151], off
	v_lshl_add_u64 v[150:151], s[30:31], 0, v[132:133]
	s_mov_b32 m0, s34
	s_nop 0
	global_load_lds_dwordx4 v[150:151], off
	v_lshl_add_u64 v[150:151], s[30:31], 0, v[128:129]
	s_add_i32 m0, s34, 0x2000
	s_nop 0
	global_load_lds_dwordx4 v[150:151], off
	v_lshl_add_u64 v[150:151], v[226:227], 0, s[12:13]
	s_mov_b32 m0, s55
	s_nop 0
	global_load_lds_dwordx4 v[150:151], off
	v_lshl_add_u64 v[150:151], v[228:229], 0, s[12:13]
	s_mov_b32 m0, s56
	s_nop 0
	global_load_lds_dwordx4 v[150:151], off
	s_waitcnt vmcnt(8)
	s_waitcnt lgkmcnt(0)
	s_barrier
	s_setprio 1
	s_waitcnt lgkmcnt(0)
	v_mfma_f32_16x16x32_bf16 v[60:63], v[146:149], v[194:197], v[60:63]
	v_mfma_f32_16x16x32_bf16 v[44:47], v[146:149], v[202:205], v[44:47]
	v_mfma_f32_16x16x32_bf16 v[28:31], v[146:149], v[210:213], v[28:31]
	v_mfma_f32_16x16x32_bf16 v[12:15], v[146:149], v[218:221], v[12:15]
	v_mfma_f32_16x16x32_bf16 v[4:7], v[160:163], v[218:221], v[4:7]
	v_mfma_f32_16x16x32_bf16 v[20:23], v[160:163], v[210:213], v[20:23]
	v_mfma_f32_16x16x32_bf16 v[36:39], v[160:163], v[202:205], v[36:39]
	v_mfma_f32_16x16x32_bf16 v[52:55], v[160:163], v[194:197], v[52:55]
	v_mfma_f32_16x16x32_bf16 v[60:63], v[156:159], v[198:201], v[60:63]
	v_mfma_f32_16x16x32_bf16 v[44:47], v[156:159], v[206:209], v[44:47]
	v_mfma_f32_16x16x32_bf16 v[28:31], v[156:159], v[214:217], v[28:31]
	v_mfma_f32_16x16x32_bf16 v[12:15], v[156:159], v[222:225], v[12:15]
	v_mfma_f32_16x16x32_bf16 v[4:7], v[174:177], v[222:225], v[4:7]
	v_mfma_f32_16x16x32_bf16 v[20:23], v[174:177], v[214:217], v[20:23]
	v_mfma_f32_16x16x32_bf16 v[36:39], v[174:177], v[206:209], v[36:39]
	v_mfma_f32_16x16x32_bf16 v[52:55], v[174:177], v[198:201], v[52:55]
	s_setprio 0
	s_setprio 1
	v_mfma_f32_16x16x32_bf16 v[56:59], v[178:181], v[194:197], v[56:59]
	v_mfma_f32_16x16x32_bf16 v[40:43], v[178:181], v[202:205], v[40:43]
	v_mfma_f32_16x16x32_bf16 v[24:27], v[178:181], v[210:213], v[24:27]
	v_mfma_f32_16x16x32_bf16 v[8:11], v[178:181], v[218:221], v[8:11]
	v_mfma_f32_16x16x32_bf16 v[0:3], v[186:189], v[218:221], v[0:3]
	v_mfma_f32_16x16x32_bf16 v[16:19], v[186:189], v[210:213], v[16:19]
	v_mfma_f32_16x16x32_bf16 v[32:35], v[186:189], v[202:205], v[32:35]
	v_mfma_f32_16x16x32_bf16 v[48:51], v[186:189], v[194:197], v[48:51]
	v_mfma_f32_16x16x32_bf16 v[56:59], v[182:185], v[198:201], v[56:59]
	v_mfma_f32_16x16x32_bf16 v[40:43], v[182:185], v[206:209], v[40:43]
	v_mfma_f32_16x16x32_bf16 v[24:27], v[182:185], v[214:217], v[24:27]
	v_mfma_f32_16x16x32_bf16 v[8:11], v[182:185], v[222:225], v[8:11]
	v_mfma_f32_16x16x32_bf16 v[0:3], v[190:193], v[222:225], v[0:3]
	v_mfma_f32_16x16x32_bf16 v[16:19], v[190:193], v[214:217], v[16:19]
	v_mfma_f32_16x16x32_bf16 v[32:35], v[190:193], v[206:209], v[32:35]
	v_mfma_f32_16x16x32_bf16 v[48:51], v[190:193], v[198:201], v[48:51]
	s_setprio 0
	s_barrier
	s_add_i32 s66, s66, 2
	s_add_u32 s64, s64, 0x100
	s_addc_u32 s65, s65, 0
	s_add_u32 s28, s28, 0x100
	s_addc_u32 s29, s29, 0
	s_cmp_gt_u32 s66, 13
	s_cbranch_scc0 .LBB0_703
	s_and_b64 vcc, exec, s[16:17]
	s_cbranch_vccz .LBB0_706
	s_barrier

; #define PG8_STAGE(bufoff, gbase, voff) do { _Pragma("unroll") for (int _i = 0; _i < 2; ++_i) \
;         __builtin_amdgcn_global_load_lds((const unsigned*)((const char*)(gbase) + (voff)[_i]), (LAS unsigned*)(lds + (bufoff) + ldsw + _i * 8192), 16, 0, 0); } while (0)
; #define PG8_LDA(dst, b, h) do { _Pragma("unroll") for (int m = 0; m < 4; ++m) _Pragma("unroll") for (int k = 0; k < 2; ++k) dst[m][k] = *(const LAS bf16x8*)(lds + PG8_SA(b, h) + aoff + m * 2048 + k * 1024); } while (0)
; #define PG8_LDB(dst, b, h) do { _Pragma("unroll") for (int n = 0; n < 2; ++n) _Pragma("unroll") for (int k = 0; k < 2; ++k) dst[n][k] = *(const LAS bf16x8*)(lds + PG8_SB(b, h) + boff + n * 2048 + k * 1024); } while (0)
; #define PG8_MMA(ai, bj, At, Bt) do { __builtin_amdgcn_s_setprio(1); _Pragma("unroll") for (int m = 0; m < 4; ++m) _Pragma("unroll") for (int n = 0; n < 2; ++n) _Pragma("unroll") for (int k = 0; k < 2; ++k) \
;         acc[ai][bj][m][n] = __builtin_amdgcn_mfma_f32_16x16x32_bf16(Bt[n][k], At[m][k], acc[ai][bj][m][n], 0, 0, 0); __builtin_amdgcn_s_setprio(0); } while (0)
; #define PG8_WAIT_V(n) asm volatile("s_waitcnt vmcnt(" #n ")" ::: "memory")
; #define PG8_WAIT_L(n) asm volatile("s_waitcnt lgkmcnt(" #n ")" ::: "memory")
; #define PG8_BAR __builtin_amdgcn_s_barrier()
; #define PG8_SCHED __builtin_amdgcn_sched_barrier(0)
; template <class Epi>
; __device__ __forceinline__ void gemm_phase(LAS unsigned char* lds, const Gemm g, const StaticOrder& S, const Epi& E) {
;     ...
;             const bool last = (t == nt - 2);
;             const char* a1 = cA + (unsigned)(t + 1) * kstep;
;             const char* a2 = last ? nA : cA + (unsigned)(t + 2) * kstep; const char* b2 = last ? nB : cB + (unsigned)(t + 2) * kstep;
;             const char* a3 = a2 + kstep; const char* b3 = b2 + kstep;
;             PG8_LDB(B0, 0, 0); PG8_LDB(B1, 0, 1); PG8_SCHED; PG8_LDA(At, 0, 0); PG8_STAGE(PG8_SA(1, 1), a1 + hstepA, voffA);
;             PG8_WAIT_V(8); PG8_WAIT_L(0); PG8_BAR; PG8_MMA(0, 0, At, B0); PG8_MMA(0, 1, At, B1); PG8_BAR; PG8_SCHED;
;             PG8_LDA(At, 0, 1); PG8_STAGE(PG8_SB(0, 0), b2, voffB); PG8_STAGE(PG8_SB(0, 1), b2 + hstepB, voffB); PG8_STAGE(PG8_SA(0, 0), a2, voffA);
;             PG8_WAIT_V(8); PG8_WAIT_L(0); PG8_BAR; PG8_MMA(1, 0, At, B0); PG8_MMA(1, 1, At, B1); PG8_BAR; PG8_SCHED;
.LBB0_767:
	ds_read_b128 v[144:147], v158
	ds_read_b128 v[148:151], v158 offset:1024
	ds_read_b128 v[162:165], v158 offset:2048
	ds_read_b128 v[166:169], v158 offset:3072
	ds_read_b128 v[170:173], v159
	ds_read_b128 v[174:177], v159 offset:1024
	ds_read_b128 v[178:181], v159 offset:2048
	ds_read_b128 v[182:185], v159 offset:3072
	s_add_u32 s34, s30, 0x100
	s_addc_u32 s35, s31, 0
	s_cmp_eq_u32 s77, 40
	s_cselect_b32 s39, s9, s35
	s_cselect_b32 s38, s8, s34
	s_cselect_b32 s37, s29, s76
	s_cselect_b32 s36, s28, s71
	v_lshl_add_u64 v[218:219], s[30:31], 0, v[138:139]
	s_add_i32 m0, s55, 0xc000
	ds_read_b128 v[186:189], v160
	ds_read_b128 v[190:193], v160 offset:1024
	ds_read_b128 v[194:197], v160 offset:2048
	ds_read_b128 v[198:201], v160 offset:3072
	ds_read_b128 v[202:205], v160 offset:4096
	ds_read_b128 v[206:209], v160 offset:5120
	ds_read_b128 v[210:213], v160 offset:6144
	ds_read_b128 v[214:217], v160 offset:7168
	global_load_lds_dwordx4 v[218:219], off
	v_lshl_add_u64 v[218:219], s[30:31], 0, v[136:137]
	s_add_i32 m0, s55, 0xe000
	s_nop 0
	global_load_lds_dwordx4 v[218:219], off
	s_waitcnt vmcnt(8)
	s_waitcnt lgkmcnt(0)
	s_barrier
	s_setprio 1
	s_waitcnt lgkmcnt(0)
	v_mfma_f32_16x16x32_bf16 v[124:127], v[144:147], v[186:189], v[124:127]
	v_mfma_f32_16x16x32_bf16 v[116:119], v[144:147], v[194:197], v[116:119]
	v_mfma_f32_16x16x32_bf16 v[96:99], v[144:147], v[202:205], v[96:99]
	v_mfma_f32_16x16x32_bf16 v[80:83], v[144:147], v[210:213], v[80:83]
	v_mfma_f32_16x16x32_bf16 v[72:75], v[162:165], v[210:213], v[72:75]
	v_mfma_f32_16x16x32_bf16 v[88:91], v[162:165], v[202:205], v[88:91]
	v_mfma_f32_16x16x32_bf16 v[112:115], v[162:165], v[194:197], v[112:115]
	v_mfma_f32_16x16x32_bf16 v[120:123], v[162:165], v[186:189], v[120:123]
	v_mfma_f32_16x16x32_bf16 v[124:127], v[148:151], v[190:193], v[124:127]
	v_mfma_f32_16x16x32_bf16 v[116:119], v[148:151], v[198:201], v[116:119]
	v_mfma_f32_16x16x32_bf16 v[96:99], v[148:151], v[206:209], v[96:99]
	v_mfma_f32_16x16x32_bf16 v[80:83], v[148:151], v[214:217], v[80:83]
	v_mfma_f32_16x16x32_bf16 v[72:75], v[166:169], v[214:217], v[72:75]
	v_mfma_f32_16x16x32_bf16 v[88:91], v[166:169], v[206:209], v[88:91]
	v_mfma_f32_16x16x32_bf16 v[112:115], v[166:169], v[198:201], v[112:115]
	v_mfma_f32_16x16x32_bf16 v[120:123], v[166:169], v[190:193], v[120:123]
	s_setprio 0
	s_setprio 1
	v_mfma_f32_16x16x32_bf16 v[108:111], v[170:173], v[186:189], v[108:111]
	v_mfma_f32_16x16x32_bf16 v[100:103], v[170:173], v[194:197], v[100:103]
	v_mfma_f32_16x16x32_bf16 v[84:87], v[170:173], v[202:205], v[84:87]
	v_mfma_f32_16x16x32_bf16 v[68:71], v[170:173], v[210:213], v[68:71]
	v_mfma_f32_16x16x32_bf16 v[64:67], v[178:181], v[210:213], v[64:67]
	v_mfma_f32_16x16x32_bf16 v[76:79], v[178:181], v[202:205], v[76:79]
	v_mfma_f32_16x16x32_bf16 v[92:95], v[178:181], v[194:197], v[92:95]
	v_mfma_f32_16x16x32_bf16 v[104:107], v[178:181], v[186:189], v[104:107]
	v_mfma_f32_16x16x32_bf16 v[108:111], v[174:177], v[190:193], v[108:111]
	v_mfma_f32_16x16x32_bf16 v[100:103], v[174:177], v[198:201], v[100:103]
	v_mfma_f32_16x16x32_bf16 v[84:87], v[174:177], v[206:209], v[84:87]
	v_mfma_f32_16x16x32_bf16 v[68:71], v[174:177], v[214:217], v[68:71]
	v_mfma_f32_16x16x32_bf16 v[64:67], v[182:185], v[214:217], v[64:67]
	v_mfma_f32_16x16x32_bf16 v[76:79], v[182:185], v[206:209], v[76:79]
	v_mfma_f32_16x16x32_bf16 v[92:95], v[182:185], v[198:201], v[92:95]
	v_mfma_f32_16x16x32_bf16 v[104:107], v[182:185], v[190:193], v[104:107]
	s_setprio 0
	s_barrier
	s_add_i32 s30, s64, s52
	v_lshl_add_u64 v[218:219], s[36:37], 0, v[132:133]
	s_mov_b32 m0, s30
	ds_read_b128 v[186:189], v160 offset:16384
	ds_read_b128 v[190:193], v160 offset:17408
	ds_read_b128 v[194:197], v160 offset:18432
	ds_read_b128 v[198:201], v160 offset:19456
	ds_read_b128 v[202:205], v160 offset:20480
	ds_read_b128 v[206:209], v160 offset:21504
	ds_read_b128 v[210:213], v160 offset:22528
	ds_read_b128 v[214:217], v160 offset:23552
	global_load_lds_dwordx4 v[218:219], off
	s_add_i32 m0, s30, 0x2000
	s_add_u32 s30, s36, 0xb0000
	v_lshl_add_u64 v[220:221], s[36:37], 0, v[128:129]
	s_addc_u32 s31, s37, 0
	s_add_i32 s50, s65, s52
	global_load_lds_dwordx4 v[220:221], off
	v_lshl_add_u64 v[222:223], s[30:31], 0, v[132:133]
	s_mov_b32 m0, s50
	v_lshl_add_u64 v[224:225], s[38:39], 0, v[130:131]
	global_load_lds_dwordx4 v[222:223], off
	v_lshl_add_u64 v[222:223], s[30:31], 0, v[128:129]
	s_add_i32 m0, s50, 0x2000
	s_nop 0
	global_load_lds_dwordx4 v[222:223], off
	v_lshl_add_u64 v[222:223], s[38:39], 0, v[134:135]
	s_mov_b32 m0, s55
	s_nop 0
	global_load_lds_dwordx4 v[222:223], off
	s_mov_b32 m0, s56
	s_nop 0
	global_load_lds_dwordx4 v[224:225], off
	s_waitcnt vmcnt(8)
	s_waitcnt lgkmcnt(0)
	s_barrier
; #define PG8_STAGE(bufoff, gbase, voff) do { _Pragma("unroll") for (int _i = 0; _i < 2; ++_i) \
;         __builtin_amdgcn_global_load_lds((const unsigned*)((const char*)(gbase) + (voff)[_i]), (LAS unsigned*)(lds + (bufoff) + ldsw + _i * 8192), 16, 0, 0); } while (0)
; #define PG8_LDA(dst, b, h) do { _Pragma("unroll") for (int m = 0; m < 4; ++m) _Pragma("unroll") for (int k = 0; k < 2; ++k) dst[m][k] = *(const LAS bf16x8*)(lds + PG8_SA(b, h) + aoff + m * 2048 + k * 1024); } while (0)
; #define PG8_LDB(dst, b, h) do { _Pragma("unroll") for (int n = 0; n < 2; ++n) _Pragma("unroll") for (int k = 0; k < 2; ++k) dst[n][k] = *(const LAS bf16x8*)(lds + PG8_SB(b, h) + boff + n * 2048 + k * 1024); } while (0)
; #define PG8_MMA(ai, bj, At, Bt) do { __builtin_amdgcn_s_setprio(1); _Pragma("unroll") for (int m = 0; m < 4; ++m) _Pragma("unroll") for (int n = 0; n < 2; ++n) _Pragma("unroll") for (int k = 0; k < 2; ++k) \
;         acc[ai][bj][m][n] = __builtin_amdgcn_mfma_f32_16x16x32_bf16(Bt[n][k], At[m][k], acc[ai][bj][m][n], 0, 0, 0); __builtin_amdgcn_s_setprio(0); } while (0)
; #define PG8_WAIT_V(n) asm volatile("s_waitcnt vmcnt(" #n ")" ::: "memory")
; #define PG8_WAIT_L(n) asm volatile("s_waitcnt lgkmcnt(" #n ")" ::: "memory")
; #define PG8_BAR __builtin_amdgcn_s_barrier()
; #define PG8_SCHED __builtin_amdgcn_sched_barrier(0)
; template <class Epi>
; __device__ __forceinline__ void gemm_phase(LAS unsigned char* lds, const Gemm g, const StaticOrder& S, const Epi& E) {
;     ...
;             PG8_WAIT_V(8); PG8_WAIT_L(0); PG8_BAR; PG8_MMA(1, 0, At, B0); PG8_MMA(1, 1, At, B1); PG8_BAR; PG8_SCHED;
;             PG8_LDB(B0, 1, 0); PG8_LDB(B1, 1, 1); PG8_SCHED; PG8_LDA(At, 1, 0); PG8_STAGE(PG8_SA(0, 1), a2 + hstepA, voffA);
;             PG8_WAIT_V(8); PG8_WAIT_L(0); PG8_BAR; PG8_MMA(0, 0, At, B0); PG8_MMA(0, 1, At, B1); PG8_BAR; PG8_SCHED;
	s_setprio 1
	s_waitcnt lgkmcnt(0)
	v_mfma_f32_16x16x32_bf16 v[60:63], v[144:147], v[186:189], v[60:63]
	v_mfma_f32_16x16x32_bf16 v[48:51], v[144:147], v[194:197], v[48:51]
	v_mfma_f32_16x16x32_bf16 v[32:35], v[144:147], v[202:205], v[32:35]
	v_mfma_f32_16x16x32_bf16 v[16:19], v[144:147], v[210:213], v[16:19]
	v_mfma_f32_16x16x32_bf16 v[8:11], v[162:165], v[210:213], v[8:11]
	v_mfma_f32_16x16x32_bf16 v[24:27], v[162:165], v[202:205], v[24:27]
	v_mfma_f32_16x16x32_bf16 v[40:43], v[162:165], v[194:197], v[40:43]
	v_mfma_f32_16x16x32_bf16 v[56:59], v[162:165], v[186:189], v[56:59]
	v_mfma_f32_16x16x32_bf16 v[60:63], v[148:151], v[190:193], v[60:63]
	v_mfma_f32_16x16x32_bf16 v[48:51], v[148:151], v[198:201], v[48:51]
	v_mfma_f32_16x16x32_bf16 v[32:35], v[148:151], v[206:209], v[32:35]
	v_mfma_f32_16x16x32_bf16 v[16:19], v[148:151], v[214:217], v[16:19]
	v_mfma_f32_16x16x32_bf16 v[8:11], v[166:169], v[214:217], v[8:11]
	v_mfma_f32_16x16x32_bf16 v[24:27], v[166:169], v[206:209], v[24:27]
	v_mfma_f32_16x16x32_bf16 v[40:43], v[166:169], v[198:201], v[40:43]
	v_mfma_f32_16x16x32_bf16 v[56:59], v[166:169], v[190:193], v[56:59]
	s_setprio 0
	s_setprio 1
	v_mfma_f32_16x16x32_bf16 v[52:55], v[170:173], v[186:189], v[52:55]
	v_mfma_f32_16x16x32_bf16 v[36:39], v[170:173], v[194:197], v[36:39]
	v_mfma_f32_16x16x32_bf16 v[20:23], v[170:173], v[202:205], v[20:23]
	v_mfma_f32_16x16x32_bf16 v[4:7], v[170:173], v[210:213], v[4:7]
	v_mfma_f32_16x16x32_bf16 v[0:3], v[178:181], v[210:213], v[0:3]
	v_mfma_f32_16x16x32_bf16 v[12:15], v[178:181], v[202:205], v[12:15]
	v_mfma_f32_16x16x32_bf16 v[28:31], v[178:181], v[194:197], v[28:31]
	v_mfma_f32_16x16x32_bf16 v[44:47], v[178:181], v[186:189], v[44:47]
	v_mfma_f32_16x16x32_bf16 v[52:55], v[174:177], v[190:193], v[52:55]
	v_mfma_f32_16x16x32_bf16 v[36:39], v[174:177], v[198:201], v[36:39]
	v_mfma_f32_16x16x32_bf16 v[20:23], v[174:177], v[206:209], v[20:23]
	v_mfma_f32_16x16x32_bf16 v[4:7], v[174:177], v[214:217], v[4:7]
	v_mfma_f32_16x16x32_bf16 v[0:3], v[182:185], v[214:217], v[0:3]
	v_mfma_f32_16x16x32_bf16 v[12:15], v[182:185], v[206:209], v[12:15]
	v_mfma_f32_16x16x32_bf16 v[28:31], v[182:185], v[198:201], v[28:31]
	v_mfma_f32_16x16x32_bf16 v[44:47], v[182:185], v[190:193], v[44:47]
	s_setprio 0
	s_barrier
	s_add_i32 s50, 0, 0x18000
	v_add_u32_e32 v161, s50, v156
	s_add_i32 s51, 0, 0x1c000
	ds_read_b128 v[144:147], v161
	ds_read_b128 v[148:151], v161 offset:1024
	ds_read_b128 v[162:165], v161 offset:2048
	ds_read_b128 v[166:169], v161 offset:3072
	v_add_u32_e32 v161, s51, v156
	ds_read_b128 v[170:173], v161
	ds_read_b128 v[174:177], v161 offset:1024
	ds_read_b128 v[178:181], v161 offset:2048
	ds_read_b128 v[182:185], v161 offset:3072
	s_add_u32 s30, s38, 0xb0000
	s_addc_u32 s31, s39, 0
	s_mov_b32 m0, s57
	v_lshl_add_u64 v[226:227], s[30:31], 0, v[134:135]
	ds_read_b128 v[186:189], v160 offset:32768
	ds_read_b128 v[190:193], v160 offset:33792
	ds_read_b128 v[194:197], v160 offset:34816
	ds_read_b128 v[198:201], v160 offset:35840
	ds_read_b128 v[202:205], v160 offset:36864
	ds_read_b128 v[206:209], v160 offset:37888
	ds_read_b128 v[210:213], v160 offset:38912
	ds_read_b128 v[214:217], v160 offset:39936
	global_load_lds_dwordx4 v[226:227], off
	v_lshl_add_u64 v[226:227], s[30:31], 0, v[130:131]
	s_mov_b32 m0, s58
	s_nop 0
	global_load_lds_dwordx4 v[226:227], off
	s_waitcnt vmcnt(8)
	s_waitcnt lgkmcnt(0)
	s_barrier
	s_setprio 1
	s_waitcnt lgkmcnt(0)
	v_mfma_f32_16x16x32_bf16 v[124:127], v[144:147], v[186:189], v[124:127]
	v_mfma_f32_16x16x32_bf16 v[116:119], v[144:147], v[194:197], v[116:119]
	v_mfma_f32_16x16x32_bf16 v[96:99], v[144:147], v[202:205], v[96:99]
	v_mfma_f32_16x16x32_bf16 v[80:83], v[144:147], v[210:213], v[80:83]
	v_mfma_f32_16x16x32_bf16 v[72:75], v[162:165], v[210:213], v[72:75]
	v_mfma_f32_16x16x32_bf16 v[88:91], v[162:165], v[202:205], v[88:91]
	v_mfma_f32_16x16x32_bf16 v[112:115], v[162:165], v[194:197], v[112:115]
	v_mfma_f32_16x16x32_bf16 v[120:123], v[162:165], v[186:189], v[120:123]
	v_mfma_f32_16x16x32_bf16 v[124:127], v[148:151], v[190:193], v[124:127]
	v_mfma_f32_16x16x32_bf16 v[116:119], v[148:151], v[198:201], v[116:119]
	v_mfma_f32_16x16x32_bf16 v[96:99], v[148:151], v[206:209], v[96:99]
	v_mfma_f32_16x16x32_bf16 v[80:83], v[148:151], v[214:217], v[80:83]
	v_mfma_f32_16x16x32_bf16 v[72:75], v[166:169], v[214:217], v[72:75]
	v_mfma_f32_16x16x32_bf16 v[88:91], v[166:169], v[206:209], v[88:91]
	v_mfma_f32_16x16x32_bf16 v[112:115], v[166:169], v[198:201], v[112:115]
	v_mfma_f32_16x16x32_bf16 v[120:123], v[166:169], v[190:193], v[120:123]
	s_setprio 0
	s_setprio 1
	v_mfma_f32_16x16x32_bf16 v[108:111], v[170:173], v[186:189], v[108:111]
	v_mfma_f32_16x16x32_bf16 v[100:103], v[170:173], v[194:197], v[100:103]
	v_mfma_f32_16x16x32_bf16 v[84:87], v[170:173], v[202:205], v[84:87]
	v_mfma_f32_16x16x32_bf16 v[68:71], v[170:173], v[210:213], v[68:71]
	v_mfma_f32_16x16x32_bf16 v[64:67], v[178:181], v[210:213], v[64:67]
	v_mfma_f32_16x16x32_bf16 v[76:79], v[178:181], v[202:205], v[76:79]
	v_mfma_f32_16x16x32_bf16 v[92:95], v[178:181], v[194:197], v[92:95]
	v_mfma_f32_16x16x32_bf16 v[104:107], v[178:181], v[186:189], v[104:107]
	v_mfma_f32_16x16x32_bf16 v[108:111], v[174:177], v[190:193], v[108:111]
	v_mfma_f32_16x16x32_bf16 v[100:103], v[174:177], v[198:201], v[100:103]
	v_mfma_f32_16x16x32_bf16 v[84:87], v[174:177], v[206:209], v[84:87]
	v_mfma_f32_16x16x32_bf16 v[68:71], v[174:177], v[214:217], v[68:71]
	v_mfma_f32_16x16x32_bf16 v[64:67], v[182:185], v[214:217], v[64:67]
	v_mfma_f32_16x16x32_bf16 v[76:79], v[182:185], v[206:209], v[76:79]
	v_mfma_f32_16x16x32_bf16 v[92:95], v[182:185], v[198:201], v[92:95]
	v_mfma_f32_16x16x32_bf16 v[104:107], v[182:185], v[190:193], v[104:107]
	s_setprio 0
	s_barrier
; #define PG8_STAGE(bufoff, gbase, voff) do { _Pragma("unroll") for (int _i = 0; _i < 2; ++_i) \
;         __builtin_amdgcn_global_load_lds((const unsigned*)((const char*)(gbase) + (voff)[_i]), (LAS unsigned*)(lds + (bufoff) + ldsw + _i * 8192), 16, 0, 0); } while (0)
; #define PG8_LDA(dst, b, h) do { _Pragma("unroll") for (int m = 0; m < 4; ++m) _Pragma("unroll") for (int k = 0; k < 2; ++k) dst[m][k] = *(const LAS bf16x8*)(lds + PG8_SA(b, h) + aoff + m * 2048 + k * 1024); } while (0)
; #define PG8_MMA(ai, bj, At, Bt) do { __builtin_amdgcn_s_setprio(1); _Pragma("unroll") for (int m = 0; m < 4; ++m) _Pragma("unroll") for (int n = 0; n < 2; ++n) _Pragma("unroll") for (int k = 0; k < 2; ++k) \
;         acc[ai][bj][m][n] = __builtin_amdgcn_mfma_f32_16x16x32_bf16(Bt[n][k], At[m][k], acc[ai][bj][m][n], 0, 0, 0); __builtin_amdgcn_s_setprio(0); } while (0)
; #define PG8_WAIT_V(n) asm volatile("s_waitcnt vmcnt(" #n ")" ::: "memory")
; #define PG8_WAIT_L(n) asm volatile("s_waitcnt lgkmcnt(" #n ")" ::: "memory")
; #define PG8_BAR __builtin_amdgcn_s_barrier()
; #define PG8_SCHED __builtin_amdgcn_sched_barrier(0)
; template <class Epi>
; __device__ __forceinline__ void gemm_phase(LAS unsigned char* lds, const Gemm g, const StaticOrder& S, const Epi& E) {
;     ...
;             PG8_LDA(At, 1, 1); PG8_STAGE(PG8_SB(1, 0), b3, voffB); PG8_STAGE(PG8_SB(1, 1), b3 + hstepB, voffB); PG8_STAGE(PG8_SA(1, 0), a3, voffA);
;             PG8_WAIT_V(8); PG8_WAIT_L(0); PG8_BAR; PG8_MMA(1, 0, At, B0); PG8_MMA(1, 1, At, B1); PG8_BAR; PG8_SCHED;
;         }
;         if (wr == 0) PG8_BAR;
	s_add_i32 s30, s50, s52
	v_lshl_add_u64 v[218:219], v[218:219], 0, s[16:17]
	s_mov_b32 m0, s30
	ds_read_b128 v[186:189], v160 offset:49152
	ds_read_b128 v[190:193], v160 offset:50176
	ds_read_b128 v[194:197], v160 offset:51200
	ds_read_b128 v[198:201], v160 offset:52224
	ds_read_b128 v[202:205], v160 offset:53248
	ds_read_b128 v[206:209], v160 offset:54272
	ds_read_b128 v[210:213], v160 offset:55296
	ds_read_b128 v[214:217], v160 offset:56320
	global_load_lds_dwordx4 v[218:219], off
	s_add_i32 m0, s30, 0x2000
	s_add_u32 s30, s36, 0xb0080
	v_lshl_add_u64 v[218:219], v[220:221], 0, s[16:17]
	s_addc_u32 s31, s37, 0
	s_add_i32 s36, s51, s52
	global_load_lds_dwordx4 v[218:219], off
	v_lshl_add_u64 v[218:219], s[30:31], 0, v[132:133]
	s_mov_b32 m0, s36
	s_nop 0
	global_load_lds_dwordx4 v[218:219], off
	v_lshl_add_u64 v[218:219], s[30:31], 0, v[128:129]
	s_add_i32 m0, s36, 0x2000
	s_nop 0
	global_load_lds_dwordx4 v[218:219], off
	v_lshl_add_u64 v[218:219], v[222:223], 0, s[16:17]
	s_mov_b32 m0, s60
	s_nop 0
	global_load_lds_dwordx4 v[218:219], off
	v_lshl_add_u64 v[218:219], v[224:225], 0, s[16:17]
	s_mov_b32 m0, s61
	s_nop 0
	global_load_lds_dwordx4 v[218:219], off
	s_waitcnt vmcnt(8)
	s_waitcnt lgkmcnt(0)
	s_barrier
	s_setprio 1
	s_waitcnt lgkmcnt(0)
	v_mfma_f32_16x16x32_bf16 v[60:63], v[144:147], v[186:189], v[60:63]
	v_mfma_f32_16x16x32_bf16 v[48:51], v[144:147], v[194:197], v[48:51]
	v_mfma_f32_16x16x32_bf16 v[32:35], v[144:147], v[202:205], v[32:35]
	v_mfma_f32_16x16x32_bf16 v[16:19], v[144:147], v[210:213], v[16:19]
	v_mfma_f32_16x16x32_bf16 v[8:11], v[162:165], v[210:213], v[8:11]
	v_mfma_f32_16x16x32_bf16 v[24:27], v[162:165], v[202:205], v[24:27]
	v_mfma_f32_16x16x32_bf16 v[40:43], v[162:165], v[194:197], v[40:43]
	v_mfma_f32_16x16x32_bf16 v[56:59], v[162:165], v[186:189], v[56:59]
	v_mfma_f32_16x16x32_bf16 v[60:63], v[148:151], v[190:193], v[60:63]
	v_mfma_f32_16x16x32_bf16 v[48:51], v[148:151], v[198:201], v[48:51]
	v_mfma_f32_16x16x32_bf16 v[32:35], v[148:151], v[206:209], v[32:35]
	v_mfma_f32_16x16x32_bf16 v[16:19], v[148:151], v[214:217], v[16:19]
	v_mfma_f32_16x16x32_bf16 v[8:11], v[166:169], v[214:217], v[8:11]
	v_mfma_f32_16x16x32_bf16 v[24:27], v[166:169], v[206:209], v[24:27]
	v_mfma_f32_16x16x32_bf16 v[40:43], v[166:169], v[198:201], v[40:43]
	v_mfma_f32_16x16x32_bf16 v[56:59], v[166:169], v[190:193], v[56:59]
	s_setprio 0
	s_setprio 1
	v_mfma_f32_16x16x32_bf16 v[52:55], v[170:173], v[186:189], v[52:55]
	v_mfma_f32_16x16x32_bf16 v[36:39], v[170:173], v[194:197], v[36:39]
	v_mfma_f32_16x16x32_bf16 v[20:23], v[170:173], v[202:205], v[20:23]
	v_mfma_f32_16x16x32_bf16 v[4:7], v[170:173], v[210:213], v[4:7]
	v_mfma_f32_16x16x32_bf16 v[0:3], v[178:181], v[210:213], v[0:3]
	v_mfma_f32_16x16x32_bf16 v[12:15], v[178:181], v[202:205], v[12:15]
	v_mfma_f32_16x16x32_bf16 v[28:31], v[178:181], v[194:197], v[28:31]
	v_mfma_f32_16x16x32_bf16 v[44:47], v[178:181], v[186:189], v[44:47]
	v_mfma_f32_16x16x32_bf16 v[52:55], v[174:177], v[190:193], v[52:55]
	v_mfma_f32_16x16x32_bf16 v[36:39], v[174:177], v[198:201], v[36:39]
	v_mfma_f32_16x16x32_bf16 v[20:23], v[174:177], v[206:209], v[20:23]
	v_mfma_f32_16x16x32_bf16 v[4:7], v[174:177], v[214:217], v[4:7]
	v_mfma_f32_16x16x32_bf16 v[0:3], v[182:185], v[214:217], v[0:3]
	v_mfma_f32_16x16x32_bf16 v[12:15], v[182:185], v[206:209], v[12:15]
	v_mfma_f32_16x16x32_bf16 v[28:31], v[182:185], v[198:201], v[28:31]
	v_mfma_f32_16x16x32_bf16 v[44:47], v[182:185], v[190:193], v[44:47]
	s_setprio 0
	s_barrier
	s_add_i32 s77, s77, 2
	s_add_u32 s71, s71, 0x100
	s_addc_u32 s76, s76, 0
	s_cmp_gt_u32 s77, 41
	s_mov_b64 s[30:31], s[34:35]
	s_cbranch_scc0 .LBB0_767
	s_and_b64 vcc, exec, s[18:19]
	s_cbranch_vccz .LBB0_770
	s_barrier

; #define PG8_STAGE(bufoff, gbase, voff) do { _Pragma("unroll") for (int _i = 0; _i < 2; ++_i) \
;         __builtin_amdgcn_global_load_lds((const unsigned*)((const char*)(gbase) + (voff)[_i]), (LAS unsigned*)(lds + (bufoff) + ldsw + _i * 8192), 16, 0, 0); } while (0)
; #define PG8_LDA(dst, b, h) do { _Pragma("unroll") for (int m = 0; m < 4; ++m) _Pragma("unroll") for (int k = 0; k < 2; ++k) dst[m][k] = *(const LAS bf16x8*)(lds + PG8_SA(b, h) + aoff + m * 2048 + k * 1024); } while (0)
; #define PG8_LDB(dst, b, h) do { _Pragma("unroll") for (int n = 0; n < 2; ++n) _Pragma("unroll") for (int k = 0; k < 2; ++k) dst[n][k] = *(const LAS bf16x8*)(lds + PG8_SB(b, h) + boff + n * 2048 + k * 1024); } while (0)
; #define PG8_MMA(ai, bj, At, Bt) do { __builtin_amdgcn_s_setprio(1); _Pragma("unroll") for (int m = 0; m < 4; ++m) _Pragma("unroll") for (int n = 0; n < 2; ++n) _Pragma("unroll") for (int k = 0; k < 2; ++k) \
;         acc[ai][bj][m][n] = __builtin_amdgcn_mfma_f32_16x16x32_bf16(Bt[n][k], At[m][k], acc[ai][bj][m][n], 0, 0, 0); __builtin_amdgcn_s_setprio(0); } while (0)
; #define PG8_WAIT_V(n) asm volatile("s_waitcnt vmcnt(" #n ")" ::: "memory")
; #define PG8_WAIT_L(n) asm volatile("s_waitcnt lgkmcnt(" #n ")" ::: "memory")
; #define PG8_BAR __builtin_amdgcn_s_barrier()
; #define PG8_SCHED __builtin_amdgcn_sched_barrier(0)
; template <class Epi>
; __device__ __forceinline__ void gemm_phase(LAS unsigned char* lds, const Gemm g, const StaticOrder& S, const Epi& E) {
;     ...
;             const bool last = (t == nt - 2);
;             const char* a1 = cA + (unsigned)(t + 1) * kstep;
;             const char* a2 = last ? nA : cA + (unsigned)(t + 2) * kstep; const char* b2 = last ? nB : cB + (unsigned)(t + 2) * kstep;
;             const char* a3 = a2 + kstep; const char* b3 = b2 + kstep;
;             PG8_LDB(B0, 0, 0); PG8_LDB(B1, 0, 1); PG8_SCHED; PG8_LDA(At, 0, 0); PG8_STAGE(PG8_SA(1, 1), a1 + hstepA, voffA);
;             PG8_WAIT_V(8); PG8_WAIT_L(0); PG8_BAR; PG8_MMA(0, 0, At, B0); PG8_MMA(0, 1, At, B1); PG8_BAR; PG8_SCHED;
;             PG8_LDA(At, 0, 1); PG8_STAGE(PG8_SB(0, 0), b2, voffB); PG8_STAGE(PG8_SB(0, 1), b2 + hstepB, voffB); PG8_STAGE(PG8_SA(0, 0), a2, voffA);
;             PG8_WAIT_V(8); PG8_WAIT_L(0); PG8_BAR; PG8_MMA(1, 0, At, B0); PG8_MMA(1, 1, At, B1); PG8_BAR; PG8_SCHED;
.LBB0_876:
	ds_read_b128 v[156:159], v149
	ds_read_b128 v[160:163], v149 offset:1024
	ds_read_b128 v[164:167], v149 offset:2048
	ds_read_b128 v[168:171], v149 offset:3072
	ds_read_b128 v[172:175], v150
	ds_read_b128 v[176:179], v150 offset:1024
	ds_read_b128 v[180:183], v150 offset:2048
	ds_read_b128 v[184:187], v150 offset:3072
	s_add_u32 s36, s34, 0xfffc0080
	s_addc_u32 s37, s35, -1
	s_cmp_eq_u32 s69, 12
	s_cselect_b32 s39, s25, s37
	s_cselect_b32 s38, s64, s36
	s_cselect_b32 s37, s23, s67
	s_cselect_b32 s36, s65, s66
	v_lshl_add_u64 v[144:145], s[34:35], 0, v[138:139]
	s_add_i32 m0, s31, 0xc000
	ds_read_b128 v[188:191], v151
	ds_read_b128 v[192:195], v151 offset:1024
	ds_read_b128 v[196:199], v151 offset:2048
	ds_read_b128 v[200:203], v151 offset:3072
	ds_read_b128 v[204:207], v151 offset:4096
	ds_read_b128 v[208:211], v151 offset:5120
	ds_read_b128 v[212:215], v151 offset:6144
	ds_read_b128 v[216:219], v151 offset:7168
	global_load_lds_dwordx4 v[144:145], off
	v_lshl_add_u64 v[144:145], s[34:35], 0, v[136:137]
	s_add_i32 m0, s31, 0xe000
	s_nop 0
	global_load_lds_dwordx4 v[144:145], off
	s_waitcnt vmcnt(8)
	s_waitcnt lgkmcnt(0)
	s_barrier
	s_setprio 1
	s_waitcnt lgkmcnt(0)
	v_mfma_f32_16x16x32_bf16 v[116:119], v[156:159], v[188:191], v[116:119]
	v_mfma_f32_16x16x32_bf16 v[108:111], v[156:159], v[196:199], v[108:111]
	v_mfma_f32_16x16x32_bf16 v[92:95], v[156:159], v[204:207], v[92:95]
	v_mfma_f32_16x16x32_bf16 v[76:79], v[156:159], v[212:215], v[76:79]
	v_mfma_f32_16x16x32_bf16 v[68:71], v[164:167], v[212:215], v[68:71]
	v_mfma_f32_16x16x32_bf16 v[84:87], v[164:167], v[204:207], v[84:87]
	v_mfma_f32_16x16x32_bf16 v[100:103], v[164:167], v[196:199], v[100:103]
	v_mfma_f32_16x16x32_bf16 v[112:115], v[164:167], v[188:191], v[112:115]
	v_mfma_f32_16x16x32_bf16 v[116:119], v[160:163], v[192:195], v[116:119]
	v_mfma_f32_16x16x32_bf16 v[108:111], v[160:163], v[200:203], v[108:111]
	v_mfma_f32_16x16x32_bf16 v[92:95], v[160:163], v[208:211], v[92:95]
	v_mfma_f32_16x16x32_bf16 v[76:79], v[160:163], v[216:219], v[76:79]
	v_mfma_f32_16x16x32_bf16 v[68:71], v[168:171], v[216:219], v[68:71]
	v_mfma_f32_16x16x32_bf16 v[84:87], v[168:171], v[208:211], v[84:87]
	v_mfma_f32_16x16x32_bf16 v[100:103], v[168:171], v[200:203], v[100:103]
	v_mfma_f32_16x16x32_bf16 v[112:115], v[168:171], v[192:195], v[112:115]
	s_setprio 0
	s_setprio 1
	v_mfma_f32_16x16x32_bf16 v[124:127], v[172:175], v[188:191], v[124:127]
	v_mfma_f32_16x16x32_bf16 v[104:107], v[172:175], v[196:199], v[104:107]
	v_mfma_f32_16x16x32_bf16 v[88:91], v[172:175], v[204:207], v[88:91]
	v_mfma_f32_16x16x32_bf16 v[72:75], v[172:175], v[212:215], v[72:75]
	v_mfma_f32_16x16x32_bf16 v[64:67], v[180:183], v[212:215], v[64:67]
	v_mfma_f32_16x16x32_bf16 v[80:83], v[180:183], v[204:207], v[80:83]
	v_mfma_f32_16x16x32_bf16 v[96:99], v[180:183], v[196:199], v[96:99]
	v_mfma_f32_16x16x32_bf16 v[120:123], v[180:183], v[188:191], v[120:123]
	v_mfma_f32_16x16x32_bf16 v[124:127], v[176:179], v[192:195], v[124:127]
	v_mfma_f32_16x16x32_bf16 v[104:107], v[176:179], v[200:203], v[104:107]
	v_mfma_f32_16x16x32_bf16 v[88:91], v[176:179], v[208:211], v[88:91]
	v_mfma_f32_16x16x32_bf16 v[72:75], v[176:179], v[216:219], v[72:75]
	v_mfma_f32_16x16x32_bf16 v[64:67], v[184:187], v[216:219], v[64:67]
	v_mfma_f32_16x16x32_bf16 v[80:83], v[184:187], v[208:211], v[80:83]
	v_mfma_f32_16x16x32_bf16 v[96:99], v[184:187], v[200:203], v[96:99]
	v_mfma_f32_16x16x32_bf16 v[120:123], v[184:187], v[192:195], v[120:123]
	s_setprio 0
	s_barrier
	s_add_i32 s50, s61, s48
	v_lshl_add_u64 v[144:145], s[36:37], 0, v[132:133]
	s_mov_b32 m0, s50
	ds_read_b128 v[188:191], v151 offset:16384
	ds_read_b128 v[192:195], v151 offset:17408
	ds_read_b128 v[196:199], v151 offset:18432
	ds_read_b128 v[200:203], v151 offset:19456
	ds_read_b128 v[204:207], v151 offset:20480
	ds_read_b128 v[208:211], v151 offset:21504
	ds_read_b128 v[212:215], v151 offset:22528
	ds_read_b128 v[216:219], v151 offset:23552
	global_load_lds_dwordx4 v[144:145], off
	s_add_i32 m0, s50, 0x2000
	s_add_u32 s50, s36, 0x40000
	v_lshl_add_u64 v[220:221], s[36:37], 0, v[128:129]
	s_addc_u32 s51, s37, 0
	s_add_i32 s71, s62, s48
	global_load_lds_dwordx4 v[220:221], off
	v_lshl_add_u64 v[222:223], s[50:51], 0, v[132:133]
	s_mov_b32 m0, s71
	v_lshl_add_u64 v[224:225], s[38:39], 0, v[130:131]
	global_load_lds_dwordx4 v[222:223], off
	v_lshl_add_u64 v[222:223], s[50:51], 0, v[128:129]
	s_add_i32 m0, s71, 0x2000
	s_nop 0
	global_load_lds_dwordx4 v[222:223], off
	v_lshl_add_u64 v[222:223], s[38:39], 0, v[134:135]
	s_mov_b32 m0, s31
	s_nop 0
	global_load_lds_dwordx4 v[222:223], off
	s_mov_b32 m0, s53
	s_nop 0
	global_load_lds_dwordx4 v[224:225], off
	s_waitcnt vmcnt(8)
	s_waitcnt lgkmcnt(0)
	s_barrier
; #define PG8_STAGE(bufoff, gbase, voff) do { _Pragma("unroll") for (int _i = 0; _i < 2; ++_i) \
;         __builtin_amdgcn_global_load_lds((const unsigned*)((const char*)(gbase) + (voff)[_i]), (LAS unsigned*)(lds + (bufoff) + ldsw + _i * 8192), 16, 0, 0); } while (0)
; #define PG8_LDA(dst, b, h) do { _Pragma("unroll") for (int m = 0; m < 4; ++m) _Pragma("unroll") for (int k = 0; k < 2; ++k) dst[m][k] = *(const LAS bf16x8*)(lds + PG8_SA(b, h) + aoff + m * 2048 + k * 1024); } while (0)
; #define PG8_LDB(dst, b, h) do { _Pragma("unroll") for (int n = 0; n < 2; ++n) _Pragma("unroll") for (int k = 0; k < 2; ++k) dst[n][k] = *(const LAS bf16x8*)(lds + PG8_SB(b, h) + boff + n * 2048 + k * 1024); } while (0)
; #define PG8_MMA(ai, bj, At, Bt) do { __builtin_amdgcn_s_setprio(1); _Pragma("unroll") for (int m = 0; m < 4; ++m) _Pragma("unroll") for (int n = 0; n < 2; ++n) _Pragma("unroll") for (int k = 0; k < 2; ++k) \
;         acc[ai][bj][m][n] = __builtin_amdgcn_mfma_f32_16x16x32_bf16(Bt[n][k], At[m][k], acc[ai][bj][m][n], 0, 0, 0); __builtin_amdgcn_s_setprio(0); } while (0)
; #define PG8_WAIT_V(n) asm volatile("s_waitcnt vmcnt(" #n ")" ::: "memory")
; #define PG8_WAIT_L(n) asm volatile("s_waitcnt lgkmcnt(" #n ")" ::: "memory")
; #define PG8_BAR __builtin_amdgcn_s_barrier()
; #define PG8_SCHED __builtin_amdgcn_sched_barrier(0)
; template <class Epi>
; __device__ __forceinline__ void gemm_phase(LAS unsigned char* lds, const Gemm g, const StaticOrder& S, const Epi& E) {
;     ...
;             PG8_WAIT_V(8); PG8_WAIT_L(0); PG8_BAR; PG8_MMA(1, 0, At, B0); PG8_MMA(1, 1, At, B1); PG8_BAR; PG8_SCHED;
;             PG8_LDB(B0, 1, 0); PG8_LDB(B1, 1, 1); PG8_SCHED; PG8_LDA(At, 1, 0); PG8_STAGE(PG8_SA(0, 1), a2 + hstepA, voffA);
;             PG8_WAIT_V(8); PG8_WAIT_L(0); PG8_BAR; PG8_MMA(0, 0, At, B0); PG8_MMA(0, 1, At, B1); PG8_BAR; PG8_SCHED;
	s_setprio 1
	s_waitcnt lgkmcnt(0)
	v_mfma_f32_16x16x32_bf16 v[60:63], v[156:159], v[188:191], v[60:63]
	v_mfma_f32_16x16x32_bf16 v[44:47], v[156:159], v[196:199], v[44:47]
	v_mfma_f32_16x16x32_bf16 v[28:31], v[156:159], v[204:207], v[28:31]
	v_mfma_f32_16x16x32_bf16 v[12:15], v[156:159], v[212:215], v[12:15]
	v_mfma_f32_16x16x32_bf16 v[4:7], v[164:167], v[212:215], v[4:7]
	v_mfma_f32_16x16x32_bf16 v[20:23], v[164:167], v[204:207], v[20:23]
	v_mfma_f32_16x16x32_bf16 v[36:39], v[164:167], v[196:199], v[36:39]
	v_mfma_f32_16x16x32_bf16 v[52:55], v[164:167], v[188:191], v[52:55]
	v_mfma_f32_16x16x32_bf16 v[60:63], v[160:163], v[192:195], v[60:63]
	v_mfma_f32_16x16x32_bf16 v[44:47], v[160:163], v[200:203], v[44:47]
	v_mfma_f32_16x16x32_bf16 v[28:31], v[160:163], v[208:211], v[28:31]
	v_mfma_f32_16x16x32_bf16 v[12:15], v[160:163], v[216:219], v[12:15]
	v_mfma_f32_16x16x32_bf16 v[4:7], v[168:171], v[216:219], v[4:7]
	v_mfma_f32_16x16x32_bf16 v[20:23], v[168:171], v[208:211], v[20:23]
	v_mfma_f32_16x16x32_bf16 v[36:39], v[168:171], v[200:203], v[36:39]
	v_mfma_f32_16x16x32_bf16 v[52:55], v[168:171], v[192:195], v[52:55]
	s_setprio 0
	s_setprio 1
	v_mfma_f32_16x16x32_bf16 v[56:59], v[172:175], v[188:191], v[56:59]
	v_mfma_f32_16x16x32_bf16 v[40:43], v[172:175], v[196:199], v[40:43]
	v_mfma_f32_16x16x32_bf16 v[24:27], v[172:175], v[204:207], v[24:27]
	v_mfma_f32_16x16x32_bf16 v[8:11], v[172:175], v[212:215], v[8:11]
	v_mfma_f32_16x16x32_bf16 v[0:3], v[180:183], v[212:215], v[0:3]
	v_mfma_f32_16x16x32_bf16 v[16:19], v[180:183], v[204:207], v[16:19]
	v_mfma_f32_16x16x32_bf16 v[32:35], v[180:183], v[196:199], v[32:35]
	v_mfma_f32_16x16x32_bf16 v[48:51], v[180:183], v[188:191], v[48:51]
	v_mfma_f32_16x16x32_bf16 v[56:59], v[176:179], v[192:195], v[56:59]
	v_mfma_f32_16x16x32_bf16 v[40:43], v[176:179], v[200:203], v[40:43]
	v_mfma_f32_16x16x32_bf16 v[24:27], v[176:179], v[208:211], v[24:27]
	v_mfma_f32_16x16x32_bf16 v[8:11], v[176:179], v[216:219], v[8:11]
	v_mfma_f32_16x16x32_bf16 v[0:3], v[184:187], v[216:219], v[0:3]
	v_mfma_f32_16x16x32_bf16 v[16:19], v[184:187], v[208:211], v[16:19]
	v_mfma_f32_16x16x32_bf16 v[32:35], v[184:187], v[200:203], v[32:35]
	v_mfma_f32_16x16x32_bf16 v[48:51], v[184:187], v[192:195], v[48:51]
	s_setprio 0
	s_barrier
	s_add_i32 s50, 0, 0x18000
	s_add_i32 s51, 0, 0x1c000
	v_add_u32_e32 v168, s50, v147
	v_add_u32_e32 v184, s51, v147
	ds_read_b128 v[156:159], v168
	ds_read_b128 v[160:163], v168 offset:1024
	ds_read_b128 v[164:167], v168 offset:2048
	ds_read_b128 v[168:171], v168 offset:3072
	ds_read_b128 v[172:175], v184
	ds_read_b128 v[176:179], v184 offset:1024
	ds_read_b128 v[180:183], v184 offset:2048
	ds_read_b128 v[184:187], v184 offset:3072
	s_add_u32 s38, s38, 0x40000
	s_addc_u32 s39, s39, 0
	s_mov_b32 m0, s54
	v_lshl_add_u64 v[226:227], s[38:39], 0, v[134:135]
	ds_read_b128 v[188:191], v151 offset:32768
	ds_read_b128 v[192:195], v151 offset:33792
	ds_read_b128 v[196:199], v151 offset:34816
	ds_read_b128 v[200:203], v151 offset:35840
	ds_read_b128 v[204:207], v151 offset:36864
	ds_read_b128 v[208:211], v151 offset:37888
	ds_read_b128 v[212:215], v151 offset:38912
	ds_read_b128 v[216:219], v151 offset:39936
	global_load_lds_dwordx4 v[226:227], off
	v_lshl_add_u64 v[226:227], s[38:39], 0, v[130:131]
	s_mov_b32 m0, s55
	s_nop 0
	global_load_lds_dwordx4 v[226:227], off
	s_waitcnt vmcnt(8)
	s_waitcnt lgkmcnt(0)
	s_barrier
	s_setprio 1
	s_waitcnt lgkmcnt(0)
	v_mfma_f32_16x16x32_bf16 v[116:119], v[156:159], v[188:191], v[116:119]
	v_mfma_f32_16x16x32_bf16 v[108:111], v[156:159], v[196:199], v[108:111]
	v_mfma_f32_16x16x32_bf16 v[92:95], v[156:159], v[204:207], v[92:95]
	v_mfma_f32_16x16x32_bf16 v[76:79], v[156:159], v[212:215], v[76:79]
	v_mfma_f32_16x16x32_bf16 v[68:71], v[164:167], v[212:215], v[68:71]
	v_mfma_f32_16x16x32_bf16 v[84:87], v[164:167], v[204:207], v[84:87]
	v_mfma_f32_16x16x32_bf16 v[100:103], v[164:167], v[196:199], v[100:103]
	v_mfma_f32_16x16x32_bf16 v[112:115], v[164:167], v[188:191], v[112:115]
	v_mfma_f32_16x16x32_bf16 v[116:119], v[160:163], v[192:195], v[116:119]
	v_mfma_f32_16x16x32_bf16 v[108:111], v[160:163], v[200:203], v[108:111]
	v_mfma_f32_16x16x32_bf16 v[92:95], v[160:163], v[208:211], v[92:95]
	v_mfma_f32_16x16x32_bf16 v[76:79], v[160:163], v[216:219], v[76:79]
	v_mfma_f32_16x16x32_bf16 v[68:71], v[168:171], v[216:219], v[68:71]
	v_mfma_f32_16x16x32_bf16 v[84:87], v[168:171], v[208:211], v[84:87]
	v_mfma_f32_16x16x32_bf16 v[100:103], v[168:171], v[200:203], v[100:103]
	v_mfma_f32_16x16x32_bf16 v[112:115], v[168:171], v[192:195], v[112:115]
	s_setprio 0
	s_setprio 1
	v_mfma_f32_16x16x32_bf16 v[124:127], v[172:175], v[188:191], v[124:127]
	v_mfma_f32_16x16x32_bf16 v[104:107], v[172:175], v[196:199], v[104:107]
	v_mfma_f32_16x16x32_bf16 v[88:91], v[172:175], v[204:207], v[88:91]
	v_mfma_f32_16x16x32_bf16 v[72:75], v[172:175], v[212:215], v[72:75]
	v_mfma_f32_16x16x32_bf16 v[64:67], v[180:183], v[212:215], v[64:67]
	v_mfma_f32_16x16x32_bf16 v[80:83], v[180:183], v[204:207], v[80:83]
	v_mfma_f32_16x16x32_bf16 v[96:99], v[180:183], v[196:199], v[96:99]
	v_mfma_f32_16x16x32_bf16 v[120:123], v[180:183], v[188:191], v[120:123]
	v_mfma_f32_16x16x32_bf16 v[124:127], v[176:179], v[192:195], v[124:127]
	v_mfma_f32_16x16x32_bf16 v[104:107], v[176:179], v[200:203], v[104:107]
	v_mfma_f32_16x16x32_bf16 v[88:91], v[176:179], v[208:211], v[88:91]
	v_mfma_f32_16x16x32_bf16 v[72:75], v[176:179], v[216:219], v[72:75]
	v_mfma_f32_16x16x32_bf16 v[64:67], v[184:187], v[216:219], v[64:67]
	v_mfma_f32_16x16x32_bf16 v[80:83], v[184:187], v[208:211], v[80:83]
	v_mfma_f32_16x16x32_bf16 v[96:99], v[184:187], v[200:203], v[96:99]
	v_mfma_f32_16x16x32_bf16 v[120:123], v[184:187], v[192:195], v[120:123]
	s_setprio 0
	s_barrier
; #define PG8_STAGE(bufoff, gbase, voff) do { _Pragma("unroll") for (int _i = 0; _i < 2; ++_i) \
;         __builtin_amdgcn_global_load_lds((const unsigned*)((const char*)(gbase) + (voff)[_i]), (LAS unsigned*)(lds + (bufoff) + ldsw + _i * 8192), 16, 0, 0); } while (0)
; #define PG8_LDA(dst, b, h) do { _Pragma("unroll") for (int m = 0; m < 4; ++m) _Pragma("unroll") for (int k = 0; k < 2; ++k) dst[m][k] = *(const LAS bf16x8*)(lds + PG8_SA(b, h) + aoff + m * 2048 + k * 1024); } while (0)
; #define PG8_MMA(ai, bj, At, Bt) do { __builtin_amdgcn_s_setprio(1); _Pragma("unroll") for (int m = 0; m < 4; ++m) _Pragma("unroll") for (int n = 0; n < 2; ++n) _Pragma("unroll") for (int k = 0; k < 2; ++k) \
;         acc[ai][bj][m][n] = __builtin_amdgcn_mfma_f32_16x16x32_bf16(Bt[n][k], At[m][k], acc[ai][bj][m][n], 0, 0, 0); __builtin_amdgcn_s_setprio(0); } while (0)
; #define PG8_WAIT_V(n) asm volatile("s_waitcnt vmcnt(" #n ")" ::: "memory")
; #define PG8_WAIT_L(n) asm volatile("s_waitcnt lgkmcnt(" #n ")" ::: "memory")
; #define PG8_BAR __builtin_amdgcn_s_barrier()
; #define PG8_SCHED __builtin_amdgcn_sched_barrier(0)
; template <class Epi>
; __device__ __forceinline__ void gemm_phase(LAS unsigned char* lds, const Gemm g, const StaticOrder& S, const Epi& E) {
;     ...
;             PG8_LDA(At, 1, 1); PG8_STAGE(PG8_SB(1, 0), b3, voffB); PG8_STAGE(PG8_SB(1, 1), b3 + hstepB, voffB); PG8_STAGE(PG8_SA(1, 0), a3, voffA);
;             PG8_WAIT_V(8); PG8_WAIT_L(0); PG8_BAR; PG8_MMA(1, 0, At, B0); PG8_MMA(1, 1, At, B1); PG8_BAR; PG8_SCHED;
;         }
;         if (wr == 0) PG8_BAR;
	s_add_i32 s38, s50, s48
	v_lshl_add_u64 v[144:145], v[144:145], 0, s[18:19]
	s_mov_b32 m0, s38
	ds_read_b128 v[188:191], v151 offset:49152
	ds_read_b128 v[192:195], v151 offset:50176
	ds_read_b128 v[196:199], v151 offset:51200
	ds_read_b128 v[200:203], v151 offset:52224
	ds_read_b128 v[204:207], v151 offset:53248
	ds_read_b128 v[208:211], v151 offset:54272
	ds_read_b128 v[212:215], v151 offset:55296
	ds_read_b128 v[216:219], v151 offset:56320
	global_load_lds_dwordx4 v[144:145], off
	s_add_i32 m0, s38, 0x2000
	s_add_u32 s36, s36, 0x40080
	v_lshl_add_u64 v[144:145], v[220:221], 0, s[18:19]
	s_addc_u32 s37, s37, 0
	s_add_i32 s38, s51, s48
	global_load_lds_dwordx4 v[144:145], off
	v_lshl_add_u64 v[144:145], s[36:37], 0, v[132:133]
	s_mov_b32 m0, s38
	s_nop 0
	global_load_lds_dwordx4 v[144:145], off
	v_lshl_add_u64 v[144:145], s[36:37], 0, v[128:129]
	s_add_i32 m0, s38, 0x2000
	s_nop 0
	global_load_lds_dwordx4 v[144:145], off
	v_lshl_add_u64 v[144:145], v[222:223], 0, s[18:19]
	s_mov_b32 m0, s57
	s_nop 0
	global_load_lds_dwordx4 v[144:145], off
	v_lshl_add_u64 v[144:145], v[224:225], 0, s[18:19]
	s_mov_b32 m0, s58
	s_nop 0
	global_load_lds_dwordx4 v[144:145], off
	s_waitcnt vmcnt(8)
	s_waitcnt lgkmcnt(0)
	s_barrier
	s_setprio 1
	s_waitcnt lgkmcnt(0)
	v_mfma_f32_16x16x32_bf16 v[60:63], v[156:159], v[188:191], v[60:63]
	v_mfma_f32_16x16x32_bf16 v[44:47], v[156:159], v[196:199], v[44:47]
	v_mfma_f32_16x16x32_bf16 v[28:31], v[156:159], v[204:207], v[28:31]
	v_mfma_f32_16x16x32_bf16 v[12:15], v[156:159], v[212:215], v[12:15]
	v_mfma_f32_16x16x32_bf16 v[4:7], v[164:167], v[212:215], v[4:7]
	v_mfma_f32_16x16x32_bf16 v[20:23], v[164:167], v[204:207], v[20:23]
	v_mfma_f32_16x16x32_bf16 v[36:39], v[164:167], v[196:199], v[36:39]
	v_mfma_f32_16x16x32_bf16 v[52:55], v[164:167], v[188:191], v[52:55]
	v_mfma_f32_16x16x32_bf16 v[60:63], v[160:163], v[192:195], v[60:63]
	v_mfma_f32_16x16x32_bf16 v[44:47], v[160:163], v[200:203], v[44:47]
	v_mfma_f32_16x16x32_bf16 v[28:31], v[160:163], v[208:211], v[28:31]
	v_mfma_f32_16x16x32_bf16 v[12:15], v[160:163], v[216:219], v[12:15]
	v_mfma_f32_16x16x32_bf16 v[4:7], v[168:171], v[216:219], v[4:7]
	v_mfma_f32_16x16x32_bf16 v[20:23], v[168:171], v[208:211], v[20:23]
	v_mfma_f32_16x16x32_bf16 v[36:39], v[168:171], v[200:203], v[36:39]
	v_mfma_f32_16x16x32_bf16 v[52:55], v[168:171], v[192:195], v[52:55]
	s_setprio 0
	s_setprio 1
	v_mfma_f32_16x16x32_bf16 v[56:59], v[172:175], v[188:191], v[56:59]
	v_mfma_f32_16x16x32_bf16 v[40:43], v[172:175], v[196:199], v[40:43]
	v_mfma_f32_16x16x32_bf16 v[24:27], v[172:175], v[204:207], v[24:27]
	v_mfma_f32_16x16x32_bf16 v[8:11], v[172:175], v[212:215], v[8:11]
	v_mfma_f32_16x16x32_bf16 v[0:3], v[180:183], v[212:215], v[0:3]
	v_mfma_f32_16x16x32_bf16 v[16:19], v[180:183], v[204:207], v[16:19]
	v_mfma_f32_16x16x32_bf16 v[32:35], v[180:183], v[196:199], v[32:35]
	v_mfma_f32_16x16x32_bf16 v[48:51], v[180:183], v[188:191], v[48:51]
	v_mfma_f32_16x16x32_bf16 v[56:59], v[176:179], v[192:195], v[56:59]
	v_mfma_f32_16x16x32_bf16 v[40:43], v[176:179], v[200:203], v[40:43]
	v_mfma_f32_16x16x32_bf16 v[24:27], v[176:179], v[208:211], v[24:27]
	v_mfma_f32_16x16x32_bf16 v[8:11], v[176:179], v[216:219], v[8:11]
	v_mfma_f32_16x16x32_bf16 v[0:3], v[184:187], v[216:219], v[0:3]
	v_mfma_f32_16x16x32_bf16 v[16:19], v[184:187], v[208:211], v[16:19]
	v_mfma_f32_16x16x32_bf16 v[32:35], v[184:187], v[200:203], v[32:35]
	v_mfma_f32_16x16x32_bf16 v[48:51], v[184:187], v[192:195], v[48:51]
	s_setprio 0
	s_barrier
	s_add_i32 s69, s69, 2
	s_add_u32 s66, s66, 0x100
	s_addc_u32 s67, s67, 0
	s_add_u32 s34, s34, 0x100
	s_addc_u32 s35, s35, 0
	s_cmp_gt_u32 s69, 13
	s_cbranch_scc0 .LBB0_876
	s_and_b64 vcc, exec, s[20:21]
	s_cbranch_vccz .LBB0_879
	s_barrier

; #define PG8_STAGE(bufoff, gbase, voff) do { _Pragma("unroll") for (int _i = 0; _i < 2; ++_i) \
;         __builtin_amdgcn_global_load_lds((const unsigned*)((const char*)(gbase) + (voff)[_i]), (LAS unsigned*)(lds + (bufoff) + ldsw + _i * 8192), 16, 0, 0); } while (0)
; #define PG8_LDA(dst, b, h) do { _Pragma("unroll") for (int m = 0; m < 4; ++m) _Pragma("unroll") for (int k = 0; k < 2; ++k) dst[m][k] = *(const LAS bf16x8*)(lds + PG8_SA(b, h) + aoff + m * 2048 + k * 1024); } while (0)
; #define PG8_LDB(dst, b, h) do { _Pragma("unroll") for (int n = 0; n < 2; ++n) _Pragma("unroll") for (int k = 0; k < 2; ++k) dst[n][k] = *(const LAS bf16x8*)(lds + PG8_SB(b, h) + boff + n * 2048 + k * 1024); } while (0)
; #define PG8_MMA(ai, bj, At, Bt) do { __builtin_amdgcn_s_setprio(1); _Pragma("unroll") for (int m = 0; m < 4; ++m) _Pragma("unroll") for (int n = 0; n < 2; ++n) _Pragma("unroll") for (int k = 0; k < 2; ++k) \
;         acc[ai][bj][m][n] = __builtin_amdgcn_mfma_f32_16x16x32_bf16(Bt[n][k], At[m][k], acc[ai][bj][m][n], 0, 0, 0); __builtin_amdgcn_s_setprio(0); } while (0)
; #define PG8_WAIT_V(n) asm volatile("s_waitcnt vmcnt(" #n ")" ::: "memory")
; #define PG8_WAIT_L(n) asm volatile("s_waitcnt lgkmcnt(" #n ")" ::: "memory")
; #define PG8_BAR __builtin_amdgcn_s_barrier()
; #define PG8_SCHED __builtin_amdgcn_sched_barrier(0)
; template <class Epi>
; __device__ __forceinline__ void gemm_phase(LAS unsigned char* lds, const Gemm g, const StaticOrder& S, const Epi& E) {
;     ...
;             const bool last = (t == nt - 2);
;             const char* a1 = cA + (unsigned)(t + 1) * kstep;
;             const char* a2 = last ? nA : cA + (unsigned)(t + 2) * kstep; const char* b2 = last ? nB : cB + (unsigned)(t + 2) * kstep;
;             const char* a3 = a2 + kstep; const char* b3 = b2 + kstep;
;             PG8_LDB(B0, 0, 0); PG8_LDB(B1, 0, 1); PG8_SCHED; PG8_LDA(At, 0, 0); PG8_STAGE(PG8_SA(1, 1), a1 + hstepA, voffA);
;             PG8_WAIT_V(8); PG8_WAIT_L(0); PG8_BAR; PG8_MMA(0, 0, At, B0); PG8_MMA(0, 1, At, B1); PG8_BAR; PG8_SCHED;
;             PG8_LDA(At, 0, 1); PG8_STAGE(PG8_SB(0, 0), b2, voffB); PG8_STAGE(PG8_SB(0, 1), b2 + hstepB, voffB); PG8_STAGE(PG8_SA(0, 0), a2, voffA);
;             PG8_WAIT_V(8); PG8_WAIT_L(0); PG8_BAR; PG8_MMA(1, 0, At, B0); PG8_MMA(1, 1, At, B1); PG8_BAR; PG8_SCHED;
.LBB0_942:
	ds_read_b128 v[128:131], v192
	ds_read_b128 v[132:135], v192 offset:1024
	ds_read_b128 v[136:139], v192 offset:2048
	ds_read_b128 v[140:143], v192 offset:3072
	ds_read_b128 v[144:147], v193
	ds_read_b128 v[148:151], v193 offset:1024
	ds_read_b128 v[172:175], v193 offset:2048
	ds_read_b128 v[176:179], v193 offset:3072
	s_add_u32 s34, s30, 0x100
	s_addc_u32 s35, s31, 0
	s_cmp_eq_u32 s71, 40
	s_cselect_b32 s39, s13, s35
	s_cselect_b32 s38, s12, s34
	s_cselect_b32 s37, s29, s69
	s_cselect_b32 s36, s28, s67
	v_lshl_add_u64 v[188:189], s[30:31], 0, v[166:167]
	s_add_i32 m0, s49, 0xc000
	ds_read_b128 v[180:183], v194
	ds_read_b128 v[184:187], v194 offset:1024
	ds_read_b128 v[196:199], v194 offset:2048
	ds_read_b128 v[200:203], v194 offset:3072
	ds_read_b128 v[204:207], v194 offset:4096
	ds_read_b128 v[208:211], v194 offset:5120
	ds_read_b128 v[212:215], v194 offset:6144
	ds_read_b128 v[216:219], v194 offset:7168
	global_load_lds_dwordx4 v[188:189], off
	v_lshl_add_u64 v[188:189], s[30:31], 0, v[164:165]
	s_add_i32 m0, s49, 0xe000
	s_nop 0
	global_load_lds_dwordx4 v[188:189], off
	s_waitcnt vmcnt(8)
	s_waitcnt lgkmcnt(0)
	s_barrier
	s_setprio 1
	s_waitcnt lgkmcnt(0)
	v_mfma_f32_16x16x32_bf16 v[124:127], v[128:131], v[180:183], v[124:127]
	v_mfma_f32_16x16x32_bf16 v[108:111], v[128:131], v[196:199], v[108:111]
	v_mfma_f32_16x16x32_bf16 v[92:95], v[128:131], v[204:207], v[92:95]
	v_mfma_f32_16x16x32_bf16 v[76:79], v[128:131], v[212:215], v[76:79]
	v_mfma_f32_16x16x32_bf16 v[72:75], v[136:139], v[212:215], v[72:75]
	v_mfma_f32_16x16x32_bf16 v[88:91], v[136:139], v[204:207], v[88:91]
	v_mfma_f32_16x16x32_bf16 v[104:107], v[136:139], v[196:199], v[104:107]
	v_mfma_f32_16x16x32_bf16 v[120:123], v[136:139], v[180:183], v[120:123]
	v_mfma_f32_16x16x32_bf16 v[124:127], v[132:135], v[184:187], v[124:127]
	v_mfma_f32_16x16x32_bf16 v[108:111], v[132:135], v[200:203], v[108:111]
	v_mfma_f32_16x16x32_bf16 v[92:95], v[132:135], v[208:211], v[92:95]
	v_mfma_f32_16x16x32_bf16 v[76:79], v[132:135], v[216:219], v[76:79]
	v_mfma_f32_16x16x32_bf16 v[72:75], v[140:143], v[216:219], v[72:75]
	v_mfma_f32_16x16x32_bf16 v[88:91], v[140:143], v[208:211], v[88:91]
	v_mfma_f32_16x16x32_bf16 v[104:107], v[140:143], v[200:203], v[104:107]
	v_mfma_f32_16x16x32_bf16 v[120:123], v[140:143], v[184:187], v[120:123]
	s_setprio 0
	s_setprio 1
	v_mfma_f32_16x16x32_bf16 v[116:119], v[144:147], v[180:183], v[116:119]
	v_mfma_f32_16x16x32_bf16 v[100:103], v[144:147], v[196:199], v[100:103]
	v_mfma_f32_16x16x32_bf16 v[84:87], v[144:147], v[204:207], v[84:87]
	v_mfma_f32_16x16x32_bf16 v[68:71], v[144:147], v[212:215], v[68:71]
	v_mfma_f32_16x16x32_bf16 v[64:67], v[172:175], v[212:215], v[64:67]
	v_mfma_f32_16x16x32_bf16 v[80:83], v[172:175], v[204:207], v[80:83]
	v_mfma_f32_16x16x32_bf16 v[96:99], v[172:175], v[196:199], v[96:99]
	v_mfma_f32_16x16x32_bf16 v[112:115], v[172:175], v[180:183], v[112:115]
	v_mfma_f32_16x16x32_bf16 v[116:119], v[148:151], v[184:187], v[116:119]
	v_mfma_f32_16x16x32_bf16 v[100:103], v[148:151], v[200:203], v[100:103]
	v_mfma_f32_16x16x32_bf16 v[84:87], v[148:151], v[208:211], v[84:87]
	v_mfma_f32_16x16x32_bf16 v[68:71], v[148:151], v[216:219], v[68:71]
	v_mfma_f32_16x16x32_bf16 v[64:67], v[176:179], v[216:219], v[64:67]
	v_mfma_f32_16x16x32_bf16 v[80:83], v[176:179], v[208:211], v[80:83]
	v_mfma_f32_16x16x32_bf16 v[96:99], v[176:179], v[200:203], v[96:99]
	v_mfma_f32_16x16x32_bf16 v[112:115], v[176:179], v[184:187], v[112:115]
	s_setprio 0
	s_barrier
	s_add_i32 s30, s62, s48
	v_lshl_add_u64 v[188:189], s[36:37], 0, v[158:159]
	s_mov_b32 m0, s30
	ds_read_b128 v[180:183], v194 offset:16384
	ds_read_b128 v[184:187], v194 offset:17408
	ds_read_b128 v[196:199], v194 offset:18432
	ds_read_b128 v[200:203], v194 offset:19456
	ds_read_b128 v[204:207], v194 offset:20480
	ds_read_b128 v[208:211], v194 offset:21504
	ds_read_b128 v[212:215], v194 offset:22528
	ds_read_b128 v[216:219], v194 offset:23552
	global_load_lds_dwordx4 v[188:189], off
	s_add_i32 m0, s30, 0x2000
	s_add_u32 s30, s36, 0xb0000
	v_lshl_add_u64 v[220:221], s[36:37], 0, v[162:163]
	s_addc_u32 s31, s37, 0
	s_add_i32 s50, s63, s48
	global_load_lds_dwordx4 v[220:221], off
	v_lshl_add_u64 v[222:223], s[30:31], 0, v[158:159]
	s_mov_b32 m0, s50
	v_lshl_add_u64 v[224:225], s[38:39], 0, v[160:161]
	global_load_lds_dwordx4 v[222:223], off
	v_lshl_add_u64 v[222:223], s[30:31], 0, v[162:163]
	s_add_i32 m0, s50, 0x2000
	s_nop 0
	global_load_lds_dwordx4 v[222:223], off
	v_lshl_add_u64 v[222:223], s[38:39], 0, v[156:157]
	s_mov_b32 m0, s49
	s_nop 0
	global_load_lds_dwordx4 v[222:223], off
	s_mov_b32 m0, s52
	s_nop 0
	global_load_lds_dwordx4 v[224:225], off
	s_waitcnt vmcnt(8)
	s_waitcnt lgkmcnt(0)
	s_barrier
; #define PG8_STAGE(bufoff, gbase, voff) do { _Pragma("unroll") for (int _i = 0; _i < 2; ++_i) \
;         __builtin_amdgcn_global_load_lds((const unsigned*)((const char*)(gbase) + (voff)[_i]), (LAS unsigned*)(lds + (bufoff) + ldsw + _i * 8192), 16, 0, 0); } while (0)
; #define PG8_LDA(dst, b, h) do { _Pragma("unroll") for (int m = 0; m < 4; ++m) _Pragma("unroll") for (int k = 0; k < 2; ++k) dst[m][k] = *(const LAS bf16x8*)(lds + PG8_SA(b, h) + aoff + m * 2048 + k * 1024); } while (0)
; #define PG8_LDB(dst, b, h) do { _Pragma("unroll") for (int n = 0; n < 2; ++n) _Pragma("unroll") for (int k = 0; k < 2; ++k) dst[n][k] = *(const LAS bf16x8*)(lds + PG8_SB(b, h) + boff + n * 2048 + k * 1024); } while (0)
; #define PG8_MMA(ai, bj, At, Bt) do { __builtin_amdgcn_s_setprio(1); _Pragma("unroll") for (int m = 0; m < 4; ++m) _Pragma("unroll") for (int n = 0; n < 2; ++n) _Pragma("unroll") for (int k = 0; k < 2; ++k) \
;         acc[ai][bj][m][n] = __builtin_amdgcn_mfma_f32_16x16x32_bf16(Bt[n][k], At[m][k], acc[ai][bj][m][n], 0, 0, 0); __builtin_amdgcn_s_setprio(0); } while (0)
; #define PG8_WAIT_V(n) asm volatile("s_waitcnt vmcnt(" #n ")" ::: "memory")
; #define PG8_WAIT_L(n) asm volatile("s_waitcnt lgkmcnt(" #n ")" ::: "memory")
; #define PG8_BAR __builtin_amdgcn_s_barrier()
; #define PG8_SCHED __builtin_amdgcn_sched_barrier(0)
; template <class Epi>
; __device__ __forceinline__ void gemm_phase(LAS unsigned char* lds, const Gemm g, const StaticOrder& S, const Epi& E) {
;     ...
;             PG8_WAIT_V(8); PG8_WAIT_L(0); PG8_BAR; PG8_MMA(1, 0, At, B0); PG8_MMA(1, 1, At, B1); PG8_BAR; PG8_SCHED;
;             PG8_LDB(B0, 1, 0); PG8_LDB(B1, 1, 1); PG8_SCHED; PG8_LDA(At, 1, 0); PG8_STAGE(PG8_SA(0, 1), a2 + hstepA, voffA);
;             PG8_WAIT_V(8); PG8_WAIT_L(0); PG8_BAR; PG8_MMA(0, 0, At, B0); PG8_MMA(0, 1, At, B1); PG8_BAR; PG8_SCHED;
	s_setprio 1
	s_waitcnt lgkmcnt(0)
	v_mfma_f32_16x16x32_bf16 v[60:63], v[128:131], v[180:183], v[60:63]
	v_mfma_f32_16x16x32_bf16 v[44:47], v[128:131], v[196:199], v[44:47]
	v_mfma_f32_16x16x32_bf16 v[28:31], v[128:131], v[204:207], v[28:31]
	v_mfma_f32_16x16x32_bf16 v[12:15], v[128:131], v[212:215], v[12:15]
	v_mfma_f32_16x16x32_bf16 v[8:11], v[136:139], v[212:215], v[8:11]
	v_mfma_f32_16x16x32_bf16 v[24:27], v[136:139], v[204:207], v[24:27]
	v_mfma_f32_16x16x32_bf16 v[40:43], v[136:139], v[196:199], v[40:43]
	v_mfma_f32_16x16x32_bf16 v[56:59], v[136:139], v[180:183], v[56:59]
	v_mfma_f32_16x16x32_bf16 v[60:63], v[132:135], v[184:187], v[60:63]
	v_mfma_f32_16x16x32_bf16 v[44:47], v[132:135], v[200:203], v[44:47]
	v_mfma_f32_16x16x32_bf16 v[28:31], v[132:135], v[208:211], v[28:31]
	v_mfma_f32_16x16x32_bf16 v[12:15], v[132:135], v[216:219], v[12:15]
	v_mfma_f32_16x16x32_bf16 v[8:11], v[140:143], v[216:219], v[8:11]
	v_mfma_f32_16x16x32_bf16 v[24:27], v[140:143], v[208:211], v[24:27]
	v_mfma_f32_16x16x32_bf16 v[40:43], v[140:143], v[200:203], v[40:43]
	v_mfma_f32_16x16x32_bf16 v[56:59], v[140:143], v[184:187], v[56:59]
	s_setprio 0
	s_setprio 1
	v_mfma_f32_16x16x32_bf16 v[52:55], v[144:147], v[180:183], v[52:55]
	v_mfma_f32_16x16x32_bf16 v[36:39], v[144:147], v[196:199], v[36:39]
	v_mfma_f32_16x16x32_bf16 v[20:23], v[144:147], v[204:207], v[20:23]
	v_mfma_f32_16x16x32_bf16 v[4:7], v[144:147], v[212:215], v[4:7]
	v_mfma_f32_16x16x32_bf16 v[0:3], v[172:175], v[212:215], v[0:3]
	v_mfma_f32_16x16x32_bf16 v[16:19], v[172:175], v[204:207], v[16:19]
	v_mfma_f32_16x16x32_bf16 v[32:35], v[172:175], v[196:199], v[32:35]
	v_mfma_f32_16x16x32_bf16 v[48:51], v[172:175], v[180:183], v[48:51]
	v_mfma_f32_16x16x32_bf16 v[52:55], v[148:151], v[184:187], v[52:55]
	v_mfma_f32_16x16x32_bf16 v[36:39], v[148:151], v[200:203], v[36:39]
	v_mfma_f32_16x16x32_bf16 v[20:23], v[148:151], v[208:211], v[20:23]
	v_mfma_f32_16x16x32_bf16 v[4:7], v[148:151], v[216:219], v[4:7]
	v_mfma_f32_16x16x32_bf16 v[0:3], v[176:179], v[216:219], v[0:3]
	v_mfma_f32_16x16x32_bf16 v[16:19], v[176:179], v[208:211], v[16:19]
	v_mfma_f32_16x16x32_bf16 v[32:35], v[176:179], v[200:203], v[32:35]
	v_mfma_f32_16x16x32_bf16 v[48:51], v[176:179], v[184:187], v[48:51]
	s_setprio 0
	s_barrier
	s_add_i32 s50, 0, 0x18000
	s_add_i32 s51, 0, 0x1c000
	v_add_u32_e32 v140, s50, v190
	v_add_u32_e32 v176, s51, v190
	ds_read_b128 v[128:131], v140
	ds_read_b128 v[132:135], v140 offset:1024
	ds_read_b128 v[136:139], v140 offset:2048
	ds_read_b128 v[140:143], v140 offset:3072
	ds_read_b128 v[144:147], v176
	ds_read_b128 v[148:151], v176 offset:1024
	ds_read_b128 v[172:175], v176 offset:2048
	ds_read_b128 v[176:179], v176 offset:3072
	s_add_u32 s30, s38, 0xb0000
	s_addc_u32 s31, s39, 0
	s_mov_b32 m0, s53
	v_lshl_add_u64 v[226:227], s[30:31], 0, v[156:157]
	ds_read_b128 v[180:183], v194 offset:32768
	ds_read_b128 v[184:187], v194 offset:33792
	ds_read_b128 v[196:199], v194 offset:34816
	ds_read_b128 v[200:203], v194 offset:35840
	ds_read_b128 v[204:207], v194 offset:36864
	ds_read_b128 v[208:211], v194 offset:37888
	ds_read_b128 v[212:215], v194 offset:38912
	ds_read_b128 v[216:219], v194 offset:39936
	global_load_lds_dwordx4 v[226:227], off
	v_lshl_add_u64 v[226:227], s[30:31], 0, v[160:161]
	s_mov_b32 m0, s54
	s_nop 0
	global_load_lds_dwordx4 v[226:227], off
	s_waitcnt vmcnt(8)
	s_waitcnt lgkmcnt(0)
	s_barrier
	s_setprio 1
	s_waitcnt lgkmcnt(0)
	v_mfma_f32_16x16x32_bf16 v[124:127], v[128:131], v[180:183], v[124:127]
	v_mfma_f32_16x16x32_bf16 v[108:111], v[128:131], v[196:199], v[108:111]
	v_mfma_f32_16x16x32_bf16 v[92:95], v[128:131], v[204:207], v[92:95]
	v_mfma_f32_16x16x32_bf16 v[76:79], v[128:131], v[212:215], v[76:79]
	v_mfma_f32_16x16x32_bf16 v[72:75], v[136:139], v[212:215], v[72:75]
	v_mfma_f32_16x16x32_bf16 v[88:91], v[136:139], v[204:207], v[88:91]
	v_mfma_f32_16x16x32_bf16 v[104:107], v[136:139], v[196:199], v[104:107]
	v_mfma_f32_16x16x32_bf16 v[120:123], v[136:139], v[180:183], v[120:123]
	v_mfma_f32_16x16x32_bf16 v[124:127], v[132:135], v[184:187], v[124:127]
	v_mfma_f32_16x16x32_bf16 v[108:111], v[132:135], v[200:203], v[108:111]
	v_mfma_f32_16x16x32_bf16 v[92:95], v[132:135], v[208:211], v[92:95]
	v_mfma_f32_16x16x32_bf16 v[76:79], v[132:135], v[216:219], v[76:79]
	v_mfma_f32_16x16x32_bf16 v[72:75], v[140:143], v[216:219], v[72:75]
	v_mfma_f32_16x16x32_bf16 v[88:91], v[140:143], v[208:211], v[88:91]
	v_mfma_f32_16x16x32_bf16 v[104:107], v[140:143], v[200:203], v[104:107]
	v_mfma_f32_16x16x32_bf16 v[120:123], v[140:143], v[184:187], v[120:123]
	s_setprio 0
	s_setprio 1
	v_mfma_f32_16x16x32_bf16 v[116:119], v[144:147], v[180:183], v[116:119]
	v_mfma_f32_16x16x32_bf16 v[100:103], v[144:147], v[196:199], v[100:103]
	v_mfma_f32_16x16x32_bf16 v[84:87], v[144:147], v[204:207], v[84:87]
	v_mfma_f32_16x16x32_bf16 v[68:71], v[144:147], v[212:215], v[68:71]
	v_mfma_f32_16x16x32_bf16 v[64:67], v[172:175], v[212:215], v[64:67]
	v_mfma_f32_16x16x32_bf16 v[80:83], v[172:175], v[204:207], v[80:83]
	v_mfma_f32_16x16x32_bf16 v[96:99], v[172:175], v[196:199], v[96:99]
	v_mfma_f32_16x16x32_bf16 v[112:115], v[172:175], v[180:183], v[112:115]
	v_mfma_f32_16x16x32_bf16 v[116:119], v[148:151], v[184:187], v[116:119]
	v_mfma_f32_16x16x32_bf16 v[100:103], v[148:151], v[200:203], v[100:103]
	v_mfma_f32_16x16x32_bf16 v[84:87], v[148:151], v[208:211], v[84:87]
	v_mfma_f32_16x16x32_bf16 v[68:71], v[148:151], v[216:219], v[68:71]
	v_mfma_f32_16x16x32_bf16 v[64:67], v[176:179], v[216:219], v[64:67]
	v_mfma_f32_16x16x32_bf16 v[80:83], v[176:179], v[208:211], v[80:83]
	v_mfma_f32_16x16x32_bf16 v[96:99], v[176:179], v[200:203], v[96:99]
	v_mfma_f32_16x16x32_bf16 v[112:115], v[176:179], v[184:187], v[112:115]
	s_setprio 0
	s_barrier
; #define PG8_STAGE(bufoff, gbase, voff) do { _Pragma("unroll") for (int _i = 0; _i < 2; ++_i) \
;         __builtin_amdgcn_global_load_lds((const unsigned*)((const char*)(gbase) + (voff)[_i]), (LAS unsigned*)(lds + (bufoff) + ldsw + _i * 8192), 16, 0, 0); } while (0)
; #define PG8_LDA(dst, b, h) do { _Pragma("unroll") for (int m = 0; m < 4; ++m) _Pragma("unroll") for (int k = 0; k < 2; ++k) dst[m][k] = *(const LAS bf16x8*)(lds + PG8_SA(b, h) + aoff + m * 2048 + k * 1024); } while (0)
; #define PG8_MMA(ai, bj, At, Bt) do { __builtin_amdgcn_s_setprio(1); _Pragma("unroll") for (int m = 0; m < 4; ++m) _Pragma("unroll") for (int n = 0; n < 2; ++n) _Pragma("unroll") for (int k = 0; k < 2; ++k) \
;         acc[ai][bj][m][n] = __builtin_amdgcn_mfma_f32_16x16x32_bf16(Bt[n][k], At[m][k], acc[ai][bj][m][n], 0, 0, 0); __builtin_amdgcn_s_setprio(0); } while (0)
; #define PG8_WAIT_V(n) asm volatile("s_waitcnt vmcnt(" #n ")" ::: "memory")
; #define PG8_WAIT_L(n) asm volatile("s_waitcnt lgkmcnt(" #n ")" ::: "memory")
; #define PG8_BAR __builtin_amdgcn_s_barrier()
; #define PG8_SCHED __builtin_amdgcn_sched_barrier(0)
; template <class Epi>
; __device__ __forceinline__ void gemm_phase(LAS unsigned char* lds, const Gemm g, const StaticOrder& S, const Epi& E) {
;     ...
;             PG8_LDA(At, 1, 1); PG8_STAGE(PG8_SB(1, 0), b3, voffB); PG8_STAGE(PG8_SB(1, 1), b3 + hstepB, voffB); PG8_STAGE(PG8_SA(1, 0), a3, voffA);
;             PG8_WAIT_V(8); PG8_WAIT_L(0); PG8_BAR; PG8_MMA(1, 0, At, B0); PG8_MMA(1, 1, At, B1); PG8_BAR; PG8_SCHED;
;         }
;         if (wr == 0) PG8_BAR;
	s_add_i32 s30, s50, s48
	v_lshl_add_u64 v[188:189], v[188:189], 0, s[24:25]
	s_mov_b32 m0, s30
	ds_read_b128 v[180:183], v194 offset:49152
	ds_read_b128 v[184:187], v194 offset:50176
	ds_read_b128 v[196:199], v194 offset:51200
	ds_read_b128 v[200:203], v194 offset:52224
	ds_read_b128 v[204:207], v194 offset:53248
	ds_read_b128 v[208:211], v194 offset:54272
	ds_read_b128 v[212:215], v194 offset:55296
	ds_read_b128 v[216:219], v194 offset:56320
	global_load_lds_dwordx4 v[188:189], off
	s_add_i32 m0, s30, 0x2000
	s_add_u32 s30, s36, 0xb0080
	v_lshl_add_u64 v[188:189], v[220:221], 0, s[24:25]
	s_addc_u32 s31, s37, 0
	s_add_i32 s36, s51, s48
	global_load_lds_dwordx4 v[188:189], off
	v_lshl_add_u64 v[188:189], s[30:31], 0, v[158:159]
	s_mov_b32 m0, s36
	s_nop 0
	global_load_lds_dwordx4 v[188:189], off
	v_lshl_add_u64 v[188:189], s[30:31], 0, v[162:163]
	s_add_i32 m0, s36, 0x2000
	s_nop 0
	global_load_lds_dwordx4 v[188:189], off
	v_lshl_add_u64 v[188:189], v[222:223], 0, s[24:25]
	s_mov_b32 m0, s56
	s_nop 0
	global_load_lds_dwordx4 v[188:189], off
	v_lshl_add_u64 v[188:189], v[224:225], 0, s[24:25]
	s_mov_b32 m0, s57
	s_nop 0
	global_load_lds_dwordx4 v[188:189], off
	s_waitcnt vmcnt(8)
	s_waitcnt lgkmcnt(0)
	s_barrier
	s_setprio 1
	s_waitcnt lgkmcnt(0)
	v_mfma_f32_16x16x32_bf16 v[60:63], v[128:131], v[180:183], v[60:63]
	v_mfma_f32_16x16x32_bf16 v[44:47], v[128:131], v[196:199], v[44:47]
	v_mfma_f32_16x16x32_bf16 v[28:31], v[128:131], v[204:207], v[28:31]
	v_mfma_f32_16x16x32_bf16 v[12:15], v[128:131], v[212:215], v[12:15]
	v_mfma_f32_16x16x32_bf16 v[8:11], v[136:139], v[212:215], v[8:11]
	v_mfma_f32_16x16x32_bf16 v[24:27], v[136:139], v[204:207], v[24:27]
	v_mfma_f32_16x16x32_bf16 v[40:43], v[136:139], v[196:199], v[40:43]
	v_mfma_f32_16x16x32_bf16 v[56:59], v[136:139], v[180:183], v[56:59]
	v_mfma_f32_16x16x32_bf16 v[60:63], v[132:135], v[184:187], v[60:63]
	v_mfma_f32_16x16x32_bf16 v[44:47], v[132:135], v[200:203], v[44:47]
	v_mfma_f32_16x16x32_bf16 v[28:31], v[132:135], v[208:211], v[28:31]
	v_mfma_f32_16x16x32_bf16 v[12:15], v[132:135], v[216:219], v[12:15]
	v_mfma_f32_16x16x32_bf16 v[8:11], v[140:143], v[216:219], v[8:11]
	v_mfma_f32_16x16x32_bf16 v[24:27], v[140:143], v[208:211], v[24:27]
	v_mfma_f32_16x16x32_bf16 v[40:43], v[140:143], v[200:203], v[40:43]
	v_mfma_f32_16x16x32_bf16 v[56:59], v[140:143], v[184:187], v[56:59]
	s_setprio 0
	s_setprio 1
	v_mfma_f32_16x16x32_bf16 v[52:55], v[144:147], v[180:183], v[52:55]
	v_mfma_f32_16x16x32_bf16 v[36:39], v[144:147], v[196:199], v[36:39]
	v_mfma_f32_16x16x32_bf16 v[20:23], v[144:147], v[204:207], v[20:23]
	v_mfma_f32_16x16x32_bf16 v[4:7], v[144:147], v[212:215], v[4:7]
	v_mfma_f32_16x16x32_bf16 v[0:3], v[172:175], v[212:215], v[0:3]
	v_mfma_f32_16x16x32_bf16 v[16:19], v[172:175], v[204:207], v[16:19]
	v_mfma_f32_16x16x32_bf16 v[32:35], v[172:175], v[196:199], v[32:35]
	v_mfma_f32_16x16x32_bf16 v[48:51], v[172:175], v[180:183], v[48:51]
	v_mfma_f32_16x16x32_bf16 v[52:55], v[148:151], v[184:187], v[52:55]
	v_mfma_f32_16x16x32_bf16 v[36:39], v[148:151], v[200:203], v[36:39]
	v_mfma_f32_16x16x32_bf16 v[20:23], v[148:151], v[208:211], v[20:23]
	v_mfma_f32_16x16x32_bf16 v[4:7], v[148:151], v[216:219], v[4:7]
	v_mfma_f32_16x16x32_bf16 v[0:3], v[176:179], v[216:219], v[0:3]
	v_mfma_f32_16x16x32_bf16 v[16:19], v[176:179], v[208:211], v[16:19]
	v_mfma_f32_16x16x32_bf16 v[32:35], v[176:179], v[200:203], v[32:35]
	v_mfma_f32_16x16x32_bf16 v[48:51], v[176:179], v[184:187], v[48:51]
	s_setprio 0
	s_barrier
	s_add_i32 s71, s71, 2
	s_add_u32 s67, s67, 0x100
	s_addc_u32 s69, s69, 0
	s_cmp_gt_u32 s71, 41
	s_mov_b64 s[30:31], s[34:35]
	s_cbranch_scc0 .LBB0_942
	s_and_b64 vcc, exec, s[26:27]
	s_cbranch_vccz .LBB0_945
	s_barrier

; #define PG8_STAGE(bufoff, gbase, voff) do { _Pragma("unroll") for (int _i = 0; _i < 2; ++_i) \
;         __builtin_amdgcn_global_load_lds((const unsigned*)((const char*)(gbase) + (voff)[_i]), (LAS unsigned*)(lds + (bufoff) + ldsw + _i * 8192), 16, 0, 0); } while (0)
; #define PG8_LDA(dst, b, h) do { _Pragma("unroll") for (int m = 0; m < 4; ++m) _Pragma("unroll") for (int k = 0; k < 2; ++k) dst[m][k] = *(const LAS bf16x8*)(lds + PG8_SA(b, h) + aoff + m * 2048 + k * 1024); } while (0)
; #define PG8_LDB(dst, b, h) do { _Pragma("unroll") for (int n = 0; n < 2; ++n) _Pragma("unroll") for (int k = 0; k < 2; ++k) dst[n][k] = *(const LAS bf16x8*)(lds + PG8_SB(b, h) + boff + n * 2048 + k * 1024); } while (0)
; #define PG8_MMA(ai, bj, At, Bt) do { __builtin_amdgcn_s_setprio(1); _Pragma("unroll") for (int m = 0; m < 4; ++m) _Pragma("unroll") for (int n = 0; n < 2; ++n) _Pragma("unroll") for (int k = 0; k < 2; ++k) \
;         acc[ai][bj][m][n] = __builtin_amdgcn_mfma_f32_16x16x32_bf16(Bt[n][k], At[m][k], acc[ai][bj][m][n], 0, 0, 0); __builtin_amdgcn_s_setprio(0); } while (0)
; #define PG8_WAIT_V(n) asm volatile("s_waitcnt vmcnt(" #n ")" ::: "memory")
; #define PG8_WAIT_L(n) asm volatile("s_waitcnt lgkmcnt(" #n ")" ::: "memory")
; #define PG8_BAR __builtin_amdgcn_s_barrier()
; #define PG8_SCHED __builtin_amdgcn_sched_barrier(0)
; template <class Epi>
; __device__ __forceinline__ void gemm_phase(LAS unsigned char* lds, const Gemm g, const StaticOrder& S, const Epi& E) {
;     ...
;             const bool last = (t == nt - 2);
;             const char* a1 = cA + (unsigned)(t + 1) * kstep;
;             const char* a2 = last ? nA : cA + (unsigned)(t + 2) * kstep; const char* b2 = last ? nB : cB + (unsigned)(t + 2) * kstep;
;             const char* a3 = a2 + kstep; const char* b3 = b2 + kstep;
;             PG8_LDB(B0, 0, 0); PG8_LDB(B1, 0, 1); PG8_SCHED; PG8_LDA(At, 0, 0); PG8_STAGE(PG8_SA(1, 1), a1 + hstepA, voffA);
;             PG8_WAIT_V(8); PG8_WAIT_L(0); PG8_BAR; PG8_MMA(0, 0, At, B0); PG8_MMA(0, 1, At, B1); PG8_BAR; PG8_SCHED;
;             PG8_LDA(At, 0, 1); PG8_STAGE(PG8_SB(0, 0), b2, voffB); PG8_STAGE(PG8_SB(0, 1), b2 + hstepB, voffB); PG8_STAGE(PG8_SA(0, 0), a2, voffA);
;             PG8_WAIT_V(8); PG8_WAIT_L(0); PG8_BAR; PG8_MMA(1, 0, At, B0); PG8_MMA(1, 1, At, B1); PG8_BAR; PG8_SCHED;
.LBB0_1020:
	ds_read_b128 v[156:159], v188
	ds_read_b128 v[160:163], v188 offset:1024
	ds_read_b128 v[164:167], v188 offset:2048
	ds_read_b128 v[168:171], v188 offset:3072
	ds_read_b128 v[172:175], v189
	ds_read_b128 v[176:179], v189 offset:1024
	ds_read_b128 v[180:183], v189 offset:2048
	ds_read_b128 v[184:187], v189 offset:3072
	s_add_u32 s46, s40, 0xfffc0080
	s_addc_u32 s47, s41, -1
	s_cmp_eq_u32 s79, 12
	s_cselect_b32 s49, s9, s47
	s_cselect_b32 s48, s11, s46
	s_cselect_b32 s47, s15, s78
	s_cselect_b32 s46, s31, s35
	v_lshl_add_u64 v[150:151], s[40:41], 0, v[144:145]
	s_add_i32 m0, s57, 0xc000
	ds_read_b128 v[194:197], v190
	ds_read_b128 v[198:201], v190 offset:1024
	ds_read_b128 v[202:205], v190 offset:2048
	ds_read_b128 v[206:209], v190 offset:3072
	ds_read_b128 v[210:213], v190 offset:4096
	ds_read_b128 v[214:217], v190 offset:5120
	ds_read_b128 v[218:221], v190 offset:6144
	ds_read_b128 v[222:225], v190 offset:7168
	global_load_lds_dwordx4 v[150:151], off
	v_lshl_add_u64 v[150:151], s[40:41], 0, v[142:143]
	s_add_i32 m0, s57, 0xe000
	s_nop 0
	global_load_lds_dwordx4 v[150:151], off
	s_waitcnt vmcnt(8)
	s_waitcnt lgkmcnt(0)
	s_barrier
	s_setprio 1
	s_waitcnt lgkmcnt(0)
	v_mfma_f32_16x16x32_bf16 v[124:127], v[156:159], v[194:197], v[124:127]
	v_mfma_f32_16x16x32_bf16 v[108:111], v[156:159], v[202:205], v[108:111]
	v_mfma_f32_16x16x32_bf16 v[92:95], v[156:159], v[210:213], v[92:95]
	v_mfma_f32_16x16x32_bf16 v[76:79], v[156:159], v[218:221], v[76:79]
	v_mfma_f32_16x16x32_bf16 v[72:75], v[164:167], v[218:221], v[72:75]
	v_mfma_f32_16x16x32_bf16 v[88:91], v[164:167], v[210:213], v[88:91]
	v_mfma_f32_16x16x32_bf16 v[104:107], v[164:167], v[202:205], v[104:107]
	v_mfma_f32_16x16x32_bf16 v[120:123], v[164:167], v[194:197], v[120:123]
	v_mfma_f32_16x16x32_bf16 v[124:127], v[160:163], v[198:201], v[124:127]
	v_mfma_f32_16x16x32_bf16 v[108:111], v[160:163], v[206:209], v[108:111]
	v_mfma_f32_16x16x32_bf16 v[92:95], v[160:163], v[214:217], v[92:95]
	v_mfma_f32_16x16x32_bf16 v[76:79], v[160:163], v[222:225], v[76:79]
	v_mfma_f32_16x16x32_bf16 v[72:75], v[168:171], v[222:225], v[72:75]
	v_mfma_f32_16x16x32_bf16 v[88:91], v[168:171], v[214:217], v[88:91]
	v_mfma_f32_16x16x32_bf16 v[104:107], v[168:171], v[206:209], v[104:107]
	v_mfma_f32_16x16x32_bf16 v[120:123], v[168:171], v[198:201], v[120:123]
	s_setprio 0
	s_setprio 1
	v_mfma_f32_16x16x32_bf16 v[116:119], v[172:175], v[194:197], v[116:119]
	v_mfma_f32_16x16x32_bf16 v[100:103], v[172:175], v[202:205], v[100:103]
	v_mfma_f32_16x16x32_bf16 v[84:87], v[172:175], v[210:213], v[84:87]
	v_mfma_f32_16x16x32_bf16 v[68:71], v[172:175], v[218:221], v[68:71]
	v_mfma_f32_16x16x32_bf16 v[64:67], v[180:183], v[218:221], v[64:67]
	v_mfma_f32_16x16x32_bf16 v[80:83], v[180:183], v[210:213], v[80:83]
	v_mfma_f32_16x16x32_bf16 v[96:99], v[180:183], v[202:205], v[96:99]
	v_mfma_f32_16x16x32_bf16 v[112:115], v[180:183], v[194:197], v[112:115]
	v_mfma_f32_16x16x32_bf16 v[116:119], v[176:179], v[198:201], v[116:119]
	v_mfma_f32_16x16x32_bf16 v[100:103], v[176:179], v[206:209], v[100:103]
	v_mfma_f32_16x16x32_bf16 v[84:87], v[176:179], v[214:217], v[84:87]
	v_mfma_f32_16x16x32_bf16 v[68:71], v[176:179], v[222:225], v[68:71]
	v_mfma_f32_16x16x32_bf16 v[64:67], v[184:187], v[222:225], v[64:67]
	v_mfma_f32_16x16x32_bf16 v[80:83], v[184:187], v[214:217], v[80:83]
	v_mfma_f32_16x16x32_bf16 v[96:99], v[184:187], v[206:209], v[96:99]
	v_mfma_f32_16x16x32_bf16 v[112:115], v[184:187], v[198:201], v[112:115]
	s_setprio 0
	s_barrier
	s_add_i32 s50, s71, s56
	v_lshl_add_u64 v[150:151], s[46:47], 0, v[130:131]
	s_mov_b32 m0, s50
	ds_read_b128 v[194:197], v190 offset:16384
	ds_read_b128 v[198:201], v190 offset:17408
	ds_read_b128 v[202:205], v190 offset:18432
	ds_read_b128 v[206:209], v190 offset:19456
	ds_read_b128 v[210:213], v190 offset:20480
	ds_read_b128 v[214:217], v190 offset:21504
	ds_read_b128 v[218:221], v190 offset:22528
	ds_read_b128 v[222:225], v190 offset:23552
	global_load_lds_dwordx4 v[150:151], off
	s_add_i32 m0, s50, 0x2000
	s_add_u32 s50, s46, 0x40000
	v_lshl_add_u64 v[226:227], s[46:47], 0, v[134:135]
	s_addc_u32 s51, s47, 0
	s_add_i32 s80, s76, s56
	global_load_lds_dwordx4 v[226:227], off
	v_lshl_add_u64 v[228:229], s[50:51], 0, v[130:131]
	s_mov_b32 m0, s80
	v_lshl_add_u64 v[230:231], s[48:49], 0, v[132:133]
	global_load_lds_dwordx4 v[228:229], off
	v_lshl_add_u64 v[228:229], s[50:51], 0, v[134:135]
	s_add_i32 m0, s80, 0x2000
	s_nop 0
	global_load_lds_dwordx4 v[228:229], off
	v_lshl_add_u64 v[228:229], s[48:49], 0, v[128:129]
	s_mov_b32 m0, s57
	s_nop 0
	global_load_lds_dwordx4 v[228:229], off
	s_mov_b32 m0, s58
	s_nop 0
	global_load_lds_dwordx4 v[230:231], off
	s_waitcnt vmcnt(8)
	s_waitcnt lgkmcnt(0)
	s_barrier
; #define PG8_STAGE(bufoff, gbase, voff) do { _Pragma("unroll") for (int _i = 0; _i < 2; ++_i) \
;         __builtin_amdgcn_global_load_lds((const unsigned*)((const char*)(gbase) + (voff)[_i]), (LAS unsigned*)(lds + (bufoff) + ldsw + _i * 8192), 16, 0, 0); } while (0)
; #define PG8_LDA(dst, b, h) do { _Pragma("unroll") for (int m = 0; m < 4; ++m) _Pragma("unroll") for (int k = 0; k < 2; ++k) dst[m][k] = *(const LAS bf16x8*)(lds + PG8_SA(b, h) + aoff + m * 2048 + k * 1024); } while (0)
; #define PG8_LDB(dst, b, h) do { _Pragma("unroll") for (int n = 0; n < 2; ++n) _Pragma("unroll") for (int k = 0; k < 2; ++k) dst[n][k] = *(const LAS bf16x8*)(lds + PG8_SB(b, h) + boff + n * 2048 + k * 1024); } while (0)
; #define PG8_MMA(ai, bj, At, Bt) do { __builtin_amdgcn_s_setprio(1); _Pragma("unroll") for (int m = 0; m < 4; ++m) _Pragma("unroll") for (int n = 0; n < 2; ++n) _Pragma("unroll") for (int k = 0; k < 2; ++k) \
;         acc[ai][bj][m][n] = __builtin_amdgcn_mfma_f32_16x16x32_bf16(Bt[n][k], At[m][k], acc[ai][bj][m][n], 0, 0, 0); __builtin_amdgcn_s_setprio(0); } while (0)
; #define PG8_WAIT_V(n) asm volatile("s_waitcnt vmcnt(" #n ")" ::: "memory")
; #define PG8_WAIT_L(n) asm volatile("s_waitcnt lgkmcnt(" #n ")" ::: "memory")
; #define PG8_BAR __builtin_amdgcn_s_barrier()
; #define PG8_SCHED __builtin_amdgcn_sched_barrier(0)
; template <class Epi>
; __device__ __forceinline__ void gemm_phase(LAS unsigned char* lds, const Gemm g, const StaticOrder& S, const Epi& E) {
;     ...
;             PG8_WAIT_V(8); PG8_WAIT_L(0); PG8_BAR; PG8_MMA(1, 0, At, B0); PG8_MMA(1, 1, At, B1); PG8_BAR; PG8_SCHED;
;             PG8_LDB(B0, 1, 0); PG8_LDB(B1, 1, 1); PG8_SCHED; PG8_LDA(At, 1, 0); PG8_STAGE(PG8_SA(0, 1), a2 + hstepA, voffA);
;             PG8_WAIT_V(8); PG8_WAIT_L(0); PG8_BAR; PG8_MMA(0, 0, At, B0); PG8_MMA(0, 1, At, B1); PG8_BAR; PG8_SCHED;
	s_setprio 1
	s_waitcnt lgkmcnt(0)
	v_mfma_f32_16x16x32_bf16 v[60:63], v[156:159], v[194:197], v[60:63]
	v_mfma_f32_16x16x32_bf16 v[44:47], v[156:159], v[202:205], v[44:47]
	v_mfma_f32_16x16x32_bf16 v[28:31], v[156:159], v[210:213], v[28:31]
	v_mfma_f32_16x16x32_bf16 v[12:15], v[156:159], v[218:221], v[12:15]
	v_mfma_f32_16x16x32_bf16 v[8:11], v[164:167], v[218:221], v[8:11]
	v_mfma_f32_16x16x32_bf16 v[24:27], v[164:167], v[210:213], v[24:27]
	v_mfma_f32_16x16x32_bf16 v[40:43], v[164:167], v[202:205], v[40:43]
	v_mfma_f32_16x16x32_bf16 v[56:59], v[164:167], v[194:197], v[56:59]
	v_mfma_f32_16x16x32_bf16 v[60:63], v[160:163], v[198:201], v[60:63]
	v_mfma_f32_16x16x32_bf16 v[44:47], v[160:163], v[206:209], v[44:47]
	v_mfma_f32_16x16x32_bf16 v[28:31], v[160:163], v[214:217], v[28:31]
	v_mfma_f32_16x16x32_bf16 v[12:15], v[160:163], v[222:225], v[12:15]
	v_mfma_f32_16x16x32_bf16 v[8:11], v[168:171], v[222:225], v[8:11]
	v_mfma_f32_16x16x32_bf16 v[24:27], v[168:171], v[214:217], v[24:27]
	v_mfma_f32_16x16x32_bf16 v[40:43], v[168:171], v[206:209], v[40:43]
	v_mfma_f32_16x16x32_bf16 v[56:59], v[168:171], v[198:201], v[56:59]
	s_setprio 0
	s_setprio 1
	v_mfma_f32_16x16x32_bf16 v[52:55], v[172:175], v[194:197], v[52:55]
	v_mfma_f32_16x16x32_bf16 v[36:39], v[172:175], v[202:205], v[36:39]
	v_mfma_f32_16x16x32_bf16 v[20:23], v[172:175], v[210:213], v[20:23]
	v_mfma_f32_16x16x32_bf16 v[4:7], v[172:175], v[218:221], v[4:7]
	v_mfma_f32_16x16x32_bf16 v[0:3], v[180:183], v[218:221], v[0:3]
	v_mfma_f32_16x16x32_bf16 v[16:19], v[180:183], v[210:213], v[16:19]
	v_mfma_f32_16x16x32_bf16 v[32:35], v[180:183], v[202:205], v[32:35]
	v_mfma_f32_16x16x32_bf16 v[48:51], v[180:183], v[194:197], v[48:51]
	v_mfma_f32_16x16x32_bf16 v[52:55], v[176:179], v[198:201], v[52:55]
	v_mfma_f32_16x16x32_bf16 v[36:39], v[176:179], v[206:209], v[36:39]
	v_mfma_f32_16x16x32_bf16 v[20:23], v[176:179], v[214:217], v[20:23]
	v_mfma_f32_16x16x32_bf16 v[4:7], v[176:179], v[222:225], v[4:7]
	v_mfma_f32_16x16x32_bf16 v[0:3], v[184:187], v[222:225], v[0:3]
	v_mfma_f32_16x16x32_bf16 v[16:19], v[184:187], v[214:217], v[16:19]
	v_mfma_f32_16x16x32_bf16 v[32:35], v[184:187], v[206:209], v[32:35]
	v_mfma_f32_16x16x32_bf16 v[48:51], v[184:187], v[198:201], v[48:51]
	s_setprio 0
	s_barrier
	s_add_i32 s50, 0, 0x18000
	v_add_u32_e32 v136, s50, v153
	s_add_i32 s51, 0, 0x1c000
	ds_read_b128 v[156:159], v136
	ds_read_b128 v[160:163], v136 offset:1024
	ds_read_b128 v[164:167], v136 offset:2048
	ds_read_b128 v[168:171], v136 offset:3072
	v_add_u32_e32 v136, s51, v153
	ds_read_b128 v[172:175], v136
	ds_read_b128 v[176:179], v136 offset:1024
	ds_read_b128 v[180:183], v136 offset:2048
	ds_read_b128 v[184:187], v136 offset:3072
	s_add_u32 s48, s48, 0x40000
	s_addc_u32 s49, s49, 0
	s_mov_b32 m0, s59
	v_lshl_add_u64 v[232:233], s[48:49], 0, v[128:129]
	ds_read_b128 v[194:197], v190 offset:32768
	ds_read_b128 v[198:201], v190 offset:33792
	ds_read_b128 v[202:205], v190 offset:34816
	ds_read_b128 v[206:209], v190 offset:35840
	ds_read_b128 v[210:213], v190 offset:36864
	ds_read_b128 v[214:217], v190 offset:37888
	ds_read_b128 v[218:221], v190 offset:38912
	ds_read_b128 v[222:225], v190 offset:39936
	global_load_lds_dwordx4 v[232:233], off
	v_lshl_add_u64 v[232:233], s[48:49], 0, v[132:133]
	s_mov_b32 m0, s60
	s_nop 0
	global_load_lds_dwordx4 v[232:233], off
	s_waitcnt vmcnt(8)
	s_waitcnt lgkmcnt(0)
	s_barrier
	s_setprio 1
	s_waitcnt lgkmcnt(0)
	v_mfma_f32_16x16x32_bf16 v[124:127], v[156:159], v[194:197], v[124:127]
	v_mfma_f32_16x16x32_bf16 v[108:111], v[156:159], v[202:205], v[108:111]
	v_mfma_f32_16x16x32_bf16 v[92:95], v[156:159], v[210:213], v[92:95]
	v_mfma_f32_16x16x32_bf16 v[76:79], v[156:159], v[218:221], v[76:79]
	v_mfma_f32_16x16x32_bf16 v[72:75], v[164:167], v[218:221], v[72:75]
	v_mfma_f32_16x16x32_bf16 v[88:91], v[164:167], v[210:213], v[88:91]
	v_mfma_f32_16x16x32_bf16 v[104:107], v[164:167], v[202:205], v[104:107]
	v_mfma_f32_16x16x32_bf16 v[120:123], v[164:167], v[194:197], v[120:123]
	v_mfma_f32_16x16x32_bf16 v[124:127], v[160:163], v[198:201], v[124:127]
	v_mfma_f32_16x16x32_bf16 v[108:111], v[160:163], v[206:209], v[108:111]
	v_mfma_f32_16x16x32_bf16 v[92:95], v[160:163], v[214:217], v[92:95]
	v_mfma_f32_16x16x32_bf16 v[76:79], v[160:163], v[222:225], v[76:79]
	v_mfma_f32_16x16x32_bf16 v[72:75], v[168:171], v[222:225], v[72:75]
	v_mfma_f32_16x16x32_bf16 v[88:91], v[168:171], v[214:217], v[88:91]
	v_mfma_f32_16x16x32_bf16 v[104:107], v[168:171], v[206:209], v[104:107]
	v_mfma_f32_16x16x32_bf16 v[120:123], v[168:171], v[198:201], v[120:123]
	s_setprio 0
	s_setprio 1
	v_mfma_f32_16x16x32_bf16 v[116:119], v[172:175], v[194:197], v[116:119]
	v_mfma_f32_16x16x32_bf16 v[100:103], v[172:175], v[202:205], v[100:103]
	v_mfma_f32_16x16x32_bf16 v[84:87], v[172:175], v[210:213], v[84:87]
	v_mfma_f32_16x16x32_bf16 v[68:71], v[172:175], v[218:221], v[68:71]
	v_mfma_f32_16x16x32_bf16 v[64:67], v[180:183], v[218:221], v[64:67]
	v_mfma_f32_16x16x32_bf16 v[80:83], v[180:183], v[210:213], v[80:83]
	v_mfma_f32_16x16x32_bf16 v[96:99], v[180:183], v[202:205], v[96:99]
	v_mfma_f32_16x16x32_bf16 v[112:115], v[180:183], v[194:197], v[112:115]
	v_mfma_f32_16x16x32_bf16 v[116:119], v[176:179], v[198:201], v[116:119]
	v_mfma_f32_16x16x32_bf16 v[100:103], v[176:179], v[206:209], v[100:103]
	v_mfma_f32_16x16x32_bf16 v[84:87], v[176:179], v[214:217], v[84:87]
	v_mfma_f32_16x16x32_bf16 v[68:71], v[176:179], v[222:225], v[68:71]
	v_mfma_f32_16x16x32_bf16 v[64:67], v[184:187], v[222:225], v[64:67]
	v_mfma_f32_16x16x32_bf16 v[80:83], v[184:187], v[214:217], v[80:83]
	v_mfma_f32_16x16x32_bf16 v[96:99], v[184:187], v[206:209], v[96:99]
	v_mfma_f32_16x16x32_bf16 v[112:115], v[184:187], v[198:201], v[112:115]
	s_setprio 0
	s_barrier
; #define PG8_STAGE(bufoff, gbase, voff) do { _Pragma("unroll") for (int _i = 0; _i < 2; ++_i) \
;         __builtin_amdgcn_global_load_lds((const unsigned*)((const char*)(gbase) + (voff)[_i]), (LAS unsigned*)(lds + (bufoff) + ldsw + _i * 8192), 16, 0, 0); } while (0)
; #define PG8_LDA(dst, b, h) do { _Pragma("unroll") for (int m = 0; m < 4; ++m) _Pragma("unroll") for (int k = 0; k < 2; ++k) dst[m][k] = *(const LAS bf16x8*)(lds + PG8_SA(b, h) + aoff + m * 2048 + k * 1024); } while (0)
; #define PG8_MMA(ai, bj, At, Bt) do { __builtin_amdgcn_s_setprio(1); _Pragma("unroll") for (int m = 0; m < 4; ++m) _Pragma("unroll") for (int n = 0; n < 2; ++n) _Pragma("unroll") for (int k = 0; k < 2; ++k) \
;         acc[ai][bj][m][n] = __builtin_amdgcn_mfma_f32_16x16x32_bf16(Bt[n][k], At[m][k], acc[ai][bj][m][n], 0, 0, 0); __builtin_amdgcn_s_setprio(0); } while (0)
; #define PG8_WAIT_V(n) asm volatile("s_waitcnt vmcnt(" #n ")" ::: "memory")
; #define PG8_WAIT_L(n) asm volatile("s_waitcnt lgkmcnt(" #n ")" ::: "memory")
; #define PG8_BAR __builtin_amdgcn_s_barrier()
; #define PG8_SCHED __builtin_amdgcn_sched_barrier(0)
; template <class Epi>
; __device__ __forceinline__ void gemm_phase(LAS unsigned char* lds, const Gemm g, const StaticOrder& S, const Epi& E) {
;     ...
;             PG8_LDA(At, 1, 1); PG8_STAGE(PG8_SB(1, 0), b3, voffB); PG8_STAGE(PG8_SB(1, 1), b3 + hstepB, voffB); PG8_STAGE(PG8_SA(1, 0), a3, voffA);
;             PG8_WAIT_V(8); PG8_WAIT_L(0); PG8_BAR; PG8_MMA(1, 0, At, B0); PG8_MMA(1, 1, At, B1); PG8_BAR; PG8_SCHED;
;         }
;         if (wr == 0) PG8_BAR;
	s_add_i32 s48, s50, s56
	v_lshl_add_u64 v[150:151], v[150:151], 0, s[26:27]
	s_mov_b32 m0, s48
	ds_read_b128 v[194:197], v190 offset:49152
	ds_read_b128 v[198:201], v190 offset:50176
	ds_read_b128 v[202:205], v190 offset:51200
	ds_read_b128 v[206:209], v190 offset:52224
	ds_read_b128 v[210:213], v190 offset:53248
	ds_read_b128 v[214:217], v190 offset:54272
	ds_read_b128 v[218:221], v190 offset:55296
	ds_read_b128 v[222:225], v190 offset:56320
	global_load_lds_dwordx4 v[150:151], off
	s_add_i32 m0, s48, 0x2000
	s_add_u32 s46, s46, 0x40080
	v_lshl_add_u64 v[150:151], v[226:227], 0, s[26:27]
	s_addc_u32 s47, s47, 0
	s_add_i32 s48, s51, s56
	global_load_lds_dwordx4 v[150:151], off
	v_lshl_add_u64 v[150:151], s[46:47], 0, v[130:131]
	s_mov_b32 m0, s48
	s_nop 0
	global_load_lds_dwordx4 v[150:151], off
	v_lshl_add_u64 v[150:151], s[46:47], 0, v[134:135]
	s_add_i32 m0, s48, 0x2000
	s_nop 0
	global_load_lds_dwordx4 v[150:151], off
	v_lshl_add_u64 v[150:151], v[228:229], 0, s[26:27]
	s_mov_b32 m0, s63
	s_nop 0
	global_load_lds_dwordx4 v[150:151], off
	v_lshl_add_u64 v[150:151], v[230:231], 0, s[26:27]
	s_mov_b32 m0, s64
	s_nop 0
	global_load_lds_dwordx4 v[150:151], off
	s_waitcnt vmcnt(8)
	s_waitcnt lgkmcnt(0)
	s_barrier
	s_setprio 1
	s_waitcnt lgkmcnt(0)
	v_mfma_f32_16x16x32_bf16 v[60:63], v[156:159], v[194:197], v[60:63]
	v_mfma_f32_16x16x32_bf16 v[44:47], v[156:159], v[202:205], v[44:47]
	v_mfma_f32_16x16x32_bf16 v[28:31], v[156:159], v[210:213], v[28:31]
	v_mfma_f32_16x16x32_bf16 v[12:15], v[156:159], v[218:221], v[12:15]
	v_mfma_f32_16x16x32_bf16 v[8:11], v[164:167], v[218:221], v[8:11]
	v_mfma_f32_16x16x32_bf16 v[24:27], v[164:167], v[210:213], v[24:27]
	v_mfma_f32_16x16x32_bf16 v[40:43], v[164:167], v[202:205], v[40:43]
	v_mfma_f32_16x16x32_bf16 v[56:59], v[164:167], v[194:197], v[56:59]
	v_mfma_f32_16x16x32_bf16 v[60:63], v[160:163], v[198:201], v[60:63]
	v_mfma_f32_16x16x32_bf16 v[44:47], v[160:163], v[206:209], v[44:47]
	v_mfma_f32_16x16x32_bf16 v[28:31], v[160:163], v[214:217], v[28:31]
	v_mfma_f32_16x16x32_bf16 v[12:15], v[160:163], v[222:225], v[12:15]
	v_mfma_f32_16x16x32_bf16 v[8:11], v[168:171], v[222:225], v[8:11]
	v_mfma_f32_16x16x32_bf16 v[24:27], v[168:171], v[214:217], v[24:27]
	v_mfma_f32_16x16x32_bf16 v[40:43], v[168:171], v[206:209], v[40:43]
	v_mfma_f32_16x16x32_bf16 v[56:59], v[168:171], v[198:201], v[56:59]
	s_setprio 0
	s_setprio 1
	v_mfma_f32_16x16x32_bf16 v[52:55], v[172:175], v[194:197], v[52:55]
	v_mfma_f32_16x16x32_bf16 v[36:39], v[172:175], v[202:205], v[36:39]
	v_mfma_f32_16x16x32_bf16 v[20:23], v[172:175], v[210:213], v[20:23]
	v_mfma_f32_16x16x32_bf16 v[4:7], v[172:175], v[218:221], v[4:7]
	v_mfma_f32_16x16x32_bf16 v[0:3], v[180:183], v[218:221], v[0:3]
	v_mfma_f32_16x16x32_bf16 v[16:19], v[180:183], v[210:213], v[16:19]
	v_mfma_f32_16x16x32_bf16 v[32:35], v[180:183], v[202:205], v[32:35]
	v_mfma_f32_16x16x32_bf16 v[48:51], v[180:183], v[194:197], v[48:51]
	v_mfma_f32_16x16x32_bf16 v[52:55], v[176:179], v[198:201], v[52:55]
	v_mfma_f32_16x16x32_bf16 v[36:39], v[176:179], v[206:209], v[36:39]
	v_mfma_f32_16x16x32_bf16 v[20:23], v[176:179], v[214:217], v[20:23]
	v_mfma_f32_16x16x32_bf16 v[4:7], v[176:179], v[222:225], v[4:7]
	v_mfma_f32_16x16x32_bf16 v[0:3], v[184:187], v[222:225], v[0:3]
	v_mfma_f32_16x16x32_bf16 v[16:19], v[184:187], v[214:217], v[16:19]
	v_mfma_f32_16x16x32_bf16 v[32:35], v[184:187], v[206:209], v[32:35]
	v_mfma_f32_16x16x32_bf16 v[48:51], v[184:187], v[198:201], v[48:51]
	s_setprio 0
	s_barrier
	s_add_i32 s79, s79, 2
	s_add_u32 s35, s35, 0x100
	s_addc_u32 s78, s78, 0
	s_add_u32 s40, s40, 0x100
	s_addc_u32 s41, s41, 0
	s_cmp_gt_u32 s79, 13
	s_cbranch_scc0 .LBB0_1020
	s_and_b64 vcc, exec, s[28:29]
	s_cbranch_vccz .LBB0_1023
	s_barrier

; #define PG8_STAGE(bufoff, gbase, voff) do { _Pragma("unroll") for (int _i = 0; _i < 2; ++_i) \
;         __builtin_amdgcn_global_load_lds((const unsigned*)((const char*)(gbase) + (voff)[_i]), (LAS unsigned*)(lds + (bufoff) + ldsw + _i * 8192), 16, 0, 0); } while (0)
; #define PG8_LDA(dst, b, h) do { _Pragma("unroll") for (int m = 0; m < 4; ++m) _Pragma("unroll") for (int k = 0; k < 2; ++k) dst[m][k] = *(const LAS bf16x8*)(lds + PG8_SA(b, h) + aoff + m * 2048 + k * 1024); } while (0)
; #define PG8_LDB(dst, b, h) do { _Pragma("unroll") for (int n = 0; n < 2; ++n) _Pragma("unroll") for (int k = 0; k < 2; ++k) dst[n][k] = *(const LAS bf16x8*)(lds + PG8_SB(b, h) + boff + n * 2048 + k * 1024); } while (0)
; #define PG8_MMA(ai, bj, At, Bt) do { __builtin_amdgcn_s_setprio(1); _Pragma("unroll") for (int m = 0; m < 4; ++m) _Pragma("unroll") for (int n = 0; n < 2; ++n) _Pragma("unroll") for (int k = 0; k < 2; ++k) \
;         acc[ai][bj][m][n] = __builtin_amdgcn_mfma_f32_16x16x32_bf16(Bt[n][k], At[m][k], acc[ai][bj][m][n], 0, 0, 0); __builtin_amdgcn_s_setprio(0); } while (0)
; #define PG8_WAIT_V(n) asm volatile("s_waitcnt vmcnt(" #n ")" ::: "memory")
; #define PG8_WAIT_L(n) asm volatile("s_waitcnt lgkmcnt(" #n ")" ::: "memory")
; template <class Epi>
; __device__ __forceinline__ void gemm_phase(LAS unsigned char* lds, const Gemm g, const StaticOrder& S, const Epi& E) {
;     ...
;         const bool has_next = S.next(ui + 1, nxt);
;         const char* nA = has_next ? (const char*)g.A + (size_t)nxt.pm * tstepA : cA; const char* nB = has_next ? (const char*)g.Bt + (size_t)nxt.pn * tstepB : cB;
;         for (int t = 0; t < nt; t += 2) {
;             const bool last = (t == nt - 2);
;             const char* a1 = cA + (unsigned)(t + 1) * kstep;
;             const char* a2 = last ? nA : cA + (unsigned)(t + 2) * kstep; const char* b2 = last ? nB : cB + (unsigned)(t + 2) * kstep;
;             const char* a3 = a2 + kstep; const char* b3 = b2 + kstep;
;             PG8_LDB(B0, 0, 0); PG8_LDB(B1, 0, 1); PG8_SCHED; PG8_LDA(At, 0, 0); PG8_STAGE(PG8_SA(1, 1), a1 + hstepA, voffA);
;             PG8_WAIT_V(8); PG8_WAIT_L(0); PG8_BAR; PG8_MMA(0, 0, At, B0); PG8_MMA(0, 1, At, B1); PG8_BAR; PG8_SCHED;
;             PG8_LDA(At, 0, 1); PG8_STAGE(PG8_SB(0, 0), b2, voffB); PG8_STAGE(PG8_SB(0, 1), b2 + hstepB, voffB); PG8_STAGE(PG8_SA(0, 0), a2, voffA);
.LBB0_1339:
	ds_read_b128 v[128:131], v192
	ds_read_b128 v[132:135], v192 offset:1024
	ds_read_b128 v[136:139], v192 offset:2048
	ds_read_b128 v[140:143], v192 offset:3072
	ds_read_b128 v[144:147], v193
	ds_read_b128 v[148:151], v193 offset:1024
	ds_read_b128 v[172:175], v193 offset:2048
	ds_read_b128 v[176:179], v193 offset:3072
	s_add_u32 s10, s34, 0x100
	s_addc_u32 s11, s35, 0
	s_cmp_eq_u32 s66, 12
	s_cselect_b32 s39, s29, s11
	s_cselect_b32 s38, s28, s10
	s_cselect_b32 s37, s27, s65
	s_cselect_b32 s36, s63, s64
	v_lshl_add_u64 v[188:189], s[34:35], 0, v[166:167]
	s_add_i32 m0, s46, 0xc000
	ds_read_b128 v[180:183], v194
	ds_read_b128 v[184:187], v194 offset:1024
	ds_read_b128 v[196:199], v194 offset:2048
	ds_read_b128 v[200:203], v194 offset:3072
	ds_read_b128 v[204:207], v194 offset:4096
	ds_read_b128 v[208:211], v194 offset:5120
	ds_read_b128 v[212:215], v194 offset:6144
	ds_read_b128 v[216:219], v194 offset:7168
	global_load_lds_dwordx4 v[188:189], off
	v_lshl_add_u64 v[188:189], s[34:35], 0, v[164:165]
	s_add_i32 m0, s46, 0xe000
	s_nop 0
	global_load_lds_dwordx4 v[188:189], off
	s_waitcnt vmcnt(8)
	s_waitcnt lgkmcnt(0)
	s_barrier
	s_setprio 1
	s_waitcnt lgkmcnt(0)
	v_mfma_f32_16x16x32_bf16 v[124:127], v[128:131], v[180:183], v[124:127]
	v_mfma_f32_16x16x32_bf16 v[108:111], v[128:131], v[196:199], v[108:111]
	v_mfma_f32_16x16x32_bf16 v[92:95], v[128:131], v[204:207], v[92:95]
	v_mfma_f32_16x16x32_bf16 v[76:79], v[128:131], v[212:215], v[76:79]
	v_mfma_f32_16x16x32_bf16 v[72:75], v[136:139], v[212:215], v[72:75]
	v_mfma_f32_16x16x32_bf16 v[88:91], v[136:139], v[204:207], v[88:91]
	v_mfma_f32_16x16x32_bf16 v[104:107], v[136:139], v[196:199], v[104:107]
	v_mfma_f32_16x16x32_bf16 v[120:123], v[136:139], v[180:183], v[120:123]
	v_mfma_f32_16x16x32_bf16 v[124:127], v[132:135], v[184:187], v[124:127]
	v_mfma_f32_16x16x32_bf16 v[108:111], v[132:135], v[200:203], v[108:111]
	v_mfma_f32_16x16x32_bf16 v[92:95], v[132:135], v[208:211], v[92:95]
	v_mfma_f32_16x16x32_bf16 v[76:79], v[132:135], v[216:219], v[76:79]
	v_mfma_f32_16x16x32_bf16 v[72:75], v[140:143], v[216:219], v[72:75]
	v_mfma_f32_16x16x32_bf16 v[88:91], v[140:143], v[208:211], v[88:91]
	v_mfma_f32_16x16x32_bf16 v[104:107], v[140:143], v[200:203], v[104:107]
	v_mfma_f32_16x16x32_bf16 v[120:123], v[140:143], v[184:187], v[120:123]
	s_setprio 0
	s_setprio 1
	v_mfma_f32_16x16x32_bf16 v[116:119], v[144:147], v[180:183], v[116:119]
	v_mfma_f32_16x16x32_bf16 v[100:103], v[144:147], v[196:199], v[100:103]
	v_mfma_f32_16x16x32_bf16 v[84:87], v[144:147], v[204:207], v[84:87]
	v_mfma_f32_16x16x32_bf16 v[68:71], v[144:147], v[212:215], v[68:71]
	v_mfma_f32_16x16x32_bf16 v[64:67], v[172:175], v[212:215], v[64:67]
	v_mfma_f32_16x16x32_bf16 v[80:83], v[172:175], v[204:207], v[80:83]
	v_mfma_f32_16x16x32_bf16 v[96:99], v[172:175], v[196:199], v[96:99]
	v_mfma_f32_16x16x32_bf16 v[112:115], v[172:175], v[180:183], v[112:115]
	v_mfma_f32_16x16x32_bf16 v[116:119], v[148:151], v[184:187], v[116:119]
	v_mfma_f32_16x16x32_bf16 v[100:103], v[148:151], v[200:203], v[100:103]
	v_mfma_f32_16x16x32_bf16 v[84:87], v[148:151], v[208:211], v[84:87]
	v_mfma_f32_16x16x32_bf16 v[68:71], v[148:151], v[216:219], v[68:71]
	v_mfma_f32_16x16x32_bf16 v[64:67], v[176:179], v[216:219], v[64:67]
	v_mfma_f32_16x16x32_bf16 v[80:83], v[176:179], v[208:211], v[80:83]
	v_mfma_f32_16x16x32_bf16 v[96:99], v[176:179], v[200:203], v[96:99]
	v_mfma_f32_16x16x32_bf16 v[112:115], v[176:179], v[184:187], v[112:115]
	s_setprio 0
	s_barrier
	s_add_i32 s34, s59, s45
	v_lshl_add_u64 v[188:189], s[36:37], 0, v[158:159]
	s_mov_b32 m0, s34
	ds_read_b128 v[180:183], v194 offset:16384
	ds_read_b128 v[184:187], v194 offset:17408
	ds_read_b128 v[196:199], v194 offset:18432
	ds_read_b128 v[200:203], v194 offset:19456
	ds_read_b128 v[204:207], v194 offset:20480
	ds_read_b128 v[208:211], v194 offset:21504
	ds_read_b128 v[212:215], v194 offset:22528
	ds_read_b128 v[216:219], v194 offset:23552
	global_load_lds_dwordx4 v[188:189], off
	s_add_i32 m0, s34, 0x2000
	s_add_u32 s34, s36, 0x40000
	v_lshl_add_u64 v[220:221], s[36:37], 0, v[162:163]
	s_addc_u32 s35, s37, 0
	s_add_i32 s50, s60, s45
	global_load_lds_dwordx4 v[220:221], off
	v_lshl_add_u64 v[222:223], s[34:35], 0, v[158:159]
	s_mov_b32 m0, s50
	v_lshl_add_u64 v[224:225], s[38:39], 0, v[160:161]
	global_load_lds_dwordx4 v[222:223], off
	v_lshl_add_u64 v[222:223], s[34:35], 0, v[162:163]
	s_add_i32 m0, s50, 0x2000
	s_nop 0
	global_load_lds_dwordx4 v[222:223], off
	v_lshl_add_u64 v[222:223], s[38:39], 0, v[156:157]
	s_mov_b32 m0, s46
	s_nop 0
	global_load_lds_dwordx4 v[222:223], off
	s_mov_b32 m0, s47
	s_nop 0
	global_load_lds_dwordx4 v[224:225], off
	s_waitcnt vmcnt(8)
	s_waitcnt lgkmcnt(0)
	s_barrier
; #define PG8_STAGE(bufoff, gbase, voff) do { _Pragma("unroll") for (int _i = 0; _i < 2; ++_i) \
;         __builtin_amdgcn_global_load_lds((const unsigned*)((const char*)(gbase) + (voff)[_i]), (LAS unsigned*)(lds + (bufoff) + ldsw + _i * 8192), 16, 0, 0); } while (0)
; #define PG8_LDA(dst, b, h) do { _Pragma("unroll") for (int m = 0; m < 4; ++m) _Pragma("unroll") for (int k = 0; k < 2; ++k) dst[m][k] = *(const LAS bf16x8*)(lds + PG8_SA(b, h) + aoff + m * 2048 + k * 1024); } while (0)
; #define PG8_LDB(dst, b, h) do { _Pragma("unroll") for (int n = 0; n < 2; ++n) _Pragma("unroll") for (int k = 0; k < 2; ++k) dst[n][k] = *(const LAS bf16x8*)(lds + PG8_SB(b, h) + boff + n * 2048 + k * 1024); } while (0)
; #define PG8_MMA(ai, bj, At, Bt) do { __builtin_amdgcn_s_setprio(1); _Pragma("unroll") for (int m = 0; m < 4; ++m) _Pragma("unroll") for (int n = 0; n < 2; ++n) _Pragma("unroll") for (int k = 0; k < 2; ++k) \
;         acc[ai][bj][m][n] = __builtin_amdgcn_mfma_f32_16x16x32_bf16(Bt[n][k], At[m][k], acc[ai][bj][m][n], 0, 0, 0); __builtin_amdgcn_s_setprio(0); } while (0)
; #define PG8_WAIT_V(n) asm volatile("s_waitcnt vmcnt(" #n ")" ::: "memory")
; #define PG8_WAIT_L(n) asm volatile("s_waitcnt lgkmcnt(" #n ")" ::: "memory")
; #define PG8_BAR __builtin_amdgcn_s_barrier()
; #define PG8_SCHED __builtin_amdgcn_sched_barrier(0)
; template <class Epi>
; __device__ __forceinline__ void gemm_phase(LAS unsigned char* lds, const Gemm g, const StaticOrder& S, const Epi& E) {
;     ...
;             PG8_WAIT_V(8); PG8_WAIT_L(0); PG8_BAR; PG8_MMA(1, 0, At, B0); PG8_MMA(1, 1, At, B1); PG8_BAR; PG8_SCHED;
;             PG8_LDB(B0, 1, 0); PG8_LDB(B1, 1, 1); PG8_SCHED; PG8_LDA(At, 1, 0); PG8_STAGE(PG8_SA(0, 1), a2 + hstepA, voffA);
;             PG8_WAIT_V(8); PG8_WAIT_L(0); PG8_BAR; PG8_MMA(0, 0, At, B0); PG8_MMA(0, 1, At, B1); PG8_BAR; PG8_SCHED;
	s_setprio 1
	s_waitcnt lgkmcnt(0)
	v_mfma_f32_16x16x32_bf16 v[60:63], v[128:131], v[180:183], v[60:63]
	v_mfma_f32_16x16x32_bf16 v[44:47], v[128:131], v[196:199], v[44:47]
	v_mfma_f32_16x16x32_bf16 v[28:31], v[128:131], v[204:207], v[28:31]
	v_mfma_f32_16x16x32_bf16 v[12:15], v[128:131], v[212:215], v[12:15]
	v_mfma_f32_16x16x32_bf16 v[8:11], v[136:139], v[212:215], v[8:11]
	v_mfma_f32_16x16x32_bf16 v[24:27], v[136:139], v[204:207], v[24:27]
	v_mfma_f32_16x16x32_bf16 v[40:43], v[136:139], v[196:199], v[40:43]
	v_mfma_f32_16x16x32_bf16 v[56:59], v[136:139], v[180:183], v[56:59]
	v_mfma_f32_16x16x32_bf16 v[60:63], v[132:135], v[184:187], v[60:63]
	v_mfma_f32_16x16x32_bf16 v[44:47], v[132:135], v[200:203], v[44:47]
	v_mfma_f32_16x16x32_bf16 v[28:31], v[132:135], v[208:211], v[28:31]
	v_mfma_f32_16x16x32_bf16 v[12:15], v[132:135], v[216:219], v[12:15]
	v_mfma_f32_16x16x32_bf16 v[8:11], v[140:143], v[216:219], v[8:11]
	v_mfma_f32_16x16x32_bf16 v[24:27], v[140:143], v[208:211], v[24:27]
	v_mfma_f32_16x16x32_bf16 v[40:43], v[140:143], v[200:203], v[40:43]
	v_mfma_f32_16x16x32_bf16 v[56:59], v[140:143], v[184:187], v[56:59]
	s_setprio 0
	s_setprio 1
	v_mfma_f32_16x16x32_bf16 v[52:55], v[144:147], v[180:183], v[52:55]
	v_mfma_f32_16x16x32_bf16 v[36:39], v[144:147], v[196:199], v[36:39]
	v_mfma_f32_16x16x32_bf16 v[20:23], v[144:147], v[204:207], v[20:23]
	v_mfma_f32_16x16x32_bf16 v[4:7], v[144:147], v[212:215], v[4:7]
	v_mfma_f32_16x16x32_bf16 v[0:3], v[172:175], v[212:215], v[0:3]
	v_mfma_f32_16x16x32_bf16 v[16:19], v[172:175], v[204:207], v[16:19]
	v_mfma_f32_16x16x32_bf16 v[32:35], v[172:175], v[196:199], v[32:35]
	v_mfma_f32_16x16x32_bf16 v[48:51], v[172:175], v[180:183], v[48:51]
	v_mfma_f32_16x16x32_bf16 v[52:55], v[148:151], v[184:187], v[52:55]
	v_mfma_f32_16x16x32_bf16 v[36:39], v[148:151], v[200:203], v[36:39]
	v_mfma_f32_16x16x32_bf16 v[20:23], v[148:151], v[208:211], v[20:23]
	v_mfma_f32_16x16x32_bf16 v[4:7], v[148:151], v[216:219], v[4:7]
	v_mfma_f32_16x16x32_bf16 v[0:3], v[176:179], v[216:219], v[0:3]
	v_mfma_f32_16x16x32_bf16 v[16:19], v[176:179], v[208:211], v[16:19]
	v_mfma_f32_16x16x32_bf16 v[32:35], v[176:179], v[200:203], v[32:35]
	v_mfma_f32_16x16x32_bf16 v[48:51], v[176:179], v[184:187], v[48:51]
	s_setprio 0
	s_barrier
	s_add_i32 s50, 0, 0x18000
	s_add_i32 s51, 0, 0x1c000
	v_add_u32_e32 v140, s50, v190
	v_add_u32_e32 v176, s51, v190
	ds_read_b128 v[128:131], v140
	ds_read_b128 v[132:135], v140 offset:1024
	ds_read_b128 v[136:139], v140 offset:2048
	ds_read_b128 v[140:143], v140 offset:3072
	ds_read_b128 v[144:147], v176
	ds_read_b128 v[148:151], v176 offset:1024
	ds_read_b128 v[172:175], v176 offset:2048
	ds_read_b128 v[176:179], v176 offset:3072
	s_add_u32 s34, s38, 0xc0000
	s_addc_u32 s35, s39, 0
	s_mov_b32 m0, s48
	v_lshl_add_u64 v[226:227], s[34:35], 0, v[156:157]
	ds_read_b128 v[180:183], v194 offset:32768
	ds_read_b128 v[184:187], v194 offset:33792
	ds_read_b128 v[196:199], v194 offset:34816
	ds_read_b128 v[200:203], v194 offset:35840
	ds_read_b128 v[204:207], v194 offset:36864
	ds_read_b128 v[208:211], v194 offset:37888
	ds_read_b128 v[212:215], v194 offset:38912
	ds_read_b128 v[216:219], v194 offset:39936
	global_load_lds_dwordx4 v[226:227], off
	v_lshl_add_u64 v[226:227], s[34:35], 0, v[160:161]
	s_mov_b32 m0, s49
	s_nop 0
	global_load_lds_dwordx4 v[226:227], off
	s_waitcnt vmcnt(8)
	s_waitcnt lgkmcnt(0)
	s_barrier
	s_setprio 1
	s_waitcnt lgkmcnt(0)
	v_mfma_f32_16x16x32_bf16 v[124:127], v[128:131], v[180:183], v[124:127]
	v_mfma_f32_16x16x32_bf16 v[108:111], v[128:131], v[196:199], v[108:111]
	v_mfma_f32_16x16x32_bf16 v[92:95], v[128:131], v[204:207], v[92:95]
	v_mfma_f32_16x16x32_bf16 v[76:79], v[128:131], v[212:215], v[76:79]
	v_mfma_f32_16x16x32_bf16 v[72:75], v[136:139], v[212:215], v[72:75]
	v_mfma_f32_16x16x32_bf16 v[88:91], v[136:139], v[204:207], v[88:91]
	v_mfma_f32_16x16x32_bf16 v[104:107], v[136:139], v[196:199], v[104:107]
	v_mfma_f32_16x16x32_bf16 v[120:123], v[136:139], v[180:183], v[120:123]
	v_mfma_f32_16x16x32_bf16 v[124:127], v[132:135], v[184:187], v[124:127]
	v_mfma_f32_16x16x32_bf16 v[108:111], v[132:135], v[200:203], v[108:111]
	v_mfma_f32_16x16x32_bf16 v[92:95], v[132:135], v[208:211], v[92:95]
	v_mfma_f32_16x16x32_bf16 v[76:79], v[132:135], v[216:219], v[76:79]
	v_mfma_f32_16x16x32_bf16 v[72:75], v[140:143], v[216:219], v[72:75]
	v_mfma_f32_16x16x32_bf16 v[88:91], v[140:143], v[208:211], v[88:91]
	v_mfma_f32_16x16x32_bf16 v[104:107], v[140:143], v[200:203], v[104:107]
	v_mfma_f32_16x16x32_bf16 v[120:123], v[140:143], v[184:187], v[120:123]
	s_setprio 0
	s_setprio 1
	v_mfma_f32_16x16x32_bf16 v[116:119], v[144:147], v[180:183], v[116:119]
	v_mfma_f32_16x16x32_bf16 v[100:103], v[144:147], v[196:199], v[100:103]
	v_mfma_f32_16x16x32_bf16 v[84:87], v[144:147], v[204:207], v[84:87]
	v_mfma_f32_16x16x32_bf16 v[68:71], v[144:147], v[212:215], v[68:71]
	v_mfma_f32_16x16x32_bf16 v[64:67], v[172:175], v[212:215], v[64:67]
	v_mfma_f32_16x16x32_bf16 v[80:83], v[172:175], v[204:207], v[80:83]
	v_mfma_f32_16x16x32_bf16 v[96:99], v[172:175], v[196:199], v[96:99]
	v_mfma_f32_16x16x32_bf16 v[112:115], v[172:175], v[180:183], v[112:115]
	v_mfma_f32_16x16x32_bf16 v[116:119], v[148:151], v[184:187], v[116:119]
	v_mfma_f32_16x16x32_bf16 v[100:103], v[148:151], v[200:203], v[100:103]
	v_mfma_f32_16x16x32_bf16 v[84:87], v[148:151], v[208:211], v[84:87]
	v_mfma_f32_16x16x32_bf16 v[68:71], v[148:151], v[216:219], v[68:71]
	v_mfma_f32_16x16x32_bf16 v[64:67], v[176:179], v[216:219], v[64:67]
	v_mfma_f32_16x16x32_bf16 v[80:83], v[176:179], v[208:211], v[80:83]
	v_mfma_f32_16x16x32_bf16 v[96:99], v[176:179], v[200:203], v[96:99]
	v_mfma_f32_16x16x32_bf16 v[112:115], v[176:179], v[184:187], v[112:115]
	s_setprio 0
	s_barrier
; #define PG8_STAGE(bufoff, gbase, voff) do { _Pragma("unroll") for (int _i = 0; _i < 2; ++_i) \
;         __builtin_amdgcn_global_load_lds((const unsigned*)((const char*)(gbase) + (voff)[_i]), (LAS unsigned*)(lds + (bufoff) + ldsw + _i * 8192), 16, 0, 0); } while (0)
; #define PG8_LDA(dst, b, h) do { _Pragma("unroll") for (int m = 0; m < 4; ++m) _Pragma("unroll") for (int k = 0; k < 2; ++k) dst[m][k] = *(const LAS bf16x8*)(lds + PG8_SA(b, h) + aoff + m * 2048 + k * 1024); } while (0)
; #define PG8_MMA(ai, bj, At, Bt) do { __builtin_amdgcn_s_setprio(1); _Pragma("unroll") for (int m = 0; m < 4; ++m) _Pragma("unroll") for (int n = 0; n < 2; ++n) _Pragma("unroll") for (int k = 0; k < 2; ++k) \
;         acc[ai][bj][m][n] = __builtin_amdgcn_mfma_f32_16x16x32_bf16(Bt[n][k], At[m][k], acc[ai][bj][m][n], 0, 0, 0); __builtin_amdgcn_s_setprio(0); } while (0)
; #define PG8_WAIT_V(n) asm volatile("s_waitcnt vmcnt(" #n ")" ::: "memory")
; #define PG8_WAIT_L(n) asm volatile("s_waitcnt lgkmcnt(" #n ")" ::: "memory")
; #define PG8_BAR __builtin_amdgcn_s_barrier()
; #define PG8_SCHED __builtin_amdgcn_sched_barrier(0)
; template <class Epi>
; __device__ __forceinline__ void gemm_phase(LAS unsigned char* lds, const Gemm g, const StaticOrder& S, const Epi& E) {
;     ...
;             PG8_LDA(At, 1, 1); PG8_STAGE(PG8_SB(1, 0), b3, voffB); PG8_STAGE(PG8_SB(1, 1), b3 + hstepB, voffB); PG8_STAGE(PG8_SA(1, 0), a3, voffA);
;             PG8_WAIT_V(8); PG8_WAIT_L(0); PG8_BAR; PG8_MMA(1, 0, At, B0); PG8_MMA(1, 1, At, B1); PG8_BAR; PG8_SCHED;
;         }
;         if (wr == 0) PG8_BAR;
	s_add_i32 s34, s50, s45
	v_lshl_add_u64 v[188:189], v[188:189], 0, s[22:23]
	s_mov_b32 m0, s34
	ds_read_b128 v[180:183], v194 offset:49152
	ds_read_b128 v[184:187], v194 offset:50176
	ds_read_b128 v[196:199], v194 offset:51200
	ds_read_b128 v[200:203], v194 offset:52224
	ds_read_b128 v[204:207], v194 offset:53248
	ds_read_b128 v[208:211], v194 offset:54272
	ds_read_b128 v[212:215], v194 offset:55296
	ds_read_b128 v[216:219], v194 offset:56320
	global_load_lds_dwordx4 v[188:189], off
	s_add_i32 m0, s34, 0x2000
	s_add_u32 s34, s36, 0x40080
	v_lshl_add_u64 v[188:189], v[220:221], 0, s[22:23]
	s_addc_u32 s35, s37, 0
	s_add_i32 s36, s51, s45
	global_load_lds_dwordx4 v[188:189], off
	v_lshl_add_u64 v[188:189], s[34:35], 0, v[158:159]
	s_mov_b32 m0, s36
	s_nop 0
	global_load_lds_dwordx4 v[188:189], off
	v_lshl_add_u64 v[188:189], s[34:35], 0, v[162:163]
	s_add_i32 m0, s36, 0x2000
	s_nop 0
	global_load_lds_dwordx4 v[188:189], off
	v_lshl_add_u64 v[188:189], v[222:223], 0, s[22:23]
	s_mov_b32 m0, s53
	s_nop 0
	global_load_lds_dwordx4 v[188:189], off
	v_lshl_add_u64 v[188:189], v[224:225], 0, s[22:23]
	s_mov_b32 m0, s54
	s_nop 0
	global_load_lds_dwordx4 v[188:189], off
	s_waitcnt vmcnt(8)
	s_waitcnt lgkmcnt(0)
	s_barrier
	s_setprio 1
	s_waitcnt lgkmcnt(0)
	v_mfma_f32_16x16x32_bf16 v[60:63], v[128:131], v[180:183], v[60:63]
	v_mfma_f32_16x16x32_bf16 v[44:47], v[128:131], v[196:199], v[44:47]
	v_mfma_f32_16x16x32_bf16 v[28:31], v[128:131], v[204:207], v[28:31]
	v_mfma_f32_16x16x32_bf16 v[12:15], v[128:131], v[212:215], v[12:15]
	v_mfma_f32_16x16x32_bf16 v[8:11], v[136:139], v[212:215], v[8:11]
	v_mfma_f32_16x16x32_bf16 v[24:27], v[136:139], v[204:207], v[24:27]
	v_mfma_f32_16x16x32_bf16 v[40:43], v[136:139], v[196:199], v[40:43]
	v_mfma_f32_16x16x32_bf16 v[56:59], v[136:139], v[180:183], v[56:59]
	v_mfma_f32_16x16x32_bf16 v[60:63], v[132:135], v[184:187], v[60:63]
	v_mfma_f32_16x16x32_bf16 v[44:47], v[132:135], v[200:203], v[44:47]
	v_mfma_f32_16x16x32_bf16 v[28:31], v[132:135], v[208:211], v[28:31]
	v_mfma_f32_16x16x32_bf16 v[12:15], v[132:135], v[216:219], v[12:15]
	v_mfma_f32_16x16x32_bf16 v[8:11], v[140:143], v[216:219], v[8:11]
	v_mfma_f32_16x16x32_bf16 v[24:27], v[140:143], v[208:211], v[24:27]
	v_mfma_f32_16x16x32_bf16 v[40:43], v[140:143], v[200:203], v[40:43]
	v_mfma_f32_16x16x32_bf16 v[56:59], v[140:143], v[184:187], v[56:59]
	s_setprio 0
	s_setprio 1
	v_mfma_f32_16x16x32_bf16 v[52:55], v[144:147], v[180:183], v[52:55]
	v_mfma_f32_16x16x32_bf16 v[36:39], v[144:147], v[196:199], v[36:39]
	v_mfma_f32_16x16x32_bf16 v[20:23], v[144:147], v[204:207], v[20:23]
	v_mfma_f32_16x16x32_bf16 v[4:7], v[144:147], v[212:215], v[4:7]
	v_mfma_f32_16x16x32_bf16 v[0:3], v[172:175], v[212:215], v[0:3]
	v_mfma_f32_16x16x32_bf16 v[16:19], v[172:175], v[204:207], v[16:19]
	v_mfma_f32_16x16x32_bf16 v[32:35], v[172:175], v[196:199], v[32:35]
	v_mfma_f32_16x16x32_bf16 v[48:51], v[172:175], v[180:183], v[48:51]
	v_mfma_f32_16x16x32_bf16 v[52:55], v[148:151], v[184:187], v[52:55]
	v_mfma_f32_16x16x32_bf16 v[36:39], v[148:151], v[200:203], v[36:39]
	v_mfma_f32_16x16x32_bf16 v[20:23], v[148:151], v[208:211], v[20:23]
	v_mfma_f32_16x16x32_bf16 v[4:7], v[148:151], v[216:219], v[4:7]
	v_mfma_f32_16x16x32_bf16 v[0:3], v[176:179], v[216:219], v[0:3]
	v_mfma_f32_16x16x32_bf16 v[16:19], v[176:179], v[208:211], v[16:19]
	v_mfma_f32_16x16x32_bf16 v[32:35], v[176:179], v[200:203], v[32:35]
	v_mfma_f32_16x16x32_bf16 v[48:51], v[176:179], v[184:187], v[48:51]
	s_setprio 0
	s_barrier
	s_add_i32 s66, s66, 2
	s_add_u32 s64, s64, 0x100
	s_addc_u32 s65, s65, 0
	s_cmp_gt_u32 s66, 13
	s_mov_b64 s[34:35], s[10:11]
	s_cbranch_scc0 .LBB0_1339
	s_and_b64 vcc, exec, s[24:25]
	s_cbranch_vccz .LBB0_1342
	s_barrier

; #define PG8_STAGE(bufoff, gbase, voff) do { _Pragma("unroll") for (int _i = 0; _i < 2; ++_i) \
;         __builtin_amdgcn_global_load_lds((const unsigned*)((const char*)(gbase) + (voff)[_i]), (LAS unsigned*)(lds + (bufoff) + ldsw + _i * 8192), 16, 0, 0); } while (0)
; #define PG8_LDA(dst, b, h) do { _Pragma("unroll") for (int m = 0; m < 4; ++m) _Pragma("unroll") for (int k = 0; k < 2; ++k) dst[m][k] = *(const LAS bf16x8*)(lds + PG8_SA(b, h) + aoff + m * 2048 + k * 1024); } while (0)
; #define PG8_LDB(dst, b, h) do { _Pragma("unroll") for (int n = 0; n < 2; ++n) _Pragma("unroll") for (int k = 0; k < 2; ++k) dst[n][k] = *(const LAS bf16x8*)(lds + PG8_SB(b, h) + boff + n * 2048 + k * 1024); } while (0)
; #define PG8_MMA(ai, bj, At, Bt) do { __builtin_amdgcn_s_setprio(1); _Pragma("unroll") for (int m = 0; m < 4; ++m) _Pragma("unroll") for (int n = 0; n < 2; ++n) _Pragma("unroll") for (int k = 0; k < 2; ++k) \
;         acc[ai][bj][m][n] = __builtin_amdgcn_mfma_f32_16x16x32_bf16(Bt[n][k], At[m][k], acc[ai][bj][m][n], 0, 0, 0); __builtin_amdgcn_s_setprio(0); } while (0)
; #define PG8_WAIT_V(n) asm volatile("s_waitcnt vmcnt(" #n ")" ::: "memory")
; #define PG8_WAIT_L(n) asm volatile("s_waitcnt lgkmcnt(" #n ")" ::: "memory")
; template <class Epi>
; __device__ __forceinline__ void gemm_phase(LAS unsigned char* lds, const Gemm g, const StaticOrder& S, const Epi& E) {
;     ...
;         const bool has_next = S.next(ui + 1, nxt);
;         const char* nA = has_next ? (const char*)g.A + (size_t)nxt.pm * tstepA : cA; const char* nB = has_next ? (const char*)g.Bt + (size_t)nxt.pn * tstepB : cB;
;         for (int t = 0; t < nt; t += 2) {
;             const bool last = (t == nt - 2);
;             const char* a1 = cA + (unsigned)(t + 1) * kstep;
;             const char* a2 = last ? nA : cA + (unsigned)(t + 2) * kstep; const char* b2 = last ? nB : cB + (unsigned)(t + 2) * kstep;
;             const char* a3 = a2 + kstep; const char* b3 = b2 + kstep;
;             PG8_LDB(B0, 0, 0); PG8_LDB(B1, 0, 1); PG8_SCHED; PG8_LDA(At, 0, 0); PG8_STAGE(PG8_SA(1, 1), a1 + hstepA, voffA);
;             PG8_WAIT_V(8); PG8_WAIT_L(0); PG8_BAR; PG8_MMA(0, 0, At, B0); PG8_MMA(0, 1, At, B1); PG8_BAR; PG8_SCHED;
;             PG8_LDA(At, 0, 1); PG8_STAGE(PG8_SB(0, 0), b2, voffB); PG8_STAGE(PG8_SB(0, 1), b2 + hstepB, voffB); PG8_STAGE(PG8_SA(0, 0), a2, voffA);
.LBB0_1415:
	ds_read_b128 v[146:149], v168
	ds_read_b128 v[156:159], v168 offset:1024
	ds_read_b128 v[160:163], v168 offset:2048
	ds_read_b128 v[174:177], v168 offset:3072
	ds_read_b128 v[178:181], v169
	ds_read_b128 v[182:185], v169 offset:1024
	ds_read_b128 v[186:189], v169 offset:2048
	ds_read_b128 v[190:193], v169 offset:3072
	s_add_u32 s28, s26, 0xfffc0080
	s_addc_u32 s29, s27, -1
	s_cmp_eq_u32 s59, 12
	s_cselect_b32 s31, s19, s29
	s_cselect_b32 s30, s55, s28
	s_cselect_b32 s29, s17, s58
	s_cselect_b32 s28, s56, s57
	v_lshl_add_u64 v[150:151], s[26:27], 0, v[140:141]
	s_add_i32 m0, s25, 0xc000
	ds_read_b128 v[194:197], v170
	ds_read_b128 v[198:201], v170 offset:1024
	ds_read_b128 v[202:205], v170 offset:2048
	ds_read_b128 v[206:209], v170 offset:3072
	ds_read_b128 v[210:213], v170 offset:4096
	ds_read_b128 v[214:217], v170 offset:5120
	ds_read_b128 v[218:221], v170 offset:6144
	ds_read_b128 v[222:225], v170 offset:7168
	global_load_lds_dwordx4 v[150:151], off
	v_lshl_add_u64 v[150:151], s[26:27], 0, v[138:139]
	s_add_i32 m0, s25, 0xe000
	s_nop 0
	global_load_lds_dwordx4 v[150:151], off
	s_waitcnt vmcnt(8)
	s_waitcnt lgkmcnt(0)
	s_barrier
	s_setprio 1
	s_waitcnt lgkmcnt(0)
	v_mfma_f32_16x16x32_bf16 v[124:127], v[146:149], v[194:197], v[124:127]
	v_mfma_f32_16x16x32_bf16 v[108:111], v[146:149], v[202:205], v[108:111]
	v_mfma_f32_16x16x32_bf16 v[92:95], v[146:149], v[210:213], v[92:95]
	v_mfma_f32_16x16x32_bf16 v[76:79], v[146:149], v[218:221], v[76:79]
	v_mfma_f32_16x16x32_bf16 v[68:71], v[160:163], v[218:221], v[68:71]
	v_mfma_f32_16x16x32_bf16 v[84:87], v[160:163], v[210:213], v[84:87]
	v_mfma_f32_16x16x32_bf16 v[100:103], v[160:163], v[202:205], v[100:103]
	v_mfma_f32_16x16x32_bf16 v[116:119], v[160:163], v[194:197], v[116:119]
	v_mfma_f32_16x16x32_bf16 v[124:127], v[156:159], v[198:201], v[124:127]
	v_mfma_f32_16x16x32_bf16 v[108:111], v[156:159], v[206:209], v[108:111]
	v_mfma_f32_16x16x32_bf16 v[92:95], v[156:159], v[214:217], v[92:95]
	v_mfma_f32_16x16x32_bf16 v[76:79], v[156:159], v[222:225], v[76:79]
	v_mfma_f32_16x16x32_bf16 v[68:71], v[174:177], v[222:225], v[68:71]
	v_mfma_f32_16x16x32_bf16 v[84:87], v[174:177], v[214:217], v[84:87]
	v_mfma_f32_16x16x32_bf16 v[100:103], v[174:177], v[206:209], v[100:103]
	v_mfma_f32_16x16x32_bf16 v[116:119], v[174:177], v[198:201], v[116:119]
	s_setprio 0
	s_setprio 1
	v_mfma_f32_16x16x32_bf16 v[120:123], v[178:181], v[194:197], v[120:123]
	v_mfma_f32_16x16x32_bf16 v[104:107], v[178:181], v[202:205], v[104:107]
	v_mfma_f32_16x16x32_bf16 v[88:91], v[178:181], v[210:213], v[88:91]
	v_mfma_f32_16x16x32_bf16 v[72:75], v[178:181], v[218:221], v[72:75]
	v_mfma_f32_16x16x32_bf16 v[64:67], v[186:189], v[218:221], v[64:67]
	v_mfma_f32_16x16x32_bf16 v[80:83], v[186:189], v[210:213], v[80:83]
	v_mfma_f32_16x16x32_bf16 v[96:99], v[186:189], v[202:205], v[96:99]
	v_mfma_f32_16x16x32_bf16 v[112:115], v[186:189], v[194:197], v[112:115]
	v_mfma_f32_16x16x32_bf16 v[120:123], v[182:185], v[198:201], v[120:123]
	v_mfma_f32_16x16x32_bf16 v[104:107], v[182:185], v[206:209], v[104:107]
	v_mfma_f32_16x16x32_bf16 v[88:91], v[182:185], v[214:217], v[88:91]
	v_mfma_f32_16x16x32_bf16 v[72:75], v[182:185], v[222:225], v[72:75]
	v_mfma_f32_16x16x32_bf16 v[64:67], v[190:193], v[222:225], v[64:67]
	v_mfma_f32_16x16x32_bf16 v[80:83], v[190:193], v[214:217], v[80:83]
	v_mfma_f32_16x16x32_bf16 v[96:99], v[190:193], v[206:209], v[96:99]
	v_mfma_f32_16x16x32_bf16 v[112:115], v[190:193], v[198:201], v[112:115]
	s_setprio 0
	s_barrier
	s_add_i32 s50, s52, s37
	v_lshl_add_u64 v[150:151], s[28:29], 0, v[132:133]
	s_mov_b32 m0, s50
	ds_read_b128 v[194:197], v170 offset:16384
	ds_read_b128 v[198:201], v170 offset:17408
	ds_read_b128 v[202:205], v170 offset:18432
	ds_read_b128 v[206:209], v170 offset:19456
	ds_read_b128 v[210:213], v170 offset:20480
	ds_read_b128 v[214:217], v170 offset:21504
	ds_read_b128 v[218:221], v170 offset:22528
	ds_read_b128 v[222:225], v170 offset:23552
	global_load_lds_dwordx4 v[150:151], off
	s_add_i32 m0, s50, 0x2000
	s_add_u32 s50, s28, 0x40000
	v_lshl_add_u64 v[164:165], s[28:29], 0, v[128:129]
	s_addc_u32 s51, s29, 0
	s_add_i32 s60, s53, s37
	global_load_lds_dwordx4 v[164:165], off
	v_lshl_add_u64 v[226:227], s[50:51], 0, v[132:133]
	s_mov_b32 m0, s60
	v_lshl_add_u64 v[228:229], s[30:31], 0, v[130:131]
	global_load_lds_dwordx4 v[226:227], off
	v_lshl_add_u64 v[226:227], s[50:51], 0, v[128:129]
	s_add_i32 m0, s60, 0x2000
	s_nop 0
	global_load_lds_dwordx4 v[226:227], off
	v_lshl_add_u64 v[226:227], s[30:31], 0, v[134:135]
	s_mov_b32 m0, s25
	s_nop 0
	global_load_lds_dwordx4 v[226:227], off
	s_mov_b32 m0, s40
	s_nop 0
	global_load_lds_dwordx4 v[228:229], off
	s_waitcnt vmcnt(8)
	s_waitcnt lgkmcnt(0)
	s_barrier
; #define PG8_STAGE(bufoff, gbase, voff) do { _Pragma("unroll") for (int _i = 0; _i < 2; ++_i) \
;         __builtin_amdgcn_global_load_lds((const unsigned*)((const char*)(gbase) + (voff)[_i]), (LAS unsigned*)(lds + (bufoff) + ldsw + _i * 8192), 16, 0, 0); } while (0)
; #define PG8_LDA(dst, b, h) do { _Pragma("unroll") for (int m = 0; m < 4; ++m) _Pragma("unroll") for (int k = 0; k < 2; ++k) dst[m][k] = *(const LAS bf16x8*)(lds + PG8_SA(b, h) + aoff + m * 2048 + k * 1024); } while (0)
; #define PG8_LDB(dst, b, h) do { _Pragma("unroll") for (int n = 0; n < 2; ++n) _Pragma("unroll") for (int k = 0; k < 2; ++k) dst[n][k] = *(const LAS bf16x8*)(lds + PG8_SB(b, h) + boff + n * 2048 + k * 1024); } while (0)
; #define PG8_MMA(ai, bj, At, Bt) do { __builtin_amdgcn_s_setprio(1); _Pragma("unroll") for (int m = 0; m < 4; ++m) _Pragma("unroll") for (int n = 0; n < 2; ++n) _Pragma("unroll") for (int k = 0; k < 2; ++k) \
;         acc[ai][bj][m][n] = __builtin_amdgcn_mfma_f32_16x16x32_bf16(Bt[n][k], At[m][k], acc[ai][bj][m][n], 0, 0, 0); __builtin_amdgcn_s_setprio(0); } while (0)
; #define PG8_WAIT_V(n) asm volatile("s_waitcnt vmcnt(" #n ")" ::: "memory")
; #define PG8_WAIT_L(n) asm volatile("s_waitcnt lgkmcnt(" #n ")" ::: "memory")
; #define PG8_BAR __builtin_amdgcn_s_barrier()
; #define PG8_SCHED __builtin_amdgcn_sched_barrier(0)
; template <class Epi>
; __device__ __forceinline__ void gemm_phase(LAS unsigned char* lds, const Gemm g, const StaticOrder& S, const Epi& E) {
;     ...
;             PG8_WAIT_V(8); PG8_WAIT_L(0); PG8_BAR; PG8_MMA(1, 0, At, B0); PG8_MMA(1, 1, At, B1); PG8_BAR; PG8_SCHED;
;             PG8_LDB(B0, 1, 0); PG8_LDB(B1, 1, 1); PG8_SCHED; PG8_LDA(At, 1, 0); PG8_STAGE(PG8_SA(0, 1), a2 + hstepA, voffA);
;             PG8_WAIT_V(8); PG8_WAIT_L(0); PG8_BAR; PG8_MMA(0, 0, At, B0); PG8_MMA(0, 1, At, B1); PG8_BAR; PG8_SCHED;
	s_setprio 1
	s_waitcnt lgkmcnt(0)
	v_mfma_f32_16x16x32_bf16 v[60:63], v[146:149], v[194:197], v[60:63]
	v_mfma_f32_16x16x32_bf16 v[44:47], v[146:149], v[202:205], v[44:47]
	v_mfma_f32_16x16x32_bf16 v[28:31], v[146:149], v[210:213], v[28:31]
	v_mfma_f32_16x16x32_bf16 v[12:15], v[146:149], v[218:221], v[12:15]
	v_mfma_f32_16x16x32_bf16 v[4:7], v[160:163], v[218:221], v[4:7]
	v_mfma_f32_16x16x32_bf16 v[20:23], v[160:163], v[210:213], v[20:23]
	v_mfma_f32_16x16x32_bf16 v[36:39], v[160:163], v[202:205], v[36:39]
	v_mfma_f32_16x16x32_bf16 v[52:55], v[160:163], v[194:197], v[52:55]
	v_mfma_f32_16x16x32_bf16 v[60:63], v[156:159], v[198:201], v[60:63]
	v_mfma_f32_16x16x32_bf16 v[44:47], v[156:159], v[206:209], v[44:47]
	v_mfma_f32_16x16x32_bf16 v[28:31], v[156:159], v[214:217], v[28:31]
	v_mfma_f32_16x16x32_bf16 v[12:15], v[156:159], v[222:225], v[12:15]
	v_mfma_f32_16x16x32_bf16 v[4:7], v[174:177], v[222:225], v[4:7]
	v_mfma_f32_16x16x32_bf16 v[20:23], v[174:177], v[214:217], v[20:23]
	v_mfma_f32_16x16x32_bf16 v[36:39], v[174:177], v[206:209], v[36:39]
	v_mfma_f32_16x16x32_bf16 v[52:55], v[174:177], v[198:201], v[52:55]
	s_setprio 0
	s_setprio 1
	v_mfma_f32_16x16x32_bf16 v[56:59], v[178:181], v[194:197], v[56:59]
	v_mfma_f32_16x16x32_bf16 v[40:43], v[178:181], v[202:205], v[40:43]
	v_mfma_f32_16x16x32_bf16 v[24:27], v[178:181], v[210:213], v[24:27]
	v_mfma_f32_16x16x32_bf16 v[8:11], v[178:181], v[218:221], v[8:11]
	v_mfma_f32_16x16x32_bf16 v[0:3], v[186:189], v[218:221], v[0:3]
	v_mfma_f32_16x16x32_bf16 v[16:19], v[186:189], v[210:213], v[16:19]
	v_mfma_f32_16x16x32_bf16 v[32:35], v[186:189], v[202:205], v[32:35]
	v_mfma_f32_16x16x32_bf16 v[48:51], v[186:189], v[194:197], v[48:51]
	v_mfma_f32_16x16x32_bf16 v[56:59], v[182:185], v[198:201], v[56:59]
	v_mfma_f32_16x16x32_bf16 v[40:43], v[182:185], v[206:209], v[40:43]
	v_mfma_f32_16x16x32_bf16 v[24:27], v[182:185], v[214:217], v[24:27]
	v_mfma_f32_16x16x32_bf16 v[8:11], v[182:185], v[222:225], v[8:11]
	v_mfma_f32_16x16x32_bf16 v[0:3], v[190:193], v[222:225], v[0:3]
	v_mfma_f32_16x16x32_bf16 v[16:19], v[190:193], v[214:217], v[16:19]
	v_mfma_f32_16x16x32_bf16 v[32:35], v[190:193], v[206:209], v[32:35]
	v_mfma_f32_16x16x32_bf16 v[48:51], v[190:193], v[198:201], v[48:51]
	s_setprio 0
	s_barrier
	s_add_i32 s50, 0, 0x18000
	v_add_u32_e32 v173, s50, v166
	s_add_i32 s51, 0, 0x1c000
	ds_read_b128 v[146:149], v173
	ds_read_b128 v[156:159], v173 offset:1024
	ds_read_b128 v[160:163], v173 offset:2048
	ds_read_b128 v[174:177], v173 offset:3072
	v_add_u32_e32 v173, s51, v166
	ds_read_b128 v[178:181], v173
	ds_read_b128 v[182:185], v173 offset:1024
	ds_read_b128 v[186:189], v173 offset:2048
	ds_read_b128 v[190:193], v173 offset:3072
	s_add_u32 s30, s30, 0x40000
	s_addc_u32 s31, s31, 0
	s_mov_b32 m0, s41
	v_lshl_add_u64 v[230:231], s[30:31], 0, v[134:135]
	ds_read_b128 v[194:197], v170 offset:32768
	ds_read_b128 v[198:201], v170 offset:33792
	ds_read_b128 v[202:205], v170 offset:34816
	ds_read_b128 v[206:209], v170 offset:35840
	ds_read_b128 v[210:213], v170 offset:36864
	ds_read_b128 v[214:217], v170 offset:37888
	ds_read_b128 v[218:221], v170 offset:38912
	ds_read_b128 v[222:225], v170 offset:39936
	global_load_lds_dwordx4 v[230:231], off
	v_lshl_add_u64 v[230:231], s[30:31], 0, v[130:131]
	s_mov_b32 m0, s44
	s_nop 0
	global_load_lds_dwordx4 v[230:231], off
	s_waitcnt vmcnt(8)
	s_waitcnt lgkmcnt(0)
	s_barrier
	s_setprio 1
	s_waitcnt lgkmcnt(0)
	v_mfma_f32_16x16x32_bf16 v[124:127], v[146:149], v[194:197], v[124:127]
	v_mfma_f32_16x16x32_bf16 v[108:111], v[146:149], v[202:205], v[108:111]
	v_mfma_f32_16x16x32_bf16 v[92:95], v[146:149], v[210:213], v[92:95]
	v_mfma_f32_16x16x32_bf16 v[76:79], v[146:149], v[218:221], v[76:79]
	v_mfma_f32_16x16x32_bf16 v[68:71], v[160:163], v[218:221], v[68:71]
	v_mfma_f32_16x16x32_bf16 v[84:87], v[160:163], v[210:213], v[84:87]
	v_mfma_f32_16x16x32_bf16 v[100:103], v[160:163], v[202:205], v[100:103]
	v_mfma_f32_16x16x32_bf16 v[116:119], v[160:163], v[194:197], v[116:119]
	v_mfma_f32_16x16x32_bf16 v[124:127], v[156:159], v[198:201], v[124:127]
	v_mfma_f32_16x16x32_bf16 v[108:111], v[156:159], v[206:209], v[108:111]
	v_mfma_f32_16x16x32_bf16 v[92:95], v[156:159], v[214:217], v[92:95]
	v_mfma_f32_16x16x32_bf16 v[76:79], v[156:159], v[222:225], v[76:79]
	v_mfma_f32_16x16x32_bf16 v[68:71], v[174:177], v[222:225], v[68:71]
	v_mfma_f32_16x16x32_bf16 v[84:87], v[174:177], v[214:217], v[84:87]
	v_mfma_f32_16x16x32_bf16 v[100:103], v[174:177], v[206:209], v[100:103]
	v_mfma_f32_16x16x32_bf16 v[116:119], v[174:177], v[198:201], v[116:119]
	s_setprio 0
	s_setprio 1
	v_mfma_f32_16x16x32_bf16 v[120:123], v[178:181], v[194:197], v[120:123]
	v_mfma_f32_16x16x32_bf16 v[104:107], v[178:181], v[202:205], v[104:107]
	v_mfma_f32_16x16x32_bf16 v[88:91], v[178:181], v[210:213], v[88:91]
	v_mfma_f32_16x16x32_bf16 v[72:75], v[178:181], v[218:221], v[72:75]
	v_mfma_f32_16x16x32_bf16 v[64:67], v[186:189], v[218:221], v[64:67]
	v_mfma_f32_16x16x32_bf16 v[80:83], v[186:189], v[210:213], v[80:83]
	v_mfma_f32_16x16x32_bf16 v[96:99], v[186:189], v[202:205], v[96:99]
	v_mfma_f32_16x16x32_bf16 v[112:115], v[186:189], v[194:197], v[112:115]
	v_mfma_f32_16x16x32_bf16 v[120:123], v[182:185], v[198:201], v[120:123]
	v_mfma_f32_16x16x32_bf16 v[104:107], v[182:185], v[206:209], v[104:107]
	v_mfma_f32_16x16x32_bf16 v[88:91], v[182:185], v[214:217], v[88:91]
	v_mfma_f32_16x16x32_bf16 v[72:75], v[182:185], v[222:225], v[72:75]
	v_mfma_f32_16x16x32_bf16 v[64:67], v[190:193], v[222:225], v[64:67]
	v_mfma_f32_16x16x32_bf16 v[80:83], v[190:193], v[214:217], v[80:83]
	v_mfma_f32_16x16x32_bf16 v[96:99], v[190:193], v[206:209], v[96:99]
	v_mfma_f32_16x16x32_bf16 v[112:115], v[190:193], v[198:201], v[112:115]
	s_setprio 0
	s_barrier
; #define PG8_STAGE(bufoff, gbase, voff) do { _Pragma("unroll") for (int _i = 0; _i < 2; ++_i) \
;         __builtin_amdgcn_global_load_lds((const unsigned*)((const char*)(gbase) + (voff)[_i]), (LAS unsigned*)(lds + (bufoff) + ldsw + _i * 8192), 16, 0, 0); } while (0)
; #define PG8_LDA(dst, b, h) do { _Pragma("unroll") for (int m = 0; m < 4; ++m) _Pragma("unroll") for (int k = 0; k < 2; ++k) dst[m][k] = *(const LAS bf16x8*)(lds + PG8_SA(b, h) + aoff + m * 2048 + k * 1024); } while (0)
; #define PG8_MMA(ai, bj, At, Bt) do { __builtin_amdgcn_s_setprio(1); _Pragma("unroll") for (int m = 0; m < 4; ++m) _Pragma("unroll") for (int n = 0; n < 2; ++n) _Pragma("unroll") for (int k = 0; k < 2; ++k) \
;         acc[ai][bj][m][n] = __builtin_amdgcn_mfma_f32_16x16x32_bf16(Bt[n][k], At[m][k], acc[ai][bj][m][n], 0, 0, 0); __builtin_amdgcn_s_setprio(0); } while (0)
; #define PG8_WAIT_V(n) asm volatile("s_waitcnt vmcnt(" #n ")" ::: "memory")
; #define PG8_WAIT_L(n) asm volatile("s_waitcnt lgkmcnt(" #n ")" ::: "memory")
; #define PG8_BAR __builtin_amdgcn_s_barrier()
; #define PG8_SCHED __builtin_amdgcn_sched_barrier(0)
; template <class Epi>
; __device__ __forceinline__ void gemm_phase(LAS unsigned char* lds, const Gemm g, const StaticOrder& S, const Epi& E) {
;     ...
;             PG8_LDA(At, 1, 1); PG8_STAGE(PG8_SB(1, 0), b3, voffB); PG8_STAGE(PG8_SB(1, 1), b3 + hstepB, voffB); PG8_STAGE(PG8_SA(1, 0), a3, voffA);
;             PG8_WAIT_V(8); PG8_WAIT_L(0); PG8_BAR; PG8_MMA(1, 0, At, B0); PG8_MMA(1, 1, At, B1); PG8_BAR; PG8_SCHED;
;         }
;         if (wr == 0) PG8_BAR;
	s_add_i32 s30, s50, s37
	v_lshl_add_u64 v[150:151], v[150:151], 0, s[10:11]
	s_mov_b32 m0, s30
	ds_read_b128 v[194:197], v170 offset:49152
	ds_read_b128 v[198:201], v170 offset:50176
	ds_read_b128 v[202:205], v170 offset:51200
	ds_read_b128 v[206:209], v170 offset:52224
	ds_read_b128 v[210:213], v170 offset:53248
	ds_read_b128 v[214:217], v170 offset:54272
	ds_read_b128 v[218:221], v170 offset:55296
	ds_read_b128 v[222:225], v170 offset:56320
	global_load_lds_dwordx4 v[150:151], off
	s_add_i32 m0, s30, 0x2000
	s_add_u32 s28, s28, 0x40080
	v_lshl_add_u64 v[150:151], v[164:165], 0, s[10:11]
	s_addc_u32 s29, s29, 0
	s_add_i32 s30, s51, s37
	global_load_lds_dwordx4 v[150:151], off
	v_lshl_add_u64 v[150:151], s[28:29], 0, v[132:133]
	s_mov_b32 m0, s30
	s_nop 0
	global_load_lds_dwordx4 v[150:151], off
	v_lshl_add_u64 v[150:151], s[28:29], 0, v[128:129]
	s_add_i32 m0, s30, 0x2000
	s_nop 0
	global_load_lds_dwordx4 v[150:151], off
	v_lshl_add_u64 v[150:151], v[226:227], 0, s[10:11]
	s_mov_b32 m0, s46
	s_nop 0
	global_load_lds_dwordx4 v[150:151], off
	v_lshl_add_u64 v[150:151], v[228:229], 0, s[10:11]
	s_mov_b32 m0, s47
	s_nop 0
	global_load_lds_dwordx4 v[150:151], off
	s_waitcnt vmcnt(8)
	s_waitcnt lgkmcnt(0)
	s_barrier
	s_setprio 1
	s_waitcnt lgkmcnt(0)
	v_mfma_f32_16x16x32_bf16 v[60:63], v[146:149], v[194:197], v[60:63]
	v_mfma_f32_16x16x32_bf16 v[44:47], v[146:149], v[202:205], v[44:47]
	v_mfma_f32_16x16x32_bf16 v[28:31], v[146:149], v[210:213], v[28:31]
	v_mfma_f32_16x16x32_bf16 v[12:15], v[146:149], v[218:221], v[12:15]
	v_mfma_f32_16x16x32_bf16 v[4:7], v[160:163], v[218:221], v[4:7]
	v_mfma_f32_16x16x32_bf16 v[20:23], v[160:163], v[210:213], v[20:23]
	v_mfma_f32_16x16x32_bf16 v[36:39], v[160:163], v[202:205], v[36:39]
	v_mfma_f32_16x16x32_bf16 v[52:55], v[160:163], v[194:197], v[52:55]
	v_mfma_f32_16x16x32_bf16 v[60:63], v[156:159], v[198:201], v[60:63]
	v_mfma_f32_16x16x32_bf16 v[44:47], v[156:159], v[206:209], v[44:47]
	v_mfma_f32_16x16x32_bf16 v[28:31], v[156:159], v[214:217], v[28:31]
	v_mfma_f32_16x16x32_bf16 v[12:15], v[156:159], v[222:225], v[12:15]
	v_mfma_f32_16x16x32_bf16 v[4:7], v[174:177], v[222:225], v[4:7]
	v_mfma_f32_16x16x32_bf16 v[20:23], v[174:177], v[214:217], v[20:23]
	v_mfma_f32_16x16x32_bf16 v[36:39], v[174:177], v[206:209], v[36:39]
	v_mfma_f32_16x16x32_bf16 v[52:55], v[174:177], v[198:201], v[52:55]
	s_setprio 0
	s_setprio 1
	v_mfma_f32_16x16x32_bf16 v[56:59], v[178:181], v[194:197], v[56:59]
	v_mfma_f32_16x16x32_bf16 v[40:43], v[178:181], v[202:205], v[40:43]
	v_mfma_f32_16x16x32_bf16 v[24:27], v[178:181], v[210:213], v[24:27]
	v_mfma_f32_16x16x32_bf16 v[8:11], v[178:181], v[218:221], v[8:11]
	v_mfma_f32_16x16x32_bf16 v[0:3], v[186:189], v[218:221], v[0:3]
	v_mfma_f32_16x16x32_bf16 v[16:19], v[186:189], v[210:213], v[16:19]
	v_mfma_f32_16x16x32_bf16 v[32:35], v[186:189], v[202:205], v[32:35]
	v_mfma_f32_16x16x32_bf16 v[48:51], v[186:189], v[194:197], v[48:51]
	v_mfma_f32_16x16x32_bf16 v[56:59], v[182:185], v[198:201], v[56:59]
	v_mfma_f32_16x16x32_bf16 v[40:43], v[182:185], v[206:209], v[40:43]
	v_mfma_f32_16x16x32_bf16 v[24:27], v[182:185], v[214:217], v[24:27]
	v_mfma_f32_16x16x32_bf16 v[8:11], v[182:185], v[222:225], v[8:11]
	v_mfma_f32_16x16x32_bf16 v[0:3], v[190:193], v[222:225], v[0:3]
	v_mfma_f32_16x16x32_bf16 v[16:19], v[190:193], v[214:217], v[16:19]
	v_mfma_f32_16x16x32_bf16 v[32:35], v[190:193], v[206:209], v[32:35]
	v_mfma_f32_16x16x32_bf16 v[48:51], v[190:193], v[198:201], v[48:51]
	s_setprio 0
	s_barrier
	s_add_i32 s59, s59, 2
	s_add_u32 s57, s57, 0x100
	s_addc_u32 s58, s58, 0
	s_add_u32 s26, s26, 0x100
	s_addc_u32 s27, s27, 0
	s_cmp_gt_u32 s59, 13
	s_cbranch_scc0 .LBB0_1415
	s_and_b64 vcc, exec, s[12:13]
	s_cbranch_vccz .LBB0_1418
	s_barrier

; #define PG8_STAGE(bufoff, gbase, voff) do { _Pragma("unroll") for (int _i = 0; _i < 2; ++_i) \
;         __builtin_amdgcn_global_load_lds((const unsigned*)((const char*)(gbase) + (voff)[_i]), (LAS unsigned*)(lds + (bufoff) + ldsw + _i * 8192), 16, 0, 0); } while (0)
; #define PG8_LDA(dst, b, h) do { _Pragma("unroll") for (int m = 0; m < 4; ++m) _Pragma("unroll") for (int k = 0; k < 2; ++k) dst[m][k] = *(const LAS bf16x8*)(lds + PG8_SA(b, h) + aoff + m * 2048 + k * 1024); } while (0)
; #define PG8_LDB(dst, b, h) do { _Pragma("unroll") for (int n = 0; n < 2; ++n) _Pragma("unroll") for (int k = 0; k < 2; ++k) dst[n][k] = *(const LAS bf16x8*)(lds + PG8_SB(b, h) + boff + n * 2048 + k * 1024); } while (0)
; #define PG8_MMA(ai, bj, At, Bt) do { __builtin_amdgcn_s_setprio(1); _Pragma("unroll") for (int m = 0; m < 4; ++m) _Pragma("unroll") for (int n = 0; n < 2; ++n) _Pragma("unroll") for (int k = 0; k < 2; ++k) \
;         acc[ai][bj][m][n] = __builtin_amdgcn_mfma_f32_16x16x32_bf16(Bt[n][k], At[m][k], acc[ai][bj][m][n], 0, 0, 0); __builtin_amdgcn_s_setprio(0); } while (0)
; #define PG8_WAIT_V(n) asm volatile("s_waitcnt vmcnt(" #n ")" ::: "memory")
; #define PG8_WAIT_L(n) asm volatile("s_waitcnt lgkmcnt(" #n ")" ::: "memory")
; template <class Epi>
; __device__ __forceinline__ void gemm_phase(LAS unsigned char* lds, const Gemm g, const StaticOrder& S, const Epi& E) {
;     ...
;         const bool has_next = S.next(ui + 1, nxt);
;         const char* nA = has_next ? (const char*)g.A + (size_t)nxt.pm * tstepA : cA; const char* nB = has_next ? (const char*)g.Bt + (size_t)nxt.pn * tstepB : cB;
;         for (int t = 0; t < nt; t += 2) {
;             const bool last = (t == nt - 2);
;             const char* a1 = cA + (unsigned)(t + 1) * kstep;
;             const char* a2 = last ? nA : cA + (unsigned)(t + 2) * kstep; const char* b2 = last ? nB : cB + (unsigned)(t + 2) * kstep;
;             const char* a3 = a2 + kstep; const char* b3 = b2 + kstep;
;             PG8_LDB(B0, 0, 0); PG8_LDB(B1, 0, 1); PG8_SCHED; PG8_LDA(At, 0, 0); PG8_STAGE(PG8_SA(1, 1), a1 + hstepA, voffA);
;             PG8_WAIT_V(8); PG8_WAIT_L(0); PG8_BAR; PG8_MMA(0, 0, At, B0); PG8_MMA(0, 1, At, B1); PG8_BAR; PG8_SCHED;
;             PG8_LDA(At, 0, 1); PG8_STAGE(PG8_SB(0, 0), b2, voffB); PG8_STAGE(PG8_SB(0, 1), b2 + hstepB, voffB); PG8_STAGE(PG8_SA(0, 0), a2, voffA);
.LBB0_1479:
	ds_read_b128 v[144:147], v158
	ds_read_b128 v[148:151], v158 offset:1024
	ds_read_b128 v[162:165], v158 offset:2048
	ds_read_b128 v[166:169], v158 offset:3072
	ds_read_b128 v[170:173], v159
	ds_read_b128 v[174:177], v159 offset:1024
	ds_read_b128 v[178:181], v159 offset:2048
	ds_read_b128 v[182:185], v159 offset:3072
	s_add_u32 s28, s26, 0x100
	s_addc_u32 s29, s27, 0
	s_cmp_eq_u32 s62, 40
	s_cselect_b32 s35, s3, s29
	s_cselect_b32 s34, s2, s28
	s_cselect_b32 s31, s25, s61
	s_cselect_b32 s30, s24, s60
	v_lshl_add_u64 v[218:219], s[26:27], 0, v[138:139]
	s_add_i32 m0, s44, 0xc000
	ds_read_b128 v[186:189], v160
	ds_read_b128 v[190:193], v160 offset:1024
	ds_read_b128 v[194:197], v160 offset:2048
	ds_read_b128 v[198:201], v160 offset:3072
	ds_read_b128 v[202:205], v160 offset:4096
	ds_read_b128 v[206:209], v160 offset:5120
	ds_read_b128 v[210:213], v160 offset:6144
	ds_read_b128 v[214:217], v160 offset:7168
	global_load_lds_dwordx4 v[218:219], off
	v_lshl_add_u64 v[218:219], s[26:27], 0, v[136:137]
	s_add_i32 m0, s44, 0xe000
	s_nop 0
	global_load_lds_dwordx4 v[218:219], off
	s_waitcnt vmcnt(8)
	s_waitcnt lgkmcnt(0)
	s_barrier
	s_setprio 1
	s_waitcnt lgkmcnt(0)
	v_mfma_f32_16x16x32_bf16 v[124:127], v[144:147], v[186:189], v[124:127]
	v_mfma_f32_16x16x32_bf16 v[116:119], v[144:147], v[194:197], v[116:119]
	v_mfma_f32_16x16x32_bf16 v[96:99], v[144:147], v[202:205], v[96:99]
	v_mfma_f32_16x16x32_bf16 v[80:83], v[144:147], v[210:213], v[80:83]
	v_mfma_f32_16x16x32_bf16 v[72:75], v[162:165], v[210:213], v[72:75]
	v_mfma_f32_16x16x32_bf16 v[88:91], v[162:165], v[202:205], v[88:91]
	v_mfma_f32_16x16x32_bf16 v[112:115], v[162:165], v[194:197], v[112:115]
	v_mfma_f32_16x16x32_bf16 v[120:123], v[162:165], v[186:189], v[120:123]
	v_mfma_f32_16x16x32_bf16 v[124:127], v[148:151], v[190:193], v[124:127]
	v_mfma_f32_16x16x32_bf16 v[116:119], v[148:151], v[198:201], v[116:119]
	v_mfma_f32_16x16x32_bf16 v[96:99], v[148:151], v[206:209], v[96:99]
	v_mfma_f32_16x16x32_bf16 v[80:83], v[148:151], v[214:217], v[80:83]
	v_mfma_f32_16x16x32_bf16 v[72:75], v[166:169], v[214:217], v[72:75]
	v_mfma_f32_16x16x32_bf16 v[88:91], v[166:169], v[206:209], v[88:91]
	v_mfma_f32_16x16x32_bf16 v[112:115], v[166:169], v[198:201], v[112:115]
	v_mfma_f32_16x16x32_bf16 v[120:123], v[166:169], v[190:193], v[120:123]
	s_setprio 0
	s_setprio 1
	v_mfma_f32_16x16x32_bf16 v[108:111], v[170:173], v[186:189], v[108:111]
	v_mfma_f32_16x16x32_bf16 v[100:103], v[170:173], v[194:197], v[100:103]
	v_mfma_f32_16x16x32_bf16 v[84:87], v[170:173], v[202:205], v[84:87]
	v_mfma_f32_16x16x32_bf16 v[68:71], v[170:173], v[210:213], v[68:71]
	v_mfma_f32_16x16x32_bf16 v[64:67], v[178:181], v[210:213], v[64:67]
	v_mfma_f32_16x16x32_bf16 v[76:79], v[178:181], v[202:205], v[76:79]
	v_mfma_f32_16x16x32_bf16 v[92:95], v[178:181], v[194:197], v[92:95]
	v_mfma_f32_16x16x32_bf16 v[104:107], v[178:181], v[186:189], v[104:107]
	v_mfma_f32_16x16x32_bf16 v[108:111], v[174:177], v[190:193], v[108:111]
	v_mfma_f32_16x16x32_bf16 v[100:103], v[174:177], v[198:201], v[100:103]
	v_mfma_f32_16x16x32_bf16 v[84:87], v[174:177], v[206:209], v[84:87]
	v_mfma_f32_16x16x32_bf16 v[68:71], v[174:177], v[214:217], v[68:71]
	v_mfma_f32_16x16x32_bf16 v[64:67], v[182:185], v[214:217], v[64:67]
	v_mfma_f32_16x16x32_bf16 v[76:79], v[182:185], v[206:209], v[76:79]
	v_mfma_f32_16x16x32_bf16 v[92:95], v[182:185], v[198:201], v[92:95]
	v_mfma_f32_16x16x32_bf16 v[104:107], v[182:185], v[190:193], v[104:107]
	s_setprio 0
	s_barrier
	s_add_i32 s26, s55, s39
	v_lshl_add_u64 v[218:219], s[30:31], 0, v[132:133]
	s_mov_b32 m0, s26
	ds_read_b128 v[186:189], v160 offset:16384
	ds_read_b128 v[190:193], v160 offset:17408
	ds_read_b128 v[194:197], v160 offset:18432
	ds_read_b128 v[198:201], v160 offset:19456
	ds_read_b128 v[202:205], v160 offset:20480
	ds_read_b128 v[206:209], v160 offset:21504
	ds_read_b128 v[210:213], v160 offset:22528
	ds_read_b128 v[214:217], v160 offset:23552
	global_load_lds_dwordx4 v[218:219], off
	s_add_i32 m0, s26, 0x2000
	s_add_u32 s26, s30, 0xb0000
	v_lshl_add_u64 v[220:221], s[30:31], 0, v[128:129]
	s_addc_u32 s27, s31, 0
	s_add_i32 s50, s56, s39
	global_load_lds_dwordx4 v[220:221], off
	v_lshl_add_u64 v[222:223], s[26:27], 0, v[132:133]
	s_mov_b32 m0, s50
	v_lshl_add_u64 v[224:225], s[34:35], 0, v[130:131]
	global_load_lds_dwordx4 v[222:223], off
	v_lshl_add_u64 v[222:223], s[26:27], 0, v[128:129]
	s_add_i32 m0, s50, 0x2000
	s_nop 0
	global_load_lds_dwordx4 v[222:223], off
	v_lshl_add_u64 v[222:223], s[34:35], 0, v[134:135]
	s_mov_b32 m0, s44
	s_nop 0
	global_load_lds_dwordx4 v[222:223], off
	s_mov_b32 m0, s45
	s_nop 0
	global_load_lds_dwordx4 v[224:225], off
	s_waitcnt vmcnt(8)
	s_waitcnt lgkmcnt(0)
	s_barrier
; #define PG8_STAGE(bufoff, gbase, voff) do { _Pragma("unroll") for (int _i = 0; _i < 2; ++_i) \
;         __builtin_amdgcn_global_load_lds((const unsigned*)((const char*)(gbase) + (voff)[_i]), (LAS unsigned*)(lds + (bufoff) + ldsw + _i * 8192), 16, 0, 0); } while (0)
; #define PG8_LDA(dst, b, h) do { _Pragma("unroll") for (int m = 0; m < 4; ++m) _Pragma("unroll") for (int k = 0; k < 2; ++k) dst[m][k] = *(const LAS bf16x8*)(lds + PG8_SA(b, h) + aoff + m * 2048 + k * 1024); } while (0)
; #define PG8_LDB(dst, b, h) do { _Pragma("unroll") for (int n = 0; n < 2; ++n) _Pragma("unroll") for (int k = 0; k < 2; ++k) dst[n][k] = *(const LAS bf16x8*)(lds + PG8_SB(b, h) + boff + n * 2048 + k * 1024); } while (0)
; #define PG8_MMA(ai, bj, At, Bt) do { __builtin_amdgcn_s_setprio(1); _Pragma("unroll") for (int m = 0; m < 4; ++m) _Pragma("unroll") for (int n = 0; n < 2; ++n) _Pragma("unroll") for (int k = 0; k < 2; ++k) \
;         acc[ai][bj][m][n] = __builtin_amdgcn_mfma_f32_16x16x32_bf16(Bt[n][k], At[m][k], acc[ai][bj][m][n], 0, 0, 0); __builtin_amdgcn_s_setprio(0); } while (0)
; #define PG8_WAIT_V(n) asm volatile("s_waitcnt vmcnt(" #n ")" ::: "memory")
; #define PG8_WAIT_L(n) asm volatile("s_waitcnt lgkmcnt(" #n ")" ::: "memory")
; #define PG8_BAR __builtin_amdgcn_s_barrier()
; #define PG8_SCHED __builtin_amdgcn_sched_barrier(0)
; template <class Epi>
; __device__ __forceinline__ void gemm_phase(LAS unsigned char* lds, const Gemm g, const StaticOrder& S, const Epi& E) {
;     ...
;             PG8_WAIT_V(8); PG8_WAIT_L(0); PG8_BAR; PG8_MMA(1, 0, At, B0); PG8_MMA(1, 1, At, B1); PG8_BAR; PG8_SCHED;
;             PG8_LDB(B0, 1, 0); PG8_LDB(B1, 1, 1); PG8_SCHED; PG8_LDA(At, 1, 0); PG8_STAGE(PG8_SA(0, 1), a2 + hstepA, voffA);
;             PG8_WAIT_V(8); PG8_WAIT_L(0); PG8_BAR; PG8_MMA(0, 0, At, B0); PG8_MMA(0, 1, At, B1); PG8_BAR; PG8_SCHED;
	s_setprio 1
	s_waitcnt lgkmcnt(0)
	v_mfma_f32_16x16x32_bf16 v[60:63], v[144:147], v[186:189], v[60:63]
	v_mfma_f32_16x16x32_bf16 v[48:51], v[144:147], v[194:197], v[48:51]
	v_mfma_f32_16x16x32_bf16 v[32:35], v[144:147], v[202:205], v[32:35]
	v_mfma_f32_16x16x32_bf16 v[16:19], v[144:147], v[210:213], v[16:19]
	v_mfma_f32_16x16x32_bf16 v[8:11], v[162:165], v[210:213], v[8:11]
	v_mfma_f32_16x16x32_bf16 v[24:27], v[162:165], v[202:205], v[24:27]
	v_mfma_f32_16x16x32_bf16 v[40:43], v[162:165], v[194:197], v[40:43]
	v_mfma_f32_16x16x32_bf16 v[56:59], v[162:165], v[186:189], v[56:59]
	v_mfma_f32_16x16x32_bf16 v[60:63], v[148:151], v[190:193], v[60:63]
	v_mfma_f32_16x16x32_bf16 v[48:51], v[148:151], v[198:201], v[48:51]
	v_mfma_f32_16x16x32_bf16 v[32:35], v[148:151], v[206:209], v[32:35]
	v_mfma_f32_16x16x32_bf16 v[16:19], v[148:151], v[214:217], v[16:19]
	v_mfma_f32_16x16x32_bf16 v[8:11], v[166:169], v[214:217], v[8:11]
	v_mfma_f32_16x16x32_bf16 v[24:27], v[166:169], v[206:209], v[24:27]
	v_mfma_f32_16x16x32_bf16 v[40:43], v[166:169], v[198:201], v[40:43]
	v_mfma_f32_16x16x32_bf16 v[56:59], v[166:169], v[190:193], v[56:59]
	s_setprio 0
	s_setprio 1
	v_mfma_f32_16x16x32_bf16 v[52:55], v[170:173], v[186:189], v[52:55]
	v_mfma_f32_16x16x32_bf16 v[36:39], v[170:173], v[194:197], v[36:39]
	v_mfma_f32_16x16x32_bf16 v[20:23], v[170:173], v[202:205], v[20:23]
	v_mfma_f32_16x16x32_bf16 v[4:7], v[170:173], v[210:213], v[4:7]
	v_mfma_f32_16x16x32_bf16 v[0:3], v[178:181], v[210:213], v[0:3]
	v_mfma_f32_16x16x32_bf16 v[12:15], v[178:181], v[202:205], v[12:15]
	v_mfma_f32_16x16x32_bf16 v[28:31], v[178:181], v[194:197], v[28:31]
	v_mfma_f32_16x16x32_bf16 v[44:47], v[178:181], v[186:189], v[44:47]
	v_mfma_f32_16x16x32_bf16 v[52:55], v[174:177], v[190:193], v[52:55]
	v_mfma_f32_16x16x32_bf16 v[36:39], v[174:177], v[198:201], v[36:39]
	v_mfma_f32_16x16x32_bf16 v[20:23], v[174:177], v[206:209], v[20:23]
	v_mfma_f32_16x16x32_bf16 v[4:7], v[174:177], v[214:217], v[4:7]
	v_mfma_f32_16x16x32_bf16 v[0:3], v[182:185], v[214:217], v[0:3]
	v_mfma_f32_16x16x32_bf16 v[12:15], v[182:185], v[206:209], v[12:15]
	v_mfma_f32_16x16x32_bf16 v[28:31], v[182:185], v[198:201], v[28:31]
	v_mfma_f32_16x16x32_bf16 v[44:47], v[182:185], v[190:193], v[44:47]
	s_setprio 0
	s_barrier
	s_add_i32 s50, 0, 0x18000
	v_add_u32_e32 v161, s50, v156
	s_add_i32 s51, 0, 0x1c000
	ds_read_b128 v[144:147], v161
	ds_read_b128 v[148:151], v161 offset:1024
	ds_read_b128 v[162:165], v161 offset:2048
	ds_read_b128 v[166:169], v161 offset:3072
	v_add_u32_e32 v161, s51, v156
	ds_read_b128 v[170:173], v161
	ds_read_b128 v[174:177], v161 offset:1024
	ds_read_b128 v[178:181], v161 offset:2048
	ds_read_b128 v[182:185], v161 offset:3072
	s_add_u32 s26, s34, 0xb0000
	s_addc_u32 s27, s35, 0
	s_mov_b32 m0, s46
	v_lshl_add_u64 v[226:227], s[26:27], 0, v[134:135]
	ds_read_b128 v[186:189], v160 offset:32768
	ds_read_b128 v[190:193], v160 offset:33792
	ds_read_b128 v[194:197], v160 offset:34816
	ds_read_b128 v[198:201], v160 offset:35840
	ds_read_b128 v[202:205], v160 offset:36864
	ds_read_b128 v[206:209], v160 offset:37888
	ds_read_b128 v[210:213], v160 offset:38912
	ds_read_b128 v[214:217], v160 offset:39936
	global_load_lds_dwordx4 v[226:227], off
	v_lshl_add_u64 v[226:227], s[26:27], 0, v[130:131]
	s_mov_b32 m0, s47
	s_nop 0
	global_load_lds_dwordx4 v[226:227], off
	s_waitcnt vmcnt(8)
	s_waitcnt lgkmcnt(0)
	s_barrier
	s_setprio 1
	s_waitcnt lgkmcnt(0)
	v_mfma_f32_16x16x32_bf16 v[124:127], v[144:147], v[186:189], v[124:127]
	v_mfma_f32_16x16x32_bf16 v[116:119], v[144:147], v[194:197], v[116:119]
	v_mfma_f32_16x16x32_bf16 v[96:99], v[144:147], v[202:205], v[96:99]
	v_mfma_f32_16x16x32_bf16 v[80:83], v[144:147], v[210:213], v[80:83]
	v_mfma_f32_16x16x32_bf16 v[72:75], v[162:165], v[210:213], v[72:75]
	v_mfma_f32_16x16x32_bf16 v[88:91], v[162:165], v[202:205], v[88:91]
	v_mfma_f32_16x16x32_bf16 v[112:115], v[162:165], v[194:197], v[112:115]
	v_mfma_f32_16x16x32_bf16 v[120:123], v[162:165], v[186:189], v[120:123]
	v_mfma_f32_16x16x32_bf16 v[124:127], v[148:151], v[190:193], v[124:127]
	v_mfma_f32_16x16x32_bf16 v[116:119], v[148:151], v[198:201], v[116:119]
	v_mfma_f32_16x16x32_bf16 v[96:99], v[148:151], v[206:209], v[96:99]
	v_mfma_f32_16x16x32_bf16 v[80:83], v[148:151], v[214:217], v[80:83]
	v_mfma_f32_16x16x32_bf16 v[72:75], v[166:169], v[214:217], v[72:75]
	v_mfma_f32_16x16x32_bf16 v[88:91], v[166:169], v[206:209], v[88:91]
	v_mfma_f32_16x16x32_bf16 v[112:115], v[166:169], v[198:201], v[112:115]
	v_mfma_f32_16x16x32_bf16 v[120:123], v[166:169], v[190:193], v[120:123]
	s_setprio 0
	s_setprio 1
	v_mfma_f32_16x16x32_bf16 v[108:111], v[170:173], v[186:189], v[108:111]
	v_mfma_f32_16x16x32_bf16 v[100:103], v[170:173], v[194:197], v[100:103]
	v_mfma_f32_16x16x32_bf16 v[84:87], v[170:173], v[202:205], v[84:87]
	v_mfma_f32_16x16x32_bf16 v[68:71], v[170:173], v[210:213], v[68:71]
	v_mfma_f32_16x16x32_bf16 v[64:67], v[178:181], v[210:213], v[64:67]
	v_mfma_f32_16x16x32_bf16 v[76:79], v[178:181], v[202:205], v[76:79]
	v_mfma_f32_16x16x32_bf16 v[92:95], v[178:181], v[194:197], v[92:95]
	v_mfma_f32_16x16x32_bf16 v[104:107], v[178:181], v[186:189], v[104:107]
	v_mfma_f32_16x16x32_bf16 v[108:111], v[174:177], v[190:193], v[108:111]
	v_mfma_f32_16x16x32_bf16 v[100:103], v[174:177], v[198:201], v[100:103]
	v_mfma_f32_16x16x32_bf16 v[84:87], v[174:177], v[206:209], v[84:87]
	v_mfma_f32_16x16x32_bf16 v[68:71], v[174:177], v[214:217], v[68:71]
	v_mfma_f32_16x16x32_bf16 v[64:67], v[182:185], v[214:217], v[64:67]
	v_mfma_f32_16x16x32_bf16 v[76:79], v[182:185], v[206:209], v[76:79]
	v_mfma_f32_16x16x32_bf16 v[92:95], v[182:185], v[198:201], v[92:95]
	v_mfma_f32_16x16x32_bf16 v[104:107], v[182:185], v[190:193], v[104:107]
	s_setprio 0
	s_barrier
; #define PG8_STAGE(bufoff, gbase, voff) do { _Pragma("unroll") for (int _i = 0; _i < 2; ++_i) \
;         __builtin_amdgcn_global_load_lds((const unsigned*)((const char*)(gbase) + (voff)[_i]), (LAS unsigned*)(lds + (bufoff) + ldsw + _i * 8192), 16, 0, 0); } while (0)
; #define PG8_LDA(dst, b, h) do { _Pragma("unroll") for (int m = 0; m < 4; ++m) _Pragma("unroll") for (int k = 0; k < 2; ++k) dst[m][k] = *(const LAS bf16x8*)(lds + PG8_SA(b, h) + aoff + m * 2048 + k * 1024); } while (0)
; #define PG8_MMA(ai, bj, At, Bt) do { __builtin_amdgcn_s_setprio(1); _Pragma("unroll") for (int m = 0; m < 4; ++m) _Pragma("unroll") for (int n = 0; n < 2; ++n) _Pragma("unroll") for (int k = 0; k < 2; ++k) \
;         acc[ai][bj][m][n] = __builtin_amdgcn_mfma_f32_16x16x32_bf16(Bt[n][k], At[m][k], acc[ai][bj][m][n], 0, 0, 0); __builtin_amdgcn_s_setprio(0); } while (0)
; #define PG8_WAIT_V(n) asm volatile("s_waitcnt vmcnt(" #n ")" ::: "memory")
; #define PG8_WAIT_L(n) asm volatile("s_waitcnt lgkmcnt(" #n ")" ::: "memory")
; #define PG8_BAR __builtin_amdgcn_s_barrier()
; #define PG8_SCHED __builtin_amdgcn_sched_barrier(0)
; template <class Epi>
; __device__ __forceinline__ void gemm_phase(LAS unsigned char* lds, const Gemm g, const StaticOrder& S, const Epi& E) {
;     ...
;             PG8_LDA(At, 1, 1); PG8_STAGE(PG8_SB(1, 0), b3, voffB); PG8_STAGE(PG8_SB(1, 1), b3 + hstepB, voffB); PG8_STAGE(PG8_SA(1, 0), a3, voffA);
;             PG8_WAIT_V(8); PG8_WAIT_L(0); PG8_BAR; PG8_MMA(1, 0, At, B0); PG8_MMA(1, 1, At, B1); PG8_BAR; PG8_SCHED;
;         }
;         if (wr == 0) PG8_BAR;
	s_add_i32 s26, s50, s39
	v_lshl_add_u64 v[218:219], v[218:219], 0, s[10:11]
	s_mov_b32 m0, s26
	ds_read_b128 v[186:189], v160 offset:49152
	ds_read_b128 v[190:193], v160 offset:50176
	ds_read_b128 v[194:197], v160 offset:51200
	ds_read_b128 v[198:201], v160 offset:52224
	ds_read_b128 v[202:205], v160 offset:53248
	ds_read_b128 v[206:209], v160 offset:54272
	ds_read_b128 v[210:213], v160 offset:55296
	ds_read_b128 v[214:217], v160 offset:56320
	global_load_lds_dwordx4 v[218:219], off
	s_add_i32 m0, s26, 0x2000
	s_add_u32 s26, s30, 0xb0080
	v_lshl_add_u64 v[218:219], v[220:221], 0, s[10:11]
	s_addc_u32 s27, s31, 0
	s_add_i32 s30, s51, s39
	global_load_lds_dwordx4 v[218:219], off
	v_lshl_add_u64 v[218:219], s[26:27], 0, v[132:133]
	s_mov_b32 m0, s30
	s_nop 0
	global_load_lds_dwordx4 v[218:219], off
	v_lshl_add_u64 v[218:219], s[26:27], 0, v[128:129]
	s_add_i32 m0, s30, 0x2000
	s_nop 0
	global_load_lds_dwordx4 v[218:219], off
	v_lshl_add_u64 v[218:219], v[222:223], 0, s[10:11]
	s_mov_b32 m0, s49
	s_nop 0
	global_load_lds_dwordx4 v[218:219], off
	v_lshl_add_u64 v[218:219], v[224:225], 0, s[10:11]
	s_mov_b32 m0, s52
	s_nop 0
	global_load_lds_dwordx4 v[218:219], off
	s_waitcnt vmcnt(8)
	s_waitcnt lgkmcnt(0)
	s_barrier
	s_setprio 1
	s_waitcnt lgkmcnt(0)
	v_mfma_f32_16x16x32_bf16 v[60:63], v[144:147], v[186:189], v[60:63]
	v_mfma_f32_16x16x32_bf16 v[48:51], v[144:147], v[194:197], v[48:51]
	v_mfma_f32_16x16x32_bf16 v[32:35], v[144:147], v[202:205], v[32:35]
	v_mfma_f32_16x16x32_bf16 v[16:19], v[144:147], v[210:213], v[16:19]
	v_mfma_f32_16x16x32_bf16 v[8:11], v[162:165], v[210:213], v[8:11]
	v_mfma_f32_16x16x32_bf16 v[24:27], v[162:165], v[202:205], v[24:27]
	v_mfma_f32_16x16x32_bf16 v[40:43], v[162:165], v[194:197], v[40:43]
	v_mfma_f32_16x16x32_bf16 v[56:59], v[162:165], v[186:189], v[56:59]
	v_mfma_f32_16x16x32_bf16 v[60:63], v[148:151], v[190:193], v[60:63]
	v_mfma_f32_16x16x32_bf16 v[48:51], v[148:151], v[198:201], v[48:51]
	v_mfma_f32_16x16x32_bf16 v[32:35], v[148:151], v[206:209], v[32:35]
	v_mfma_f32_16x16x32_bf16 v[16:19], v[148:151], v[214:217], v[16:19]
	v_mfma_f32_16x16x32_bf16 v[8:11], v[166:169], v[214:217], v[8:11]
	v_mfma_f32_16x16x32_bf16 v[24:27], v[166:169], v[206:209], v[24:27]
	v_mfma_f32_16x16x32_bf16 v[40:43], v[166:169], v[198:201], v[40:43]
	v_mfma_f32_16x16x32_bf16 v[56:59], v[166:169], v[190:193], v[56:59]
	s_setprio 0
	s_setprio 1
	v_mfma_f32_16x16x32_bf16 v[52:55], v[170:173], v[186:189], v[52:55]
	v_mfma_f32_16x16x32_bf16 v[36:39], v[170:173], v[194:197], v[36:39]
	v_mfma_f32_16x16x32_bf16 v[20:23], v[170:173], v[202:205], v[20:23]
	v_mfma_f32_16x16x32_bf16 v[4:7], v[170:173], v[210:213], v[4:7]
	v_mfma_f32_16x16x32_bf16 v[0:3], v[178:181], v[210:213], v[0:3]
	v_mfma_f32_16x16x32_bf16 v[12:15], v[178:181], v[202:205], v[12:15]
	v_mfma_f32_16x16x32_bf16 v[28:31], v[178:181], v[194:197], v[28:31]
	v_mfma_f32_16x16x32_bf16 v[44:47], v[178:181], v[186:189], v[44:47]
	v_mfma_f32_16x16x32_bf16 v[52:55], v[174:177], v[190:193], v[52:55]
	v_mfma_f32_16x16x32_bf16 v[36:39], v[174:177], v[198:201], v[36:39]
	v_mfma_f32_16x16x32_bf16 v[20:23], v[174:177], v[206:209], v[20:23]
	v_mfma_f32_16x16x32_bf16 v[4:7], v[174:177], v[214:217], v[4:7]
	v_mfma_f32_16x16x32_bf16 v[0:3], v[182:185], v[214:217], v[0:3]
	v_mfma_f32_16x16x32_bf16 v[12:15], v[182:185], v[206:209], v[12:15]
	v_mfma_f32_16x16x32_bf16 v[28:31], v[182:185], v[198:201], v[28:31]
	v_mfma_f32_16x16x32_bf16 v[44:47], v[182:185], v[190:193], v[44:47]
	s_setprio 0
	s_barrier
	s_add_i32 s62, s62, 2
	s_add_u32 s60, s60, 0x100
	s_addc_u32 s61, s61, 0
	s_cmp_gt_u32 s62, 41
	s_mov_b64 s[26:27], s[28:29]
	s_cbranch_scc0 .LBB0_1479
	s_and_b64 vcc, exec, s[12:13]
	s_cbranch_vccz .LBB0_1482
	s_barrier
